# v32 + rsqrt(ssq*inv_k+eps): the denormal-safe 8-instruction rsqrtf expansion (never taken: argument >= 1e-6) replaced by the single v_rsq_f32 it reduces to, bit-identical, at 42 sites in GEMM epilogue
# speedup vs baseline: 1.0026x; 1.0026x over previous
; __device__ __forceinline__ float row_ssq(const float* part, int pitch, int n4, int row, int fq) {
;     f32x4 v = (f32x4){0.f, 0.f, 0.f, 0.f};
;     if (fq < n4) v = *(const f32x4*)(part + (size_t)row * pitch + 4 * fq);
;     float s = (v[0] + v[1]) + (v[2] + v[3]);
;     s += __shfl_xor(s, 16); s += __shfl_xor(s, 32);
;     return s;
; }
;     __device__ __forceinline__ void operator()(const f32x4 (&acc)[2][2][4][2], const Unit& u, int wr, int wc, int fr, int fq) const {
;         const int row0 = u.pm * BM + wr * 64 + fr, col0 = u.pn * 128 + wc * 32 + 8 * fq;
; #pragma unroll
;         for (int ai = 0; ai < 2; ++ai)
; #pragma unroll
;             for (int m = 0; m < 4; ++m) {
;                 const int row = row0 + ai * HALF + m * 16;
;                 const float rs = rsqrtf(row_ssq(ssq, 16, 4, row, fq) * (1.f / 1024.f) + EPS);
.LBB0_168:
	v_and_b32_e32 v145, 64, v241
	v_xor_b32_e32 v143, 16, v241
	v_add_u32_e32 v145, 64, v145
	v_cmp_lt_i32_e32 vcc, v143, v145
	v_lshl_add_u32 v144, s44, 8, v146
	v_lshl_or_b32 v142, s4, 7, v148
	v_cndmask_b32_e32 v143, v241, v143, vcc
	v_lshlrev_b32_e32 v150, 2, v143
	v_xor_b32_e32 v143, 32, v241
	v_cmp_lt_i32_e32 vcc, v143, v145
	v_ashrrev_i32_e32 v145, 31, v144
	v_and_b32_e32 v166, 48, v241
	v_lshl_add_u32 v166, v146, 6, v166
	v_add_u32_e32 v166, 0x24000, v166
	ds_read_b128 v[168:171], v166
	ds_read_b128 v[172:175], v166 offset:1024
	ds_read_b128 v[176:179], v166 offset:2048
	ds_read_b128 v[180:183], v166 offset:3072
	v_cndmask_b32_e32 v143, v241, v143, vcc
	v_lshlrev_b32_e32 v151, 2, v143
	ds_read_b128 v[184:187], v166 offset:8192
	ds_read_b128 v[188:191], v166 offset:9216
	ds_read_b128 v[192:195], v166 offset:10240
	ds_read_b128 v[196:199], v166 offset:11264
	v_ashrrev_i32_e32 v143, 31, v142
	v_lshl_add_u64 v[142:143], v[142:143], 1, s[96:97]
	s_movk_i32 s4, 0x1600
	s_mov_b64 s[24:25], -1
	s_waitcnt lgkmcnt(7)
	v_add_f32_e32 v168, v169, v168
	v_add_f32_e32 v170, v170, v171
	v_add_f32_e32 v168, v168, v170
	v_mov_b32_e32 v169, v168
	s_nop 1
	v_permlane16_swap_b32_e32 v168, v169
	s_waitcnt lgkmcnt(6)
	v_add_f32_e32 v172, v173, v172
	v_add_f32_e32 v174, v174, v175
	v_add_f32_e32 v172, v172, v174
	v_mov_b32_e32 v173, v172
	s_nop 1
	v_permlane16_swap_b32_e32 v172, v173
	s_waitcnt lgkmcnt(5)
	v_add_f32_e32 v176, v177, v176
	v_add_f32_e32 v178, v178, v179
	v_add_f32_e32 v176, v176, v178
	v_mov_b32_e32 v177, v176
	s_nop 1
	v_permlane16_swap_b32_e32 v176, v177
	s_waitcnt lgkmcnt(4)
	v_add_f32_e32 v180, v181, v180
	v_add_f32_e32 v182, v182, v183
	v_add_f32_e32 v180, v180, v182
	v_mov_b32_e32 v181, v180
	s_nop 1
	v_permlane16_swap_b32_e32 v180, v181
	s_waitcnt lgkmcnt(3)
	v_add_f32_e32 v184, v185, v184
	v_add_f32_e32 v186, v186, v187
	v_add_f32_e32 v184, v184, v186
	v_mov_b32_e32 v185, v184
	s_nop 1
	v_permlane16_swap_b32_e32 v184, v185
	s_waitcnt lgkmcnt(2)
	v_add_f32_e32 v188, v189, v188
	v_add_f32_e32 v190, v190, v191
	v_add_f32_e32 v188, v188, v190
	v_mov_b32_e32 v189, v188
	s_nop 1
	v_permlane16_swap_b32_e32 v188, v189
	s_waitcnt lgkmcnt(1)
	v_add_f32_e32 v192, v193, v192
	v_add_f32_e32 v194, v194, v195
	v_add_f32_e32 v192, v192, v194
	v_mov_b32_e32 v193, v192
	s_nop 1
	v_permlane16_swap_b32_e32 v192, v193
	s_waitcnt lgkmcnt(0)
	v_add_f32_e32 v196, v197, v196
	v_add_f32_e32 v198, v198, v199
	v_add_f32_e32 v196, v196, v198
	v_mov_b32_e32 v197, v196
	s_nop 1
	v_permlane16_swap_b32_e32 v196, v197
	s_waitcnt lgkmcnt(7)
	v_add_f32_e32 v168, v168, v169
	v_mov_b32_e32 v169, v168
	s_nop 1
	v_permlane32_swap_b32_e32 v168, v169
	s_waitcnt lgkmcnt(7)
	v_add_f32_e32 v172, v172, v173
	v_mov_b32_e32 v173, v172
	s_nop 1
	v_permlane32_swap_b32_e32 v172, v173
	s_waitcnt lgkmcnt(7)
	v_add_f32_e32 v176, v176, v177
	v_mov_b32_e32 v177, v176
	s_nop 1
	v_permlane32_swap_b32_e32 v176, v177
	s_waitcnt lgkmcnt(7)
	v_add_f32_e32 v180, v180, v181
	v_mov_b32_e32 v181, v180
	s_nop 1
	v_permlane32_swap_b32_e32 v180, v181
	s_waitcnt lgkmcnt(7)
	v_add_f32_e32 v184, v184, v185
	v_mov_b32_e32 v185, v184
	s_nop 1
	v_permlane32_swap_b32_e32 v184, v185
	s_waitcnt lgkmcnt(7)
	v_add_f32_e32 v188, v188, v189
	v_mov_b32_e32 v189, v188
	s_nop 1
	v_permlane32_swap_b32_e32 v188, v189
	s_waitcnt lgkmcnt(7)
	v_add_f32_e32 v192, v192, v193
	v_mov_b32_e32 v193, v192
	s_nop 1
	v_permlane32_swap_b32_e32 v192, v193
	s_waitcnt lgkmcnt(7)
	v_add_f32_e32 v196, v196, v197
	v_mov_b32_e32 v197, v196
	s_nop 1
	v_permlane32_swap_b32_e32 v196, v197
	s_waitcnt lgkmcnt(7)
	v_add_f32_e32 v168, v168, v169
	v_fmamk_f32 v168, v168, 0x3a800000, v239
	s_waitcnt lgkmcnt(6)
	v_add_f32_e32 v172, v172, v173
	v_fmamk_f32 v172, v172, 0x3a800000, v239
	s_waitcnt lgkmcnt(5)
	v_add_f32_e32 v176, v176, v177
	v_fmamk_f32 v176, v176, 0x3a800000, v239
	s_waitcnt lgkmcnt(4)
	v_add_f32_e32 v180, v180, v181
	v_fmamk_f32 v180, v180, 0x3a800000, v239
	s_waitcnt lgkmcnt(3)
	v_add_f32_e32 v184, v184, v185
	v_fmamk_f32 v184, v184, 0x3a800000, v239
	s_waitcnt lgkmcnt(2)
	v_add_f32_e32 v188, v188, v189
	v_fmamk_f32 v188, v188, 0x3a800000, v239
	s_waitcnt lgkmcnt(1)
	v_add_f32_e32 v192, v192, v193
	v_fmamk_f32 v192, v192, 0x3a800000, v239
	s_waitcnt lgkmcnt(0)
; __device__ __forceinline__ unsigned pk2(float lo, float hi) { f32x2_t v = {lo, hi}; bf16x2_t b = __builtin_convertvector(v, bf16x2_t); return __builtin_bit_cast(unsigned, b); }
; __device__ __forceinline__ float fast_sigmoid(float x) { return __builtin_amdgcn_rcpf(1.f + __expf(-x)); }
;     __device__ __forceinline__ void operator()(const f32x4 (&acc)[2][2][4][2], const Unit& u, int wr, int wc, int fr, int fq) const {
;     ...
;                 const int row = row0 + ai * HALF + m * 16;
;                 const float rs = rsqrtf(row_ssq(ssq, 16, 4, row, fq) * (1.f / 1024.f) + EPS);
;                 float r[8];
; #pragma unroll
;                 for (int n = 0; n < 2; ++n)
; #pragma unroll
;                     for (int e = 0; e < 4; ++e) { const float gv = acc[ai][0][m][n][e] * rs, uv = acc[ai][1][m][n][e] * rs; r[n * 4 + e] = gv * fast_sigmoid(gv) * uv; }
;                 u32x4 w; w.x = pk2(r[0], r[1]); w.y = pk2(r[2], r[3]); w.z = pk2(r[4], r[5]); w.w = pk2(r[6], r[7]);
;                 *(u32x4*)(O + (size_t)row * DFF + col0) = w;
	v_add_f32_e32 v196, v196, v197
	v_fmamk_f32 v196, v196, 0x3a800000, v239
	s_nop 0
	v_rsq_f32_e32 v158, v168
	s_nop 0
	s_nop 0
	s_nop 0
	v_rsq_f32_e32 v159, v172
	s_nop 0
	s_nop 0
	s_nop 0
	v_rsq_f32_e32 v160, v176
	s_nop 0
	s_nop 0
	s_nop 0
	v_rsq_f32_e32 v161, v180
	s_nop 0
	s_nop 0
	s_nop 0
	v_rsq_f32_e32 v162, v184
	s_nop 0
	s_nop 0
	s_nop 0
	v_rsq_f32_e32 v163, v188
	s_nop 0
	s_nop 0
	s_nop 0
	v_rsq_f32_e32 v164, v192
	s_nop 0
	s_nop 0
	s_nop 0
	v_rsq_f32_e32 v165, v196
	s_nop 0
	s_nop 0
	v_mov_b32_e32 v152, v158
	v_pk_mul_f32 v[126:127], v[126:127], v[152:153] op_sel_hi:[1,0]
	v_pk_mul_f32 v[118:119], v[118:119], v[152:153] op_sel_hi:[1,0]
	v_mul_f32_e32 v145, 0xbfb8aa3b, v126
	v_exp_f32_e32 v145, v145
	v_pk_mul_f32 v[120:121], v[120:121], v[152:153] op_sel_hi:[1,0]
	v_pk_mul_f32 v[122:123], v[122:123], v[152:153] op_sel_hi:[1,0]
	v_pk_mul_f32 v[114:115], v[114:115], v[152:153] op_sel_hi:[1,0]
	v_add_f32_e32 v145, 1.0, v145
	v_rcp_f32_e32 v154, v145
	v_mul_f32_e32 v145, 0xbfb8aa3b, v127
	v_exp_f32_e32 v145, v145
	v_pk_mul_f32 v[116:117], v[116:117], v[152:153] op_sel_hi:[1,0]
	v_add_f32_e32 v145, 1.0, v145
	v_rcp_f32_e32 v155, v145
	s_nop 0
	v_pk_mul_f32 v[126:127], v[126:127], v[154:155]
	s_nop 0
	v_pk_mul_f32 v[118:119], v[118:119], v[126:127]
	v_pk_mul_f32 v[126:127], v[128:129], v[152:153] op_sel_hi:[1,0]
	s_nop 0
	v_mul_f32_e32 v128, 0xbfb8aa3b, v126
	v_mul_f32_e32 v129, 0xbfb8aa3b, v127
	v_exp_f32_e32 v128, v128
	v_exp_f32_e32 v129, v129
	v_add_f32_e32 v128, 1.0, v128
	v_add_f32_e32 v129, 1.0, v129
	v_rcp_f32_e32 v128, v128
	v_rcp_f32_e32 v129, v129
	s_nop 0
	v_pk_mul_f32 v[126:127], v[126:127], v[128:129]
	s_nop 0
	v_pk_mul_f32 v[120:121], v[120:121], v[126:127]
	v_mul_f32_e32 v126, 0xbfb8aa3b, v122
	v_mul_f32_e32 v127, 0xbfb8aa3b, v123
	v_exp_f32_e32 v126, v126
	v_exp_f32_e32 v127, v127
	v_add_f32_e32 v126, 1.0, v126
	v_add_f32_e32 v127, 1.0, v127
	v_rcp_f32_e32 v126, v126
	v_rcp_f32_e32 v127, v127
	s_nop 0
	v_pk_mul_f32 v[122:123], v[122:123], v[126:127]
	s_nop 0
	v_pk_mul_f32 v[122:123], v[114:115], v[122:123]
	v_pk_mul_f32 v[114:115], v[124:125], v[152:153] op_sel_hi:[1,0]
	s_nop 0
	v_mul_f32_e32 v124, 0xbfb8aa3b, v114
	v_mul_f32_e32 v125, 0xbfb8aa3b, v115
	v_exp_f32_e32 v124, v124
	v_exp_f32_e32 v125, v125
	v_add_f32_e32 v124, 1.0, v124
	v_add_f32_e32 v125, 1.0, v125
	v_rcp_f32_e32 v124, v124
	v_rcp_f32_e32 v125, v125
	s_nop 0
	v_pk_mul_f32 v[114:115], v[114:115], v[124:125]
	s_nop 0
	v_pk_mul_f32 v[124:125], v[116:117], v[114:115]
	v_cvt_pk_bf16_f32 v114, v118, v119
	v_cvt_pk_bf16_f32 v115, v120, v121
	v_cvt_pk_bf16_f32 v116, v122, v123
	v_cvt_pk_bf16_f32 v117, v124, v125
	v_mad_i64_i32 v[118:119], s[6:7], v144, s4, v[142:143]
	global_store_dwordx4 v[118:119], v[114:117], off
	s_nop 1
	v_or_b32_e32 v114, 16, v144
	v_mov_b32_e32 v116, v159
	v_pk_mul_f32 v[110:111], v[110:111], v[116:117] op_sel_hi:[1,0]
	v_pk_mul_f32 v[102:103], v[102:103], v[116:117] op_sel_hi:[1,0]
	v_mul_f32_e32 v115, 0xbfb8aa3b, v110
	v_exp_f32_e32 v115, v115
	v_pk_mul_f32 v[104:105], v[104:105], v[116:117] op_sel_hi:[1,0]
	v_pk_mul_f32 v[106:107], v[106:107], v[116:117] op_sel_hi:[1,0]
	v_pk_mul_f32 v[98:99], v[98:99], v[116:117] op_sel_hi:[1,0]
	v_add_f32_e32 v115, 1.0, v115
	v_rcp_f32_e32 v118, v115
	v_mul_f32_e32 v115, 0xbfb8aa3b, v111
	v_exp_f32_e32 v115, v115
	v_pk_mul_f32 v[100:101], v[100:101], v[116:117] op_sel_hi:[1,0]
	v_add_f32_e32 v115, 1.0, v115
	v_rcp_f32_e32 v119, v115
	s_nop 0
	v_pk_mul_f32 v[110:111], v[110:111], v[118:119]
	s_nop 0
	v_pk_mul_f32 v[102:103], v[102:103], v[110:111]
	v_pk_mul_f32 v[110:111], v[112:113], v[116:117] op_sel_hi:[1,0]
	s_nop 0
	v_mul_f32_e32 v112, 0xbfb8aa3b, v110
	v_mul_f32_e32 v113, 0xbfb8aa3b, v111
	v_exp_f32_e32 v112, v112
	v_exp_f32_e32 v113, v113
	v_add_f32_e32 v112, 1.0, v112
	v_add_f32_e32 v113, 1.0, v113
	v_rcp_f32_e32 v112, v112
	v_rcp_f32_e32 v113, v113
	s_nop 0
	v_pk_mul_f32 v[110:111], v[110:111], v[112:113]
	s_nop 0
	v_pk_mul_f32 v[104:105], v[104:105], v[110:111]
	v_mul_f32_e32 v110, 0xbfb8aa3b, v106
	v_mul_f32_e32 v111, 0xbfb8aa3b, v107
	v_exp_f32_e32 v110, v110
	v_exp_f32_e32 v111, v111
	v_add_f32_e32 v110, 1.0, v110
	v_add_f32_e32 v111, 1.0, v111
	v_rcp_f32_e32 v110, v110
	v_rcp_f32_e32 v111, v111
	s_nop 0
	v_pk_mul_f32 v[106:107], v[106:107], v[110:111]
	s_nop 0
	v_pk_mul_f32 v[106:107], v[98:99], v[106:107]
	v_pk_mul_f32 v[98:99], v[108:109], v[116:117] op_sel_hi:[1,0]
	s_nop 0
	v_mul_f32_e32 v108, 0xbfb8aa3b, v98
	v_mul_f32_e32 v109, 0xbfb8aa3b, v99
	v_exp_f32_e32 v108, v108
	v_exp_f32_e32 v109, v109
	v_add_f32_e32 v108, 1.0, v108
	v_add_f32_e32 v109, 1.0, v109
	v_rcp_f32_e32 v108, v108
	v_rcp_f32_e32 v109, v109
	s_nop 0
	v_pk_mul_f32 v[98:99], v[98:99], v[108:109]
	s_nop 0
	v_pk_mul_f32 v[108:109], v[100:101], v[98:99]
	v_cvt_pk_bf16_f32 v98, v102, v103
	v_cvt_pk_bf16_f32 v99, v104, v105
	v_cvt_pk_bf16_f32 v100, v106, v107
	v_cvt_pk_bf16_f32 v101, v108, v109
	v_mad_i64_i32 v[102:103], s[6:7], v114, s4, v[142:143]
	global_store_dwordx4 v[102:103], v[98:101], off
	s_nop 1
	v_or_b32_e32 v98, 32, v144
	v_mov_b32_e32 v100, v160
	v_pk_mul_f32 v[94:95], v[94:95], v[100:101] op_sel_hi:[1,0]
	v_pk_mul_f32 v[86:87], v[86:87], v[100:101] op_sel_hi:[1,0]
	v_mul_f32_e32 v99, 0xbfb8aa3b, v94
	v_exp_f32_e32 v99, v99
	v_pk_mul_f32 v[88:89], v[88:89], v[100:101] op_sel_hi:[1,0]
	v_pk_mul_f32 v[90:91], v[90:91], v[100:101] op_sel_hi:[1,0]
	v_pk_mul_f32 v[82:83], v[82:83], v[100:101] op_sel_hi:[1,0]
	v_add_f32_e32 v99, 1.0, v99
	v_rcp_f32_e32 v102, v99
	v_mul_f32_e32 v99, 0xbfb8aa3b, v95
	v_exp_f32_e32 v99, v99
	v_pk_mul_f32 v[84:85], v[84:85], v[100:101] op_sel_hi:[1,0]
	v_add_f32_e32 v99, 1.0, v99
; __device__ __forceinline__ unsigned pk2(float lo, float hi) { f32x2_t v = {lo, hi}; bf16x2_t b = __builtin_convertvector(v, bf16x2_t); return __builtin_bit_cast(unsigned, b); }
; __device__ __forceinline__ float fast_sigmoid(float x) { return __builtin_amdgcn_rcpf(1.f + __expf(-x)); }
;     __device__ __forceinline__ void operator()(const f32x4 (&acc)[2][2][4][2], const Unit& u, int wr, int wc, int fr, int fq) const {
;     ...
;                 float r[8];
; #pragma unroll
;                 for (int n = 0; n < 2; ++n)
; #pragma unroll
;                     for (int e = 0; e < 4; ++e) { const float gv = acc[ai][0][m][n][e] * rs, uv = acc[ai][1][m][n][e] * rs; r[n * 4 + e] = gv * fast_sigmoid(gv) * uv; }
;                 u32x4 w; w.x = pk2(r[0], r[1]); w.y = pk2(r[2], r[3]); w.z = pk2(r[4], r[5]); w.w = pk2(r[6], r[7]);
;                 *(u32x4*)(O + (size_t)row * DFF + col0) = w;
	v_rcp_f32_e32 v103, v99
	s_nop 0
	v_pk_mul_f32 v[94:95], v[94:95], v[102:103]
	s_nop 0
	v_pk_mul_f32 v[86:87], v[86:87], v[94:95]
	v_pk_mul_f32 v[94:95], v[96:97], v[100:101] op_sel_hi:[1,0]
	s_nop 0
	v_mul_f32_e32 v96, 0xbfb8aa3b, v94
	v_mul_f32_e32 v97, 0xbfb8aa3b, v95
	v_exp_f32_e32 v96, v96
	v_exp_f32_e32 v97, v97
	v_add_f32_e32 v96, 1.0, v96
	v_add_f32_e32 v97, 1.0, v97
	v_rcp_f32_e32 v96, v96
	v_rcp_f32_e32 v97, v97
	s_nop 0
	v_pk_mul_f32 v[94:95], v[94:95], v[96:97]
	s_nop 0
	v_pk_mul_f32 v[88:89], v[88:89], v[94:95]
	v_mul_f32_e32 v94, 0xbfb8aa3b, v90
	v_mul_f32_e32 v95, 0xbfb8aa3b, v91
	v_exp_f32_e32 v94, v94
	v_exp_f32_e32 v95, v95
	v_add_f32_e32 v94, 1.0, v94
	v_add_f32_e32 v95, 1.0, v95
	v_rcp_f32_e32 v94, v94
	v_rcp_f32_e32 v95, v95
	s_nop 0
	v_pk_mul_f32 v[90:91], v[90:91], v[94:95]
	s_nop 0
	v_pk_mul_f32 v[90:91], v[82:83], v[90:91]
	v_pk_mul_f32 v[82:83], v[92:93], v[100:101] op_sel_hi:[1,0]
	s_nop 0
	v_mul_f32_e32 v92, 0xbfb8aa3b, v82
	v_mul_f32_e32 v93, 0xbfb8aa3b, v83
	v_exp_f32_e32 v92, v92
	v_exp_f32_e32 v93, v93
	v_add_f32_e32 v92, 1.0, v92
	v_add_f32_e32 v93, 1.0, v93
	v_rcp_f32_e32 v92, v92
	v_rcp_f32_e32 v93, v93
	s_nop 0
	v_pk_mul_f32 v[82:83], v[82:83], v[92:93]
	s_nop 0
	v_pk_mul_f32 v[92:93], v[84:85], v[82:83]
	v_cvt_pk_bf16_f32 v82, v86, v87
	v_cvt_pk_bf16_f32 v83, v88, v89
	v_cvt_pk_bf16_f32 v84, v90, v91
	v_cvt_pk_bf16_f32 v85, v92, v93
	v_mad_i64_i32 v[86:87], s[6:7], v98, s4, v[142:143]
	global_store_dwordx4 v[86:87], v[82:85], off
	s_nop 1
	v_or_b32_e32 v82, 48, v144
	v_mov_b32_e32 v84, v161
	v_pk_mul_f32 v[78:79], v[78:79], v[84:85] op_sel_hi:[1,0]
	v_pk_mul_f32 v[70:71], v[70:71], v[84:85] op_sel_hi:[1,0]
	v_mul_f32_e32 v83, 0xbfb8aa3b, v78
	v_exp_f32_e32 v83, v83
	v_pk_mul_f32 v[72:73], v[72:73], v[84:85] op_sel_hi:[1,0]
	v_pk_mul_f32 v[74:75], v[74:75], v[84:85] op_sel_hi:[1,0]
	v_pk_mul_f32 v[66:67], v[66:67], v[84:85] op_sel_hi:[1,0]
	v_add_f32_e32 v83, 1.0, v83
	v_rcp_f32_e32 v86, v83
	v_mul_f32_e32 v83, 0xbfb8aa3b, v79
	v_exp_f32_e32 v83, v83
	v_pk_mul_f32 v[68:69], v[68:69], v[84:85] op_sel_hi:[1,0]
	v_add_f32_e32 v83, 1.0, v83
	v_rcp_f32_e32 v87, v83
	s_nop 0
	v_pk_mul_f32 v[78:79], v[78:79], v[86:87]
	s_nop 0
	v_pk_mul_f32 v[70:71], v[70:71], v[78:79]
	v_pk_mul_f32 v[78:79], v[80:81], v[84:85] op_sel_hi:[1,0]
	s_nop 0
	v_mul_f32_e32 v80, 0xbfb8aa3b, v78
	v_mul_f32_e32 v81, 0xbfb8aa3b, v79
	v_exp_f32_e32 v80, v80
	v_exp_f32_e32 v81, v81
	v_add_f32_e32 v80, 1.0, v80
	v_add_f32_e32 v81, 1.0, v81
	v_rcp_f32_e32 v80, v80
	v_rcp_f32_e32 v81, v81
	s_nop 0
	v_pk_mul_f32 v[78:79], v[78:79], v[80:81]
	s_nop 0
	v_pk_mul_f32 v[72:73], v[72:73], v[78:79]
	v_mul_f32_e32 v78, 0xbfb8aa3b, v74
	v_mul_f32_e32 v79, 0xbfb8aa3b, v75
	v_exp_f32_e32 v78, v78
	v_exp_f32_e32 v79, v79
	v_add_f32_e32 v78, 1.0, v78
	v_add_f32_e32 v79, 1.0, v79
	v_rcp_f32_e32 v78, v78
	v_rcp_f32_e32 v79, v79
	s_nop 0
	v_pk_mul_f32 v[74:75], v[74:75], v[78:79]
	s_nop 0
	v_pk_mul_f32 v[74:75], v[66:67], v[74:75]
	v_pk_mul_f32 v[66:67], v[76:77], v[84:85] op_sel_hi:[1,0]
	s_nop 0
	v_mul_f32_e32 v76, 0xbfb8aa3b, v66
	v_mul_f32_e32 v77, 0xbfb8aa3b, v67
	v_exp_f32_e32 v76, v76
	v_exp_f32_e32 v77, v77
	v_add_f32_e32 v76, 1.0, v76
	v_add_f32_e32 v77, 1.0, v77
	v_rcp_f32_e32 v76, v76
	v_rcp_f32_e32 v77, v77
	s_nop 0
	v_pk_mul_f32 v[66:67], v[66:67], v[76:77]
	s_nop 0
	v_pk_mul_f32 v[76:77], v[68:69], v[66:67]
	v_cvt_pk_bf16_f32 v66, v70, v71
	v_cvt_pk_bf16_f32 v67, v72, v73
	v_cvt_pk_bf16_f32 v68, v74, v75
	v_cvt_pk_bf16_f32 v69, v76, v77
	v_mad_i64_i32 v[70:71], s[6:7], v82, s4, v[142:143]
	global_store_dwordx4 v[70:71], v[66:69], off
	s_nop 1
	v_add_u32_e32 v66, 0x80, v144
	v_mov_b32_e32 v68, v162
	v_pk_mul_f32 v[62:63], v[62:63], v[68:69] op_sel_hi:[1,0]
	v_pk_mul_f32 v[54:55], v[54:55], v[68:69] op_sel_hi:[1,0]
	v_mul_f32_e32 v67, 0xbfb8aa3b, v62
	v_exp_f32_e32 v67, v67
	v_pk_mul_f32 v[56:57], v[56:57], v[68:69] op_sel_hi:[1,0]
	v_pk_mul_f32 v[58:59], v[58:59], v[68:69] op_sel_hi:[1,0]
	v_pk_mul_f32 v[50:51], v[50:51], v[68:69] op_sel_hi:[1,0]
	v_add_f32_e32 v67, 1.0, v67
	v_rcp_f32_e32 v70, v67
	v_mul_f32_e32 v67, 0xbfb8aa3b, v63
	v_exp_f32_e32 v67, v67
	v_pk_mul_f32 v[52:53], v[52:53], v[68:69] op_sel_hi:[1,0]
	v_add_f32_e32 v67, 1.0, v67
	v_rcp_f32_e32 v71, v67
	s_nop 0
	v_pk_mul_f32 v[62:63], v[62:63], v[70:71]
	s_nop 0
	v_pk_mul_f32 v[54:55], v[54:55], v[62:63]
	v_pk_mul_f32 v[62:63], v[64:65], v[68:69] op_sel_hi:[1,0]
	s_nop 0
	v_mul_f32_e32 v64, 0xbfb8aa3b, v62
	v_mul_f32_e32 v65, 0xbfb8aa3b, v63
	v_exp_f32_e32 v64, v64
	v_exp_f32_e32 v65, v65
	v_add_f32_e32 v64, 1.0, v64
	v_add_f32_e32 v65, 1.0, v65
	v_rcp_f32_e32 v64, v64
	v_rcp_f32_e32 v65, v65
	s_nop 0
	v_pk_mul_f32 v[62:63], v[62:63], v[64:65]
	s_nop 0
	v_pk_mul_f32 v[56:57], v[56:57], v[62:63]
	v_mul_f32_e32 v62, 0xbfb8aa3b, v58
	v_mul_f32_e32 v63, 0xbfb8aa3b, v59
	v_exp_f32_e32 v62, v62
	v_exp_f32_e32 v63, v63
	v_add_f32_e32 v62, 1.0, v62
	v_add_f32_e32 v63, 1.0, v63
	v_rcp_f32_e32 v62, v62
	v_rcp_f32_e32 v63, v63
	s_nop 0
	v_pk_mul_f32 v[58:59], v[58:59], v[62:63]
	s_nop 0
	v_pk_mul_f32 v[58:59], v[50:51], v[58:59]
	v_pk_mul_f32 v[50:51], v[60:61], v[68:69] op_sel_hi:[1,0]
	s_nop 0
	v_mul_f32_e32 v60, 0xbfb8aa3b, v50
	v_mul_f32_e32 v61, 0xbfb8aa3b, v51
	v_exp_f32_e32 v60, v60
	v_exp_f32_e32 v61, v61
	v_add_f32_e32 v60, 1.0, v60
	v_add_f32_e32 v61, 1.0, v61
	v_rcp_f32_e32 v60, v60
	v_rcp_f32_e32 v61, v61
	s_nop 0
	v_pk_mul_f32 v[50:51], v[50:51], v[60:61]
	s_nop 0
	v_pk_mul_f32 v[60:61], v[52:53], v[50:51]
	v_cvt_pk_bf16_f32 v50, v54, v55
	v_cvt_pk_bf16_f32 v51, v56, v57
	v_cvt_pk_bf16_f32 v52, v58, v59
	v_cvt_pk_bf16_f32 v53, v60, v61
	v_mad_i64_i32 v[54:55], s[6:7], v66, s4, v[142:143]
; __device__ __forceinline__ unsigned pk2(float lo, float hi) { f32x2_t v = {lo, hi}; bf16x2_t b = __builtin_convertvector(v, bf16x2_t); return __builtin_bit_cast(unsigned, b); }
; __device__ __forceinline__ float fast_sigmoid(float x) { return __builtin_amdgcn_rcpf(1.f + __expf(-x)); }
; #define PG8_BAR __builtin_amdgcn_s_barrier()
; template <class Epi>
; __device__ __forceinline__ void gemm_phase(LAS unsigned char* lds, int wave_s, const Gemm g, const StaticOrder S, const Epi E) {
;     ...
;         if (!has_next) break;
; #pragma unroll
;         for (int a = 0; a < 2; ++a)
; #pragma unroll
;             for (int b = 0; b < 2; ++b)
; #pragma unroll
;                 for (int m = 0; m < 4; ++m)
; #pragma unroll
;                     for (int n = 0; n < 2; ++n) acc[a][b][m][n] = (f32x4){0.f, 0.f, 0.f, 0.f};
;         cur = nxt; cA = nA; cB = nB; ++ui;
;         if (wr == 1) PG8_BAR;
;     __device__ __forceinline__ void operator()(const f32x4 (&acc)[2][2][4][2], const Unit& u, int wr, int wc, int fr, int fq) const {
;     ...
;                 float r[8];
; #pragma unroll
;                 for (int n = 0; n < 2; ++n)
; #pragma unroll
;                     for (int e = 0; e < 4; ++e) { const float gv = acc[ai][0][m][n][e] * rs, uv = acc[ai][1][m][n][e] * rs; r[n * 4 + e] = gv * fast_sigmoid(gv) * uv; }
;                 u32x4 w; w.x = pk2(r[0], r[1]); w.y = pk2(r[2], r[3]); w.z = pk2(r[4], r[5]); w.w = pk2(r[6], r[7]);
;                 *(u32x4*)(O + (size_t)row * DFF + col0) = w;
	global_store_dwordx4 v[54:55], v[50:53], off
	s_nop 1
	v_add_u32_e32 v50, 0x90, v144
	v_mov_b32_e32 v52, v163
	v_pk_mul_f32 v[46:47], v[46:47], v[52:53] op_sel_hi:[1,0]
	v_pk_mul_f32 v[38:39], v[38:39], v[52:53] op_sel_hi:[1,0]
	v_mul_f32_e32 v51, 0xbfb8aa3b, v46
	v_exp_f32_e32 v51, v51
	v_pk_mul_f32 v[40:41], v[40:41], v[52:53] op_sel_hi:[1,0]
	v_pk_mul_f32 v[42:43], v[42:43], v[52:53] op_sel_hi:[1,0]
	v_pk_mul_f32 v[34:35], v[34:35], v[52:53] op_sel_hi:[1,0]
	v_add_f32_e32 v51, 1.0, v51
	v_rcp_f32_e32 v54, v51
	v_mul_f32_e32 v51, 0xbfb8aa3b, v47
	v_exp_f32_e32 v51, v51
	v_pk_mul_f32 v[36:37], v[36:37], v[52:53] op_sel_hi:[1,0]
	v_add_f32_e32 v51, 1.0, v51
	v_rcp_f32_e32 v55, v51
	s_nop 0
	v_pk_mul_f32 v[46:47], v[46:47], v[54:55]
	s_nop 0
	v_pk_mul_f32 v[38:39], v[38:39], v[46:47]
	v_pk_mul_f32 v[46:47], v[48:49], v[52:53] op_sel_hi:[1,0]
	s_nop 0
	v_mul_f32_e32 v48, 0xbfb8aa3b, v46
	v_mul_f32_e32 v49, 0xbfb8aa3b, v47
	v_exp_f32_e32 v48, v48
	v_exp_f32_e32 v49, v49
	v_add_f32_e32 v48, 1.0, v48
	v_add_f32_e32 v49, 1.0, v49
	v_rcp_f32_e32 v48, v48
	v_rcp_f32_e32 v49, v49
	s_nop 0
	v_pk_mul_f32 v[46:47], v[46:47], v[48:49]
	s_nop 0
	v_pk_mul_f32 v[40:41], v[40:41], v[46:47]
	v_mul_f32_e32 v46, 0xbfb8aa3b, v42
	v_mul_f32_e32 v47, 0xbfb8aa3b, v43
	v_exp_f32_e32 v46, v46
	v_exp_f32_e32 v47, v47
	v_add_f32_e32 v46, 1.0, v46
	v_add_f32_e32 v47, 1.0, v47
	v_rcp_f32_e32 v46, v46
	v_rcp_f32_e32 v47, v47
	s_nop 0
	v_pk_mul_f32 v[42:43], v[42:43], v[46:47]
	s_nop 0
	v_pk_mul_f32 v[42:43], v[34:35], v[42:43]
	v_pk_mul_f32 v[34:35], v[44:45], v[52:53] op_sel_hi:[1,0]
	s_nop 0
	v_mul_f32_e32 v44, 0xbfb8aa3b, v34
	v_mul_f32_e32 v45, 0xbfb8aa3b, v35
	v_exp_f32_e32 v44, v44
	v_exp_f32_e32 v45, v45
	v_add_f32_e32 v44, 1.0, v44
	v_add_f32_e32 v45, 1.0, v45
	v_rcp_f32_e32 v44, v44
	v_rcp_f32_e32 v45, v45
	s_nop 0
	v_pk_mul_f32 v[34:35], v[34:35], v[44:45]
	s_nop 0
	v_pk_mul_f32 v[44:45], v[36:37], v[34:35]
	v_cvt_pk_bf16_f32 v34, v38, v39
	v_cvt_pk_bf16_f32 v35, v40, v41
	v_cvt_pk_bf16_f32 v36, v42, v43
	v_cvt_pk_bf16_f32 v37, v44, v45
	v_mad_i64_i32 v[38:39], s[6:7], v50, s4, v[142:143]
	global_store_dwordx4 v[38:39], v[34:37], off
	s_nop 1
	v_add_u32_e32 v34, 0xa0, v144
	v_mov_b32_e32 v36, v164
	v_pk_mul_f32 v[30:31], v[30:31], v[36:37] op_sel_hi:[1,0]
	v_pk_mul_f32 v[22:23], v[22:23], v[36:37] op_sel_hi:[1,0]
	v_mul_f32_e32 v35, 0xbfb8aa3b, v30
	v_exp_f32_e32 v35, v35
	v_pk_mul_f32 v[24:25], v[24:25], v[36:37] op_sel_hi:[1,0]
	v_pk_mul_f32 v[26:27], v[26:27], v[36:37] op_sel_hi:[1,0]
	v_pk_mul_f32 v[18:19], v[18:19], v[36:37] op_sel_hi:[1,0]
	v_add_f32_e32 v35, 1.0, v35
	v_rcp_f32_e32 v38, v35
	v_mul_f32_e32 v35, 0xbfb8aa3b, v31
	v_exp_f32_e32 v35, v35
	v_pk_mul_f32 v[20:21], v[20:21], v[36:37] op_sel_hi:[1,0]
	v_add_f32_e32 v35, 1.0, v35
	v_rcp_f32_e32 v39, v35
	s_nop 0
	v_pk_mul_f32 v[30:31], v[30:31], v[38:39]
	s_nop 0
	v_pk_mul_f32 v[22:23], v[22:23], v[30:31]
	v_pk_mul_f32 v[30:31], v[32:33], v[36:37] op_sel_hi:[1,0]
	s_nop 0
	v_mul_f32_e32 v32, 0xbfb8aa3b, v30
	v_mul_f32_e32 v33, 0xbfb8aa3b, v31
	v_exp_f32_e32 v32, v32
	v_exp_f32_e32 v33, v33
	v_add_f32_e32 v32, 1.0, v32
	v_add_f32_e32 v33, 1.0, v33
	v_rcp_f32_e32 v32, v32
	v_rcp_f32_e32 v33, v33
	s_nop 0
	v_pk_mul_f32 v[30:31], v[30:31], v[32:33]
	s_nop 0
	v_pk_mul_f32 v[24:25], v[24:25], v[30:31]
	v_mul_f32_e32 v30, 0xbfb8aa3b, v26
	v_mul_f32_e32 v31, 0xbfb8aa3b, v27
	v_exp_f32_e32 v30, v30
	v_exp_f32_e32 v31, v31
	v_add_f32_e32 v30, 1.0, v30
	v_add_f32_e32 v31, 1.0, v31
	v_rcp_f32_e32 v30, v30
	v_rcp_f32_e32 v31, v31
	s_nop 0
	v_pk_mul_f32 v[26:27], v[26:27], v[30:31]
	s_nop 0
	v_pk_mul_f32 v[26:27], v[18:19], v[26:27]
	v_pk_mul_f32 v[18:19], v[28:29], v[36:37] op_sel_hi:[1,0]
	s_nop 0
	v_mul_f32_e32 v28, 0xbfb8aa3b, v18
	v_mul_f32_e32 v29, 0xbfb8aa3b, v19
	v_exp_f32_e32 v28, v28
	v_exp_f32_e32 v29, v29
	v_add_f32_e32 v28, 1.0, v28
	v_add_f32_e32 v29, 1.0, v29
	v_rcp_f32_e32 v28, v28
	v_rcp_f32_e32 v29, v29
	s_nop 0
	v_pk_mul_f32 v[18:19], v[18:19], v[28:29]
	s_nop 0
	v_pk_mul_f32 v[28:29], v[20:21], v[18:19]
	v_cvt_pk_bf16_f32 v18, v22, v23
	v_cvt_pk_bf16_f32 v19, v24, v25
	v_cvt_pk_bf16_f32 v20, v26, v27
	v_cvt_pk_bf16_f32 v21, v28, v29
	v_mad_i64_i32 v[22:23], s[6:7], v34, s4, v[142:143]
	global_store_dwordx4 v[22:23], v[18:21], off
	s_nop 1
	v_add_u32_e32 v18, 0xb0, v144
	v_mov_b32_e32 v20, v165
	v_pk_mul_f32 v[14:15], v[14:15], v[20:21] op_sel_hi:[1,0]
	v_pk_mul_f32 v[6:7], v[6:7], v[20:21] op_sel_hi:[1,0]
	v_mul_f32_e32 v19, 0xbfb8aa3b, v14
	v_exp_f32_e32 v19, v19
	v_pk_mul_f32 v[8:9], v[8:9], v[20:21] op_sel_hi:[1,0]
	v_pk_mul_f32 v[10:11], v[10:11], v[20:21] op_sel_hi:[1,0]
	v_pk_mul_f32 v[2:3], v[2:3], v[20:21] op_sel_hi:[1,0]
	v_add_f32_e32 v19, 1.0, v19
	v_rcp_f32_e32 v22, v19
	v_mul_f32_e32 v19, 0xbfb8aa3b, v15
	v_exp_f32_e32 v19, v19
	v_pk_mul_f32 v[4:5], v[4:5], v[20:21] op_sel_hi:[1,0]
	s_andn2_b64 vcc, exec, s[0:1]
	v_add_f32_e32 v19, 1.0, v19
	v_rcp_f32_e32 v23, v19
	s_nop 0
	v_pk_mul_f32 v[14:15], v[14:15], v[22:23]
	s_nop 0
	v_pk_mul_f32 v[6:7], v[6:7], v[14:15]
	v_pk_mul_f32 v[14:15], v[16:17], v[20:21] op_sel_hi:[1,0]
	s_nop 0
	v_mul_f32_e32 v16, 0xbfb8aa3b, v14
	v_mul_f32_e32 v17, 0xbfb8aa3b, v15
	v_exp_f32_e32 v16, v16
	v_exp_f32_e32 v17, v17
	v_add_f32_e32 v16, 1.0, v16
	v_add_f32_e32 v17, 1.0, v17
	v_rcp_f32_e32 v16, v16
	v_rcp_f32_e32 v17, v17
	s_nop 0
	v_pk_mul_f32 v[14:15], v[14:15], v[16:17]
	s_nop 0
	v_pk_mul_f32 v[8:9], v[8:9], v[14:15]
	v_mul_f32_e32 v14, 0xbfb8aa3b, v10
	v_mul_f32_e32 v15, 0xbfb8aa3b, v11
	v_exp_f32_e32 v14, v14
	v_exp_f32_e32 v15, v15
	v_add_f32_e32 v14, 1.0, v14
	v_add_f32_e32 v15, 1.0, v15
	v_rcp_f32_e32 v14, v14
	v_rcp_f32_e32 v15, v15
	s_nop 0
	v_pk_mul_f32 v[10:11], v[10:11], v[14:15]
	s_nop 0
	v_pk_mul_f32 v[10:11], v[2:3], v[10:11]
	v_pk_mul_f32 v[2:3], v[12:13], v[20:21] op_sel_hi:[1,0]
	s_nop 0
	v_mul_f32_e32 v12, 0xbfb8aa3b, v2
	v_mul_f32_e32 v13, 0xbfb8aa3b, v3
	v_exp_f32_e32 v12, v12
	v_exp_f32_e32 v13, v13
	v_add_f32_e32 v12, 1.0, v12
	v_add_f32_e32 v13, 1.0, v13
	v_rcp_f32_e32 v12, v12
	v_rcp_f32_e32 v13, v13
	s_nop 0
	v_pk_mul_f32 v[2:3], v[2:3], v[12:13]
	s_nop 0
	v_pk_mul_f32 v[12:13], v[4:5], v[2:3]
	v_cvt_pk_bf16_f32 v2, v6, v7
	v_cvt_pk_bf16_f32 v3, v8, v9
	v_cvt_pk_bf16_f32 v4, v10, v11
	v_cvt_pk_bf16_f32 v5, v12, v13
	v_mad_i64_i32 v[6:7], s[6:7], v18, s4, v[142:143]
	global_store_dwordx4 v[6:7], v[2:5], off
	s_cbranch_vccnz .LBB0_161
	s_andn2_b64 vcc, exec, s[12:13]
	s_cbranch_vccnz .LBB0_160
	s_barrier
	s_branch .LBB0_160

; __device__ __forceinline__ float row_ssq(const float* part, int pitch, int n4, int row, int fq) {
;     f32x4 v = (f32x4){0.f, 0.f, 0.f, 0.f};
;     if (fq < n4) v = *(const f32x4*)(part + (size_t)row * pitch + 4 * fq);
;     float s = (v[0] + v[1]) + (v[2] + v[3]);
;     s += __shfl_xor(s, 16); s += __shfl_xor(s, 32);
;     return s;
; }
;     __device__ __forceinline__ void operator()(const f32x4 (&acc)[2][2][4][2], const Unit& u, int wr, int wc, int fr, int fq) const {
;         const int row0 = u.pm * BM + wr * 64 + fr;
;         float rsv[2][4];
; #pragma unroll
;         for (int ai = 0; ai < 2; ++ai)
; #pragma unroll
;             for (int m = 0; m < 4; ++m) rsv[ai][m] = ssq_in ? rsqrtf(row_ssq(ssq_in, in_pitch, in_n4, row0 + ai * HALF + m * 16, fq) * inv_k + EPS) : 1.f;
.LBB0_331:
	v_readlane_b32 s0, v252, 23
	v_readlane_b32 s1, v252, 24
	v_lshl_add_u32 v156, s4, 8, v139
	v_mov_b32_e32 v163, 1.0
	v_cndmask_b32_e64 v0, 0, 1, s[0:1]
	v_cmp_ne_u32_e64 s[50:51], 1, v0
	s_andn2_b64 vcc, exec, s[0:1]
	v_ashrrev_i32_e32 v157, 31, v156
	v_mov_b32_e32 v164, 1.0
	v_mov_b32_e32 v162, 1.0
	v_mov_b32_e32 v161, 1.0
	v_mov_b32_e32 v160, 1.0
	v_mov_b32_e32 v155, 1.0
	v_mov_b32_e32 v153, 1.0
	v_mov_b32_e32 v151, 1.0
	v_or_b32_e32 v154, 16, v156
	v_or_b32_e32 v152, 32, v156
	v_or_b32_e32 v150, 48, v156
	v_add_u32_e32 v148, 0x80, v156
	v_ashrrev_i32_e32 v149, 31, v148
	s_cbranch_vccnz .Lrsv_win_done
	v_and_b32_e32 v166, 48, v241
	v_lshl_add_u32 v166, v139, 6, v166
	v_add_u32_e32 v166, 0x24000, v166
	ds_read_b128 v[168:171], v166
	ds_read_b128 v[172:175], v166 offset:1024
	ds_read_b128 v[176:179], v166 offset:2048
	ds_read_b128 v[180:183], v166 offset:3072
	v_and_b32_e32 v202, 64, v241
	v_xor_b32_e32 v200, 16, v241
	ds_read_b128 v[184:187], v166 offset:8192
	ds_read_b128 v[188:191], v166 offset:9216
	ds_read_b128 v[192:195], v166 offset:10240
	ds_read_b128 v[196:199], v166 offset:11264
	v_add_u32_e32 v202, 64, v202
	v_cmp_lt_i32_e32 vcc, v200, v202
	v_xor_b32_e32 v201, 32, v241
	s_nop 0
	v_cndmask_b32_e32 v200, v241, v200, vcc
	v_cmp_lt_i32_e32 vcc, v201, v202
	v_lshlrev_b32_e32 v200, 2, v200
	s_nop 0
	v_cndmask_b32_e32 v201, v241, v201, vcc
	v_lshlrev_b32_e32 v201, 2, v201
	s_waitcnt lgkmcnt(7)
	v_add_f32_e32 v168, v168, v169
	v_add_f32_e32 v170, v170, v171
	v_add_f32_e32 v168, v168, v170
	v_mov_b32_e32 v169, v168
	s_nop 1
	v_permlane16_swap_b32_e32 v168, v169
	s_waitcnt lgkmcnt(6)
	v_add_f32_e32 v172, v172, v173
	v_add_f32_e32 v174, v174, v175
	v_add_f32_e32 v172, v172, v174
	v_mov_b32_e32 v173, v172
	s_nop 1
	v_permlane16_swap_b32_e32 v172, v173
	s_waitcnt lgkmcnt(5)
	v_add_f32_e32 v176, v176, v177
	v_add_f32_e32 v178, v178, v179
	v_add_f32_e32 v176, v176, v178
	v_mov_b32_e32 v177, v176
	s_nop 1
	v_permlane16_swap_b32_e32 v176, v177
	s_waitcnt lgkmcnt(4)
	v_add_f32_e32 v180, v180, v181
	v_add_f32_e32 v182, v182, v183
	v_add_f32_e32 v180, v180, v182
	v_mov_b32_e32 v181, v180
	s_nop 1
	v_permlane16_swap_b32_e32 v180, v181
	s_waitcnt lgkmcnt(3)
	v_add_f32_e32 v184, v184, v185
	v_add_f32_e32 v186, v186, v187
	v_add_f32_e32 v184, v184, v186
	v_mov_b32_e32 v185, v184
	s_nop 1
	v_permlane16_swap_b32_e32 v184, v185
	s_waitcnt lgkmcnt(2)
	v_add_f32_e32 v188, v188, v189
	v_add_f32_e32 v190, v190, v191
	v_add_f32_e32 v188, v188, v190
	v_mov_b32_e32 v189, v188
	s_nop 1
	v_permlane16_swap_b32_e32 v188, v189
	s_waitcnt lgkmcnt(1)
	v_add_f32_e32 v192, v192, v193
	v_add_f32_e32 v194, v194, v195
	v_add_f32_e32 v192, v192, v194
	v_mov_b32_e32 v193, v192
	s_nop 1
	v_permlane16_swap_b32_e32 v192, v193
	s_waitcnt lgkmcnt(0)
	v_add_f32_e32 v196, v196, v197
	v_add_f32_e32 v198, v198, v199
	v_add_f32_e32 v196, v196, v198
	v_mov_b32_e32 v197, v196
	s_nop 1
	v_permlane16_swap_b32_e32 v196, v197
	s_waitcnt lgkmcnt(7)
	v_add_f32_e32 v168, v168, v169
	v_mov_b32_e32 v169, v168
	s_nop 1
	v_permlane32_swap_b32_e32 v168, v169
	s_waitcnt lgkmcnt(7)
	v_add_f32_e32 v172, v172, v173
	v_mov_b32_e32 v173, v172
	s_nop 1
	v_permlane32_swap_b32_e32 v172, v173
	s_waitcnt lgkmcnt(7)
	v_add_f32_e32 v176, v176, v177
	v_mov_b32_e32 v177, v176
	s_nop 1
	v_permlane32_swap_b32_e32 v176, v177
	s_waitcnt lgkmcnt(7)
	v_add_f32_e32 v180, v180, v181
	v_mov_b32_e32 v181, v180
	s_nop 1
	v_permlane32_swap_b32_e32 v180, v181
	s_waitcnt lgkmcnt(7)
	v_add_f32_e32 v184, v184, v185
	v_mov_b32_e32 v185, v184
	s_nop 1
	v_permlane32_swap_b32_e32 v184, v185
	s_waitcnt lgkmcnt(7)
	v_add_f32_e32 v188, v188, v189
	v_mov_b32_e32 v189, v188
	s_nop 1
	v_permlane32_swap_b32_e32 v188, v189
	s_waitcnt lgkmcnt(7)
	v_add_f32_e32 v192, v192, v193
	v_mov_b32_e32 v193, v192
	s_nop 1
	v_permlane32_swap_b32_e32 v192, v193
	s_waitcnt lgkmcnt(7)
	v_add_f32_e32 v196, v196, v197
	v_mov_b32_e32 v197, v196
	s_nop 1
	v_permlane32_swap_b32_e32 v196, v197
	s_waitcnt lgkmcnt(7)
	v_add_f32_e32 v168, v168, v169
	v_fmamk_f32 v168, v168, 0x3a800000, v239
	s_waitcnt lgkmcnt(6)
	v_add_f32_e32 v172, v172, v173
	v_fmamk_f32 v172, v172, 0x3a800000, v239
	s_waitcnt lgkmcnt(5)
	v_add_f32_e32 v176, v176, v177
	v_fmamk_f32 v176, v176, 0x3a800000, v239
	s_waitcnt lgkmcnt(4)
	v_add_f32_e32 v180, v180, v181
	v_fmamk_f32 v180, v180, 0x3a800000, v239
	s_waitcnt lgkmcnt(3)
	v_add_f32_e32 v184, v184, v185
	v_fmamk_f32 v184, v184, 0x3a800000, v239
	s_waitcnt lgkmcnt(2)
	v_add_f32_e32 v188, v188, v189
	v_fmamk_f32 v188, v188, 0x3a800000, v239
	s_waitcnt lgkmcnt(1)
	v_add_f32_e32 v192, v192, v193
	v_fmamk_f32 v192, v192, 0x3a800000, v239
	s_waitcnt lgkmcnt(0)
	v_add_f32_e32 v196, v196, v197
	v_fmamk_f32 v196, v196, 0x3a800000, v239
	s_nop 0
	v_rsq_f32_e32 v164, v168
	s_nop 0
	s_nop 0
	s_nop 0
	v_rsq_f32_e32 v163, v172
	s_nop 0
	s_nop 0
	s_nop 0
	v_rsq_f32_e32 v162, v176
	s_nop 0
	s_nop 0
	s_nop 0
	v_rsq_f32_e32 v161, v180
	s_nop 0
	s_nop 0
	s_nop 0
	v_rsq_f32_e32 v160, v184
	s_nop 0
	s_nop 0
	s_nop 0
	v_rsq_f32_e32 v155, v188
	s_nop 0
	s_nop 0
	s_nop 0
	v_rsq_f32_e32 v153, v192
	s_nop 0
	s_nop 0
	s_nop 0
	v_rsq_f32_e32 v151, v196
	s_nop 0
	s_nop 0

;     __device__ __forceinline__ void operator()(const f32x4 (&acc)[2][2][4][2], const Unit& u, int wr, int wc, int fr, int fq) const {
;     ...
;             for (int m = 0; m < 4; ++m) rsv[ai][m] = ssq_in ? rsqrtf(row_ssq(ssq_in, in_pitch, in_n4, row0 + ai * HALF + m * 16, fq) * inv_k + EPS) : 1.f;
; #pragma unroll
;         for (int bj = 0; bj < 2; ++bj) {
;             const int c0 = u.pn * BM + bj * HALF + wc * 32;
;             float scale = 1.f; bool sig = false, rp = false, st = true; float* sq = nullptr; int sqp = 0;
;             if (mode == 1) { const int slab = c0 >> 7;
;                 if (slab < 3) { sq = ssq_q + 4 * slab + wc; sqp = 16; } else if (slab < 5) { sq = ssq_kv + 4 * (slab - 3) + wc; sqp = 8; } else if (slab == 5) { rp = (wc == 0); st = (wc == 0); }
;                 else if (slab < 14) scale = C2_64; else if (slab < 18) {} else if (slab < 26) scale = C2_64; else if (slab < 42) {} else sig = true;
;             } else if (mode == 2) { rp = ((c0 % 96) == 64); scale = C2_96; }
;             if (!st) continue;
; #pragma unroll
;             for (int ai = 0; ai < 2; ++ai)
; #pragma unroll
;                 for (int m = 0; m < 4; ++m) {
;                     const int row = row0 + ai * HALF + m * 16; const float rs = rsv[ai][m] * scale;
;                     f32x4 v0 = acc[ai][bj][m][0] * rs, v1 = acc[ai][bj][m][1] * rs;
;                     if (rp) {
;                         const int pos = row & (SEQ - 1); const float* rb = rope + pos * 32 + 8 * (fq & 1); const bool hi2 = (fq >> 1) != 0;
;                         const f32x4 cs0 = *(const f32x4*)(rb), cs1 = *(const f32x4*)(rb + 4), sn0 = *(const f32x4*)(rb + 16), sn1 = *(const f32x4*)(rb + 20);
; #pragma unroll
;                         for (int e = 0; e < 4; ++e) { const float q0 = __shfl_xor(v0[e], 32), q1 = __shfl_xor(v1[e], 32);
;                             v0[e] = hi2 ? v0[e] * cs0[e] + q0 * sn0[e] : v0[e] * cs0[e] - q0 * sn0[e];
;                             v1[e] = hi2 ? v1[e] * cs1[e] + q1 * sn1[e] : v1[e] * cs1[e] - q1 * sn1[e]; } }
.LBB0_584:
	s_or_b64 exec, exec, s[18:19]
	v_mov_b32_e32 v202, v154
	v_add_f32_e32 v132, v177, v178
	v_pk_add_f32 v[130:131], v[134:135], v[130:131]
	v_fmamk_f32 v132, v132, 0x3b2aaaab, v239
	v_add_f32_e32 v130, v130, v131
	v_mov_b32_e32 v131, v130
	s_nop 1
	v_permlane16_swap_b32_e32 v130, v131
	s_lshl_b32 s4, s4, 8
	v_rsq_f32_e32 v132, v132
	s_nop 0
	s_or_b32 s18, s4, s31
	s_mul_hi_i32 s4, s18, 0x2aaaaaab
	s_waitcnt lgkmcnt(0)
	v_add_f32_e32 v131, v130, v131
	s_lshr_b32 s6, s4, 31
	s_lshr_b32 s4, s4, 4
	ds_bpermute_b32 v134, v168, v131
	s_add_i32 s4, s4, s6
	s_mulk_i32 s4, 0x60
	s_sub_i32 s4, s18, s4
	v_mul_f32_e32 v130, 0x3e16c740, v132
	s_cmp_eq_u32 s4, 64
	v_pk_mul_f32 v[132:133], v[122:123], v[130:131] op_sel_hi:[1,0]
	v_lshlrev_b32_e32 v122, 7, v154
	s_cselect_b64 s[20:21], -1, 0
	s_cmp_lg_u32 s4, 64
	v_pk_mul_f32 v[128:129], v[128:129], v[130:131] op_sel_hi:[1,0]
	v_pk_mul_f32 v[126:127], v[126:127], v[130:131] op_sel_hi:[1,0]
	v_pk_mul_f32 v[124:125], v[124:125], v[130:131] op_sel_hi:[1,0]
	v_and_b32_e32 v122, 0x3e780, v122
	s_cbranch_scc1 .LBB0_586
	v_mov_b32_e32 v123, v1
	v_lshl_add_u64 v[164:165], v[148:149], 0, v[122:123]
	global_load_dwordx4 v[176:179], v[164:165], off offset:16
	global_load_dwordx4 v[180:183], v[164:165], off
	global_load_dwordx4 v[184:187], v[164:165], off offset:80
	global_load_dwordx4 v[188:191], v[164:165], off offset:64
	v_add_u32_e32 v194, 0x10, v202
	v_lshlrev_b32_e32 v194, 7, v194
	v_and_b32_e32 v194, 0x3ff80, v194
	v_mov_b32_e32 v195, v1
	v_lshl_add_u64 v[194:195], v[148:149], 0, v[194:195]
	global_load_dwordx4 v[222:225], v[194:195], off offset:16
	global_load_dwordx4 v[226:229], v[194:195], off
	global_load_dwordx4 v[230:233], v[194:195], off offset:80
	global_load_dwordx4 v[234:237], v[194:195], off offset:64
	ds_bpermute_b32 v164, v168, v126
	ds_bpermute_b32 v192, v168, v132
	ds_bpermute_b32 v165, v168, v127
	ds_bpermute_b32 v193, v168, v133
	s_waitcnt vmcnt(4) lgkmcnt(0)
	v_pk_mul_f32 v[184:185], v[184:185], v[192:193]
	v_pk_mul_f32 v[164:165], v[188:189], v[164:165]
	ds_bpermute_b32 v188, v168, v128
	ds_bpermute_b32 v192, v168, v124
	ds_bpermute_b32 v189, v168, v129
	ds_bpermute_b32 v193, v168, v125
	v_cndmask_b32_e64 v165, v165, -v165, s[46:47]
	v_cndmask_b32_e64 v164, v164, -v164, s[46:47]
	v_pk_fma_f32 v[126:127], v[126:127], v[180:181], v[164:165]
	s_waitcnt lgkmcnt(1)
	v_pk_mul_f32 v[188:189], v[190:191], v[188:189]
	s_waitcnt lgkmcnt(0)
	v_pk_mul_f32 v[164:165], v[186:187], v[192:193]
	v_cndmask_b32_e64 v189, v189, -v189, s[46:47]
	v_cndmask_b32_e64 v188, v188, -v188, s[46:47]
	v_cndmask_b32_e64 v165, v165, -v165, s[46:47]
	v_cndmask_b32_e64 v164, v164, -v164, s[46:47]
	v_cndmask_b32_e64 v181, v185, -v185, s[46:47]
	v_cndmask_b32_e64 v180, v184, -v184, s[46:47]
	v_pk_fma_f32 v[128:129], v[128:129], v[182:183], v[188:189]
	v_pk_fma_f32 v[124:125], v[124:125], v[178:179], v[164:165]
	v_pk_fma_f32 v[132:133], v[132:133], v[176:177], v[180:181]

;     __device__ __forceinline__ void operator()(const f32x4 (&acc)[2][2][4][2], const Unit& u, int wr, int wc, int fr, int fq) const {
;     ...
;             for (int m = 0; m < 4; ++m) rsv[ai][m] = ssq_in ? rsqrtf(row_ssq(ssq_in, in_pitch, in_n4, row0 + ai * HALF + m * 16, fq) * inv_k + EPS) : 1.f;
; #pragma unroll
;         for (int bj = 0; bj < 2; ++bj) {
;             const int c0 = u.pn * BM + bj * HALF + wc * 32;
;             float scale = 1.f; bool sig = false, rp = false, st = true; float* sq = nullptr; int sqp = 0;
;             if (mode == 1) { const int slab = c0 >> 7;
;                 if (slab < 3) { sq = ssq_q + 4 * slab + wc; sqp = 16; } else if (slab < 5) { sq = ssq_kv + 4 * (slab - 3) + wc; sqp = 8; } else if (slab == 5) { rp = (wc == 0); st = (wc == 0); }
;                 else if (slab < 14) scale = C2_64; else if (slab < 18) {} else if (slab < 26) scale = C2_64; else if (slab < 42) {} else sig = true;
;             } else if (mode == 2) { rp = ((c0 % 96) == 64); scale = C2_96; }
;             if (!st) continue;
; #pragma unroll
;             for (int ai = 0; ai < 2; ++ai)
; #pragma unroll
;                 for (int m = 0; m < 4; ++m) {
;                     const int row = row0 + ai * HALF + m * 16; const float rs = rsv[ai][m] * scale;
;                     f32x4 v0 = acc[ai][bj][m][0] * rs, v1 = acc[ai][bj][m][1] * rs;
;                     if (rp) {
;                         const int pos = row & (SEQ - 1); const float* rb = rope + pos * 32 + 8 * (fq & 1); const bool hi2 = (fq >> 1) != 0;
;                         const f32x4 cs0 = *(const f32x4*)(rb), cs1 = *(const f32x4*)(rb + 4), sn0 = *(const f32x4*)(rb + 16), sn1 = *(const f32x4*)(rb + 20);
; #pragma unroll
;                         for (int e = 0; e < 4; ++e) { const float q0 = __shfl_xor(v0[e], 32), q1 = __shfl_xor(v1[e], 32);
;                             v0[e] = hi2 ? v0[e] * cs0[e] + q0 * sn0[e] : v0[e] * cs0[e] - q0 * sn0[e];
;                             v1[e] = hi2 ? v1[e] * cs1[e] + q1 * sn1[e] : v1[e] * cs1[e] - q1 * sn1[e]; } }
;                     if (sig) {
; #pragma unroll
;                         for (int e = 0; e < 4; ++e) { v0[e] = fast_sigmoid(v0[e]); v1[e] = fast_sigmoid(v1[e]); } }
;                     if (sq) { float s = (v0[0] * v0[0] + v0[1] * v0[1]) + (v0[2] * v0[2] + v0[3] * v0[3]) + (v1[0] * v1[0] + v1[1] * v1[1]) + (v1[2] * v1[2] + v1[3] * v1[3]);
.LBB0_588:
	v_add_f32_e32 v115, v173, v174
	v_fmamk_f32 v115, v115, 0x3b2aaaab, v239
	v_cvt_pk_bf16_f32 v177, v116, v117
	v_mov_b64_e32 v[116:117], s[58:59]
	v_rsq_f32_e32 v115, v115
	s_nop 0
	v_cvt_pk_bf16_f32 v174, v118, v119
	v_mad_i64_i32 v[116:117], s[6:7], v162, s4, v[116:117]
	v_lshl_add_u64 v[116:117], s[18:19], 1, v[116:117]
	v_lshl_add_u64 v[118:119], v[116:117], 0, v[0:1]
	v_mul_f32_e32 v116, 0x3e16c740, v115
	v_cvt_pk_bf16_f32 v175, v120, v121
	v_pk_mul_f32 v[120:121], v[106:107], v[116:117] op_sel_hi:[1,0]
	v_lshlrev_b32_e32 v106, 7, v160
	v_cvt_pk_bf16_f32 v176, v128, v129
	v_pk_mul_f32 v[112:113], v[112:113], v[116:117] op_sel_hi:[1,0]
	v_pk_mul_f32 v[110:111], v[110:111], v[116:117] op_sel_hi:[1,0]
	v_pk_mul_f32 v[108:109], v[108:109], v[116:117] op_sel_hi:[1,0]
	s_and_b64 vcc, exec, s[50:51]
	v_and_b32_e32 v106, 0x3f780, v106
	global_store_dwordx4 v[118:119], v[174:177], off
	s_cbranch_vccnz .LBB0_590
	v_mov_b32_e32 v107, v1
	v_lshl_add_u64 v[128:129], v[148:149], 0, v[106:107]
	v_add_u32_e32 v194, 0x30, v202
	v_lshlrev_b32_e32 v194, 7, v194
	v_and_b32_e32 v194, 0x3ff80, v194
	v_mov_b32_e32 v195, v1
	v_lshl_add_u64 v[194:195], v[148:149], 0, v[194:195]
	global_load_dwordx4 v[222:225], v[194:195], off offset:16
	global_load_dwordx4 v[226:229], v[194:195], off
	global_load_dwordx4 v[230:233], v[194:195], off offset:80
	global_load_dwordx4 v[234:237], v[194:195], off offset:64
	ds_bpermute_b32 v132, v168, v120
	ds_bpermute_b32 v133, v168, v121
	ds_bpermute_b32 v128, v168, v110
	ds_bpermute_b32 v129, v168, v111
	ds_bpermute_b32 v164, v168, v112
	ds_bpermute_b32 v165, v168, v113
	s_waitcnt vmcnt(4) lgkmcnt(0)
	v_mov_b32_e32 v174, v206
	v_mov_b32_e32 v175, v207
	v_mov_b32_e32 v176, v208
	v_mov_b32_e32 v177, v209
	v_mov_b32_e32 v178, v210
	v_mov_b32_e32 v179, v211
	v_mov_b32_e32 v180, v212
	v_mov_b32_e32 v181, v213
	v_mov_b32_e32 v182, v214
	v_mov_b32_e32 v183, v215
	v_mov_b32_e32 v184, v216
	v_mov_b32_e32 v185, v217
	v_mov_b32_e32 v186, v218
	v_mov_b32_e32 v187, v219
	v_mov_b32_e32 v188, v220
	v_mov_b32_e32 v189, v221
	v_pk_mul_f32 v[132:133], v[182:183], v[132:133]
	ds_bpermute_b32 v182, v168, v108
	ds_bpermute_b32 v183, v168, v109
	v_pk_mul_f32 v[128:129], v[186:187], v[128:129]
	v_pk_mul_f32 v[164:165], v[188:189], v[164:165]
	v_cndmask_b32_e64 v129, v129, -v129, s[46:47]
	v_cndmask_b32_e64 v128, v128, -v128, s[46:47]
	v_pk_fma_f32 v[110:111], v[110:111], v[178:179], v[128:129]
	s_waitcnt lgkmcnt(0)
	v_pk_mul_f32 v[128:129], v[184:185], v[182:183]
	v_cndmask_b32_e64 v165, v165, -v165, s[46:47]
	v_cndmask_b32_e64 v164, v164, -v164, s[46:47]
	v_cndmask_b32_e64 v129, v129, -v129, s[46:47]
	v_cndmask_b32_e64 v128, v128, -v128, s[46:47]
	v_cndmask_b32_e64 v133, v133, -v133, s[46:47]
	v_cndmask_b32_e64 v132, v132, -v132, s[46:47]
	v_pk_fma_f32 v[112:113], v[112:113], v[180:181], v[164:165]
	v_pk_fma_f32 v[108:109], v[108:109], v[176:177], v[128:129]
	v_pk_fma_f32 v[120:121], v[120:121], v[174:175], v[132:133]
;     __device__ __forceinline__ void operator()(const f32x4 (&acc)[2][2][4][2], const Unit& u, int wr, int wc, int fr, int fq) const {
;     ...
;             for (int m = 0; m < 4; ++m) rsv[ai][m] = ssq_in ? rsqrtf(row_ssq(ssq_in, in_pitch, in_n4, row0 + ai * HALF + m * 16, fq) * inv_k + EPS) : 1.f;
; #pragma unroll
;         for (int bj = 0; bj < 2; ++bj) {
;             const int c0 = u.pn * BM + bj * HALF + wc * 32;
;             float scale = 1.f; bool sig = false, rp = false, st = true; float* sq = nullptr; int sqp = 0;
;             if (mode == 1) { const int slab = c0 >> 7;
;                 if (slab < 3) { sq = ssq_q + 4 * slab + wc; sqp = 16; } else if (slab < 5) { sq = ssq_kv + 4 * (slab - 3) + wc; sqp = 8; } else if (slab == 5) { rp = (wc == 0); st = (wc == 0); }
;                 else if (slab < 14) scale = C2_64; else if (slab < 18) {} else if (slab < 26) scale = C2_64; else if (slab < 42) {} else sig = true;
;             } else if (mode == 2) { rp = ((c0 % 96) == 64); scale = C2_96; }
;             if (!st) continue;
; #pragma unroll
;             for (int ai = 0; ai < 2; ++ai)
; #pragma unroll
;                 for (int m = 0; m < 4; ++m) {
;                     const int row = row0 + ai * HALF + m * 16; const float rs = rsv[ai][m] * scale;
;                     f32x4 v0 = acc[ai][bj][m][0] * rs, v1 = acc[ai][bj][m][1] * rs;
;                     if (rp) {
;                         const int pos = row & (SEQ - 1); const float* rb = rope + pos * 32 + 8 * (fq & 1); const bool hi2 = (fq >> 1) != 0;
;                         const f32x4 cs0 = *(const f32x4*)(rb), cs1 = *(const f32x4*)(rb + 4), sn0 = *(const f32x4*)(rb + 16), sn1 = *(const f32x4*)(rb + 20);
; #pragma unroll
;                         for (int e = 0; e < 4; ++e) { const float q0 = __shfl_xor(v0[e], 32), q1 = __shfl_xor(v1[e], 32);
;                             v0[e] = hi2 ? v0[e] * cs0[e] + q0 * sn0[e] : v0[e] * cs0[e] - q0 * sn0[e];
;                             v1[e] = hi2 ? v1[e] * cs1[e] + q1 * sn1[e] : v1[e] * cs1[e] - q1 * sn1[e]; } }
;                     if (sig) {
; #pragma unroll
;                         for (int e = 0; e < 4; ++e) { v0[e] = fast_sigmoid(v0[e]); v1[e] = fast_sigmoid(v1[e]); } }
;                     if (sq) { float s = (v0[0] * v0[0] + v0[1] * v0[1]) + (v0[2] * v0[2] + v0[3] * v0[3]) + (v1[0] * v1[0] + v1[1] * v1[1]) + (v1[2] * v1[2] + v1[3] * v1[3]);
.LBB0_590:
	v_add_f32_e32 v107, v171, v172
	v_fmamk_f32 v107, v107, 0x3b2aaaab, v239
	v_cvt_pk_bf16_f32 v175, v108, v109
	v_mov_b64_e32 v[108:109], s[58:59]
	v_rsq_f32_e32 v107, v107
	s_nop 0
	v_cvt_pk_bf16_f32 v172, v110, v111
	v_mad_i64_i32 v[108:109], s[6:7], v160, s4, v[108:109]
	v_lshl_add_u64 v[108:109], s[18:19], 1, v[108:109]
	v_lshl_add_u64 v[110:111], v[108:109], 0, v[0:1]
	v_mul_f32_e32 v108, 0x3e16c740, v107
	v_cvt_pk_bf16_f32 v173, v112, v113
	v_pk_mul_f32 v[112:113], v[98:99], v[108:109] op_sel_hi:[1,0]
	v_lshlrev_b32_e32 v98, 7, v158
	v_cvt_pk_bf16_f32 v174, v120, v121
	v_pk_mul_f32 v[104:105], v[104:105], v[108:109] op_sel_hi:[1,0]
	v_pk_mul_f32 v[102:103], v[102:103], v[108:109] op_sel_hi:[1,0]
	v_pk_mul_f32 v[100:101], v[100:101], v[108:109] op_sel_hi:[1,0]
	s_and_b64 vcc, exec, s[50:51]
	v_and_b32_e32 v98, 0x3ff80, v98
	global_store_dwordx4 v[110:111], v[172:175], off
	s_cbranch_vccnz .LBB0_592
	v_mov_b32_e32 v99, v1
	v_lshl_add_u64 v[120:121], v[148:149], 0, v[98:99]
	v_add_u32_e32 v194, 0x80, v202
	v_lshlrev_b32_e32 v194, 7, v194
	v_and_b32_e32 v194, 0x3ff80, v194
	v_mov_b32_e32 v195, v1
	v_lshl_add_u64 v[194:195], v[148:149], 0, v[194:195]
	global_load_dwordx4 v[206:209], v[194:195], off offset:16
	global_load_dwordx4 v[210:213], v[194:195], off
	global_load_dwordx4 v[214:217], v[194:195], off offset:80
	global_load_dwordx4 v[218:221], v[194:195], off offset:64
	ds_bpermute_b32 v120, v168, v102
	ds_bpermute_b32 v121, v168, v103
	ds_bpermute_b32 v128, v168, v112
	ds_bpermute_b32 v129, v168, v113
	ds_bpermute_b32 v132, v168, v104
	ds_bpermute_b32 v164, v168, v100
	ds_bpermute_b32 v133, v168, v105
	ds_bpermute_b32 v165, v168, v101
	s_waitcnt vmcnt(4) lgkmcnt(0)
	v_mov_b32_e32 v172, v222
	v_mov_b32_e32 v173, v223
	v_mov_b32_e32 v174, v224
	v_mov_b32_e32 v175, v225
	v_mov_b32_e32 v176, v226
	v_mov_b32_e32 v177, v227
	v_mov_b32_e32 v178, v228
	v_mov_b32_e32 v179, v229
	v_mov_b32_e32 v180, v230
	v_mov_b32_e32 v181, v231
	v_mov_b32_e32 v182, v232
	v_mov_b32_e32 v183, v233
	v_mov_b32_e32 v184, v234
	v_mov_b32_e32 v185, v235
	v_mov_b32_e32 v186, v236
	v_mov_b32_e32 v187, v237
	v_pk_mul_f32 v[128:129], v[180:181], v[128:129]
	v_pk_mul_f32 v[120:121], v[184:185], v[120:121]
	v_pk_mul_f32 v[132:133], v[186:187], v[132:133]
	v_cndmask_b32_e64 v121, v121, -v121, s[46:47]
	v_cndmask_b32_e64 v120, v120, -v120, s[46:47]
	v_pk_fma_f32 v[102:103], v[102:103], v[176:177], v[120:121]
	v_pk_mul_f32 v[120:121], v[182:183], v[164:165]
	v_cndmask_b32_e64 v133, v133, -v133, s[46:47]
	v_cndmask_b32_e64 v132, v132, -v132, s[46:47]
	v_cndmask_b32_e64 v121, v121, -v121, s[46:47]
	v_cndmask_b32_e64 v120, v120, -v120, s[46:47]
	v_cndmask_b32_e64 v129, v129, -v129, s[46:47]
	v_cndmask_b32_e64 v128, v128, -v128, s[46:47]
	v_pk_fma_f32 v[104:105], v[104:105], v[178:179], v[132:133]
	v_pk_fma_f32 v[100:101], v[100:101], v[174:175], v[120:121]
	v_pk_fma_f32 v[112:113], v[112:113], v[172:173], v[128:129]
.LBB0_592:
	v_add_f32_e32 v99, v169, v170
	v_fmamk_f32 v99, v99, 0x3b2aaaab, v239
	v_cvt_pk_bf16_f32 v173, v100, v101
	v_mov_b64_e32 v[100:101], s[58:59]
	v_rsq_f32_e32 v99, v99
	s_nop 0
	v_cvt_pk_bf16_f32 v170, v102, v103
	v_mad_i64_i32 v[100:101], s[6:7], v158, s4, v[100:101]
	v_lshl_add_u64 v[100:101], s[18:19], 1, v[100:101]
	v_lshl_add_u64 v[102:103], v[100:101], 0, v[0:1]
	v_mul_f32_e32 v100, 0x3e16c740, v99
	v_cvt_pk_bf16_f32 v171, v104, v105
	v_pk_mul_f32 v[104:105], v[90:91], v[100:101] op_sel_hi:[1,0]
	v_lshlrev_b32_e32 v90, 7, v156
	v_cvt_pk_bf16_f32 v172, v112, v113
	v_pk_mul_f32 v[96:97], v[96:97], v[100:101] op_sel_hi:[1,0]
	v_pk_mul_f32 v[94:95], v[94:95], v[100:101] op_sel_hi:[1,0]
	v_pk_mul_f32 v[92:93], v[92:93], v[100:101] op_sel_hi:[1,0]
	s_and_b64 vcc, exec, s[50:51]
	v_and_b32_e32 v90, 0x3e780, v90
	global_store_dwordx4 v[102:103], v[170:173], off
	s_cbranch_vccnz .LBB0_594
	v_mov_b32_e32 v91, v1
	v_lshl_add_u64 v[112:113], v[148:149], 0, v[90:91]
	v_add_u32_e32 v194, 0x90, v202
	v_lshlrev_b32_e32 v194, 7, v194
	v_and_b32_e32 v194, 0x3ff80, v194
	v_mov_b32_e32 v195, v1
	v_lshl_add_u64 v[194:195], v[148:149], 0, v[194:195]
	global_load_dwordx4 v[222:225], v[194:195], off offset:16
	global_load_dwordx4 v[226:229], v[194:195], off
	global_load_dwordx4 v[230:233], v[194:195], off offset:80
	global_load_dwordx4 v[234:237], v[194:195], off offset:64
	ds_bpermute_b32 v112, v168, v94
	ds_bpermute_b32 v113, v168, v95
	ds_bpermute_b32 v120, v168, v104
	ds_bpermute_b32 v121, v168, v105
	ds_bpermute_b32 v128, v168, v96
	ds_bpermute_b32 v132, v168, v92
	ds_bpermute_b32 v129, v168, v97
	ds_bpermute_b32 v133, v168, v93
	s_waitcnt vmcnt(4) lgkmcnt(0)
	v_mov_b32_e32 v170, v206
	v_mov_b32_e32 v171, v207
	v_mov_b32_e32 v172, v208
	v_mov_b32_e32 v173, v209
	v_mov_b32_e32 v174, v210
	v_mov_b32_e32 v175, v211
	v_mov_b32_e32 v176, v212
	v_mov_b32_e32 v177, v213
	v_mov_b32_e32 v178, v214
	v_mov_b32_e32 v179, v215
	v_mov_b32_e32 v180, v216
	v_mov_b32_e32 v181, v217
	v_mov_b32_e32 v182, v218
	v_mov_b32_e32 v183, v219
	v_mov_b32_e32 v184, v220
	v_mov_b32_e32 v185, v221
	v_pk_mul_f32 v[120:121], v[178:179], v[120:121]
	v_pk_mul_f32 v[112:113], v[182:183], v[112:113]
	v_pk_mul_f32 v[128:129], v[184:185], v[128:129]
	v_cndmask_b32_e64 v113, v113, -v113, s[46:47]
	v_cndmask_b32_e64 v112, v112, -v112, s[46:47]
	v_pk_fma_f32 v[94:95], v[94:95], v[174:175], v[112:113]
	v_pk_mul_f32 v[112:113], v[180:181], v[132:133]
	v_cndmask_b32_e64 v129, v129, -v129, s[46:47]
	v_cndmask_b32_e64 v128, v128, -v128, s[46:47]
	v_cndmask_b32_e64 v113, v113, -v113, s[46:47]
	v_cndmask_b32_e64 v112, v112, -v112, s[46:47]
	v_cndmask_b32_e64 v121, v121, -v121, s[46:47]
	v_cndmask_b32_e64 v120, v120, -v120, s[46:47]
	v_pk_fma_f32 v[96:97], v[96:97], v[176:177], v[128:129]
	v_pk_fma_f32 v[92:93], v[92:93], v[172:173], v[112:113]
	v_pk_fma_f32 v[104:105], v[104:105], v[170:171], v[120:121]

;     __device__ __forceinline__ void operator()(const f32x4 (&acc)[2][2][4][2], const Unit& u, int wr, int wc, int fr, int fq) const {
;     ...
;             for (int m = 0; m < 4; ++m) rsv[ai][m] = ssq_in ? rsqrtf(row_ssq(ssq_in, in_pitch, in_n4, row0 + ai * HALF + m * 16, fq) * inv_k + EPS) : 1.f;
; #pragma unroll
;         for (int bj = 0; bj < 2; ++bj) {
;             const int c0 = u.pn * BM + bj * HALF + wc * 32;
;             float scale = 1.f; bool sig = false, rp = false, st = true; float* sq = nullptr; int sqp = 0;
;             if (mode == 1) { const int slab = c0 >> 7;
;                 if (slab < 3) { sq = ssq_q + 4 * slab + wc; sqp = 16; } else if (slab < 5) { sq = ssq_kv + 4 * (slab - 3) + wc; sqp = 8; } else if (slab == 5) { rp = (wc == 0); st = (wc == 0); }
;                 else if (slab < 14) scale = C2_64; else if (slab < 18) {} else if (slab < 26) scale = C2_64; else if (slab < 42) {} else sig = true;
;             } else if (mode == 2) { rp = ((c0 % 96) == 64); scale = C2_96; }
;             if (!st) continue;
; #pragma unroll
;             for (int ai = 0; ai < 2; ++ai)
; #pragma unroll
;                 for (int m = 0; m < 4; ++m) {
;                     const int row = row0 + ai * HALF + m * 16; const float rs = rsv[ai][m] * scale;
;                     f32x4 v0 = acc[ai][bj][m][0] * rs, v1 = acc[ai][bj][m][1] * rs;
;                     if (rp) {
;                         const int pos = row & (SEQ - 1); const float* rb = rope + pos * 32 + 8 * (fq & 1); const bool hi2 = (fq >> 1) != 0;
;                         const f32x4 cs0 = *(const f32x4*)(rb), cs1 = *(const f32x4*)(rb + 4), sn0 = *(const f32x4*)(rb + 16), sn1 = *(const f32x4*)(rb + 20);
; #pragma unroll
;                         for (int e = 0; e < 4; ++e) { const float q0 = __shfl_xor(v0[e], 32), q1 = __shfl_xor(v1[e], 32);
;                             v0[e] = hi2 ? v0[e] * cs0[e] + q0 * sn0[e] : v0[e] * cs0[e] - q0 * sn0[e];
;                             v1[e] = hi2 ? v1[e] * cs1[e] + q1 * sn1[e] : v1[e] * cs1[e] - q1 * sn1[e]; } }
;                     if (sig) {
; #pragma unroll
;                         for (int e = 0; e < 4; ++e) { v0[e] = fast_sigmoid(v0[e]); v1[e] = fast_sigmoid(v1[e]); } }
;                     if (sq) { float s = (v0[0] * v0[0] + v0[1] * v0[1]) + (v0[2] * v0[2] + v0[3] * v0[3]) + (v1[0] * v1[0] + v1[1] * v1[1]) + (v1[2] * v1[2] + v1[3] * v1[3]);
.LBB0_654:
	s_or_b64 exec, exec, s[0:1]
	s_waitcnt lgkmcnt(0)
	v_add_f32_e32 v132, v134, v135
	v_fmamk_f32 v132, v132, 0x3b800000, v239
	s_mov_b32 s0, 0x800000
	v_pk_add_f32 v[130:131], v[168:169], v[130:131]
	v_rsq_f32_e32 v132, v132
	s_nop 0
	v_add_f32_e32 v130, v130, v131
	v_mov_b32_e32 v131, v130
	s_nop 1
	v_permlane16_swap_b32_e32 v130, v131
	v_readlane_b32 s1, v254, 20
	v_add_f32_e32 v133, v175, v176
	v_fmamk_f32 v133, v133, 0x3b800000, v239
	s_waitcnt lgkmcnt(0)
	v_add_f32_e32 v130, v130, v131
	v_rsq_f32_e32 v134, v133
	s_nop 0
	v_mov_b32_e32 v131, v130
	s_nop 1
	v_permlane32_swap_b32_e32 v130, v131
	v_readlane_b32 s10, v250, 45
	v_readlane_b32 s11, v250, 46
	v_add_f32_e32 v133, v158, v174
	v_fmamk_f32 v133, v133, 0x3b800000, v239
	s_waitcnt lgkmcnt(0)
	v_add_f32_e32 v130, v130, v131
	v_rsq_f32_e32 v158, v133
	s_nop 0
	v_fmamk_f32 v130, v130, 0x3b800000, v239
	v_mul_f32_e32 v131, 0x4b800000, v130
	s_mov_b64 s[6:7], 0x90000
	v_add_f32_e32 v133, v160, v173
	v_fmamk_f32 v133, v133, 0x3b800000, v239
	v_pk_mul_f32 v[94:95], v[94:95], v[158:159] op_sel_hi:[1,0]
	v_rsq_f32_e32 v160, v133
	s_nop 0
	v_pk_mul_f32 v[96:97], v[96:97], v[158:159] op_sel_hi:[1,0]
	v_pk_mul_f32 v[32:33], v[32:33], v[158:159] op_sel_hi:[1,0]
	v_pk_mul_f32 v[30:31], v[30:31], v[158:159] op_sel_hi:[1,0]
	v_add_f32_e32 v133, v162, v172
	v_fmamk_f32 v133, v133, 0x3b800000, v239
	v_pk_mul_f32 v[102:103], v[102:103], v[160:161] op_sel_hi:[1,0]
	v_rsq_f32_e32 v162, v133
	s_nop 0
	v_pk_mul_f32 v[104:105], v[104:105], v[160:161] op_sel_hi:[1,0]
	v_pk_mul_f32 v[40:41], v[40:41], v[160:161] op_sel_hi:[1,0]
	v_pk_mul_f32 v[38:39], v[38:39], v[160:161] op_sel_hi:[1,0]
	v_add_f32_e32 v133, v164, v171
	v_fmamk_f32 v133, v133, 0x3b800000, v239
	v_pk_mul_f32 v[110:111], v[110:111], v[162:163] op_sel_hi:[1,0]
	v_rsq_f32_e32 v164, v133
	s_nop 0
	v_pk_mul_f32 v[112:113], v[112:113], v[162:163] op_sel_hi:[1,0]
	v_pk_mul_f32 v[48:49], v[48:49], v[162:163] op_sel_hi:[1,0]
	v_pk_mul_f32 v[46:47], v[46:47], v[162:163] op_sel_hi:[1,0]
	v_add_f32_e32 v133, v166, v170
	v_fmamk_f32 v133, v133, 0x3b800000, v239
	v_cmp_gt_f32_e32 vcc, s0, v133
	v_mul_f32_e32 v135, 0x4b800000, v133
	v_pk_mul_f32 v[118:119], v[118:119], v[164:165] op_sel_hi:[1,0]
	v_cndmask_b32_e32 v133, v133, v135, vcc
	v_rsq_f32_e32 v133, v133
	v_pk_mul_f32 v[120:121], v[120:121], v[164:165] op_sel_hi:[1,0]
	v_pk_mul_f32 v[58:59], v[58:59], v[164:165] op_sel_hi:[1,0]
	v_mul_f32_e32 v135, 0x45800000, v133
	v_cndmask_b32_e32 v166, v133, v135, vcc
	v_cmp_gt_f32_e32 vcc, s0, v130
	s_lshl_b32 s0, s4, 8
	s_or_b32 s0, s0, s1
	v_pk_mul_f32 v[126:127], v[126:127], v[166:167] op_sel_hi:[1,0]
	s_ashr_i32 s1, s0, 31
	v_pk_mul_f32 v[168:169], v[124:125], v[166:167] op_sel_hi:[1,0]
	v_pk_mul_f32 v[124:125], v[122:123], v[166:167] op_sel_hi:[1,0]
	v_cvt_pk_bf16_f32 v122, v126, v127
	v_lshlrev_b64 v[126:127], 12, v[146:147]
	v_lshl_add_u64 v[126:127], s[10:11], 0, v[126:127]
	s_lshl_b64 s[0:1], s[0:1], 1
	v_pk_mul_f32 v[128:129], v[128:129], v[166:167] op_sel_hi:[1,0]
	v_lshl_add_u64 v[126:127], v[126:127], 0, s[0:1]
	v_cvt_pk_bf16_f32 v123, v128, v129
	v_cvt_pk_bf16_f32 v124, v124, v125
	v_cvt_pk_bf16_f32 v125, v168, v169
	v_lshl_add_u64 v[126:127], v[126:127], 0, v[0:1]
	global_store_dwordx4 v[126:127], v[122:125], off
	v_cndmask_b32_e32 v130, v130, v131, vcc
	v_rsq_f32_e32 v130, v130
	v_pk_mul_f32 v[122:123], v[116:117], v[164:165] op_sel_hi:[1,0]
	v_pk_mul_f32 v[116:117], v[114:115], v[164:165] op_sel_hi:[1,0]
	v_cvt_pk_bf16_f32 v114, v118, v119
	v_lshlrev_b64 v[118:119], 12, v[148:149]
	v_lshl_add_u64 v[118:119], s[10:11], 0, v[118:119]
	v_lshl_add_u64 v[118:119], v[118:119], 0, s[0:1]
	v_cvt_pk_bf16_f32 v115, v120, v121
	v_cvt_pk_bf16_f32 v116, v116, v117
	v_cvt_pk_bf16_f32 v117, v122, v123
	v_lshl_add_u64 v[118:119], v[118:119], 0, v[0:1]
	global_store_dwordx4 v[118:119], v[114:117], off
	v_mul_f32_e32 v131, 0x45800000, v130
	v_pk_mul_f32 v[88:89], v[88:89], v[134:135] op_sel_hi:[1,0]
	v_pk_mul_f32 v[114:115], v[108:109], v[162:163] op_sel_hi:[1,0]
	v_pk_mul_f32 v[108:109], v[106:107], v[162:163] op_sel_hi:[1,0]
	v_cvt_pk_bf16_f32 v106, v110, v111
	v_lshlrev_b64 v[110:111], 12, v[150:151]
	v_lshl_add_u64 v[110:111], s[10:11], 0, v[110:111]
	v_lshl_add_u64 v[110:111], v[110:111], 0, s[0:1]
	v_cvt_pk_bf16_f32 v107, v112, v113
	v_cvt_pk_bf16_f32 v108, v108, v109
	v_cvt_pk_bf16_f32 v109, v114, v115
	v_lshl_add_u64 v[110:111], v[110:111], 0, v[0:1]
	global_store_dwordx4 v[110:111], v[106:109], off
	s_mov_b32 s4, 0x90000
	v_cndmask_b32_e32 v130, v130, v131, vcc
	v_pk_mul_f32 v[106:107], v[100:101], v[160:161] op_sel_hi:[1,0]
	v_pk_mul_f32 v[100:101], v[98:99], v[160:161] op_sel_hi:[1,0]
	v_cvt_pk_bf16_f32 v98, v102, v103
	v_lshlrev_b64 v[102:103], 12, v[152:153]
	v_lshl_add_u64 v[102:103], s[10:11], 0, v[102:103]
	v_lshl_add_u64 v[102:103], v[102:103], 0, s[0:1]
	v_cvt_pk_bf16_f32 v99, v104, v105
	v_cvt_pk_bf16_f32 v100, v100, v101
	v_cvt_pk_bf16_f32 v101, v106, v107
	v_lshl_add_u64 v[102:103], v[102:103], 0, v[0:1]
	global_store_dwordx4 v[102:103], v[98:101], off
	v_pk_mul_f32 v[86:87], v[86:87], v[134:135] op_sel_hi:[1,0]
	v_pk_mul_f32 v[76:77], v[76:77], v[132:133] op_sel_hi:[1,0]
	v_pk_mul_f32 v[98:99], v[92:93], v[158:159] op_sel_hi:[1,0]
; __device__ __forceinline__ float fast_sigmoid(float x) { return __builtin_amdgcn_rcpf(1.f + __expf(-x)); }
; #define PG8_BAR __builtin_amdgcn_s_barrier()
; template <class Epi>
; __device__ __forceinline__ void gemm_phase(LAS unsigned char* lds, int wave_s, const Gemm g, const StaticOrder S, const Epi E) {
;     ...
;         if (!has_next) break;
; #pragma unroll
;         for (int a = 0; a < 2; ++a)
; #pragma unroll
;             for (int b = 0; b < 2; ++b)
; #pragma unroll
;                 for (int m = 0; m < 4; ++m)
; #pragma unroll
;                     for (int n = 0; n < 2; ++n) acc[a][b][m][n] = (f32x4){0.f, 0.f, 0.f, 0.f};
;         cur = nxt; cA = nA; cB = nB; ++ui;
;         if (wr == 1) PG8_BAR;
;     __device__ __forceinline__ void operator()(const f32x4 (&acc)[2][2][4][2], const Unit& u, int wr, int wc, int fr, int fq) const {
;     ...
;                     const int row = row0 + ai * HALF + m * 16; const float rs = rsv[ai][m] * scale;
;                     f32x4 v0 = acc[ai][bj][m][0] * rs, v1 = acc[ai][bj][m][1] * rs;
;                     if (rp) {
;                         const int pos = row & (SEQ - 1); const float* rb = rope + pos * 32 + 8 * (fq & 1); const bool hi2 = (fq >> 1) != 0;
;                         const f32x4 cs0 = *(const f32x4*)(rb), cs1 = *(const f32x4*)(rb + 4), sn0 = *(const f32x4*)(rb + 16), sn1 = *(const f32x4*)(rb + 20);
; #pragma unroll
;                         for (int e = 0; e < 4; ++e) { const float q0 = __shfl_xor(v0[e], 32), q1 = __shfl_xor(v1[e], 32);
;                             v0[e] = hi2 ? v0[e] * cs0[e] + q0 * sn0[e] : v0[e] * cs0[e] - q0 * sn0[e];
;                             v1[e] = hi2 ? v1[e] * cs1[e] + q1 * sn1[e] : v1[e] * cs1[e] - q1 * sn1[e]; } }
;                     if (sig) {
; #pragma unroll
;                         for (int e = 0; e < 4; ++e) { v0[e] = fast_sigmoid(v0[e]); v1[e] = fast_sigmoid(v1[e]); } }
;                     if (sq) { float s = (v0[0] * v0[0] + v0[1] * v0[1]) + (v0[2] * v0[2] + v0[3] * v0[3]) + (v1[0] * v1[0] + v1[1] * v1[1]) + (v1[2] * v1[2] + v1[3] * v1[3]);
;                         s += __shfl_xor(s, 16); s += __shfl_xor(s, 32); if (fq == 0) sq[(size_t)row * sqp] = s; }
;                     u32x4 w; w.x = pk2(v0[0], v0[1]); w.y = pk2(v0[2], v0[3]); w.z = pk2(v1[0], v1[1]); w.w = pk2(v1[2], v1[3]);
;                     *(u32x4*)(O + (size_t)row * ldc + c0 + 8 * fq) = w;
	v_pk_mul_f32 v[92:93], v[90:91], v[158:159] op_sel_hi:[1,0]
	v_cvt_pk_bf16_f32 v90, v94, v95
	v_lshlrev_b64 v[94:95], 12, v[154:155]
	v_lshl_add_u64 v[94:95], s[10:11], 0, v[94:95]
	v_lshl_add_u64 v[94:95], v[94:95], 0, s[0:1]
	v_cvt_pk_bf16_f32 v91, v96, v97
	v_cvt_pk_bf16_f32 v92, v92, v93
	v_cvt_pk_bf16_f32 v93, v98, v99
	v_lshl_add_u64 v[94:95], v[94:95], 0, v[0:1]
	global_store_dwordx4 v[94:95], v[90:93], off
	v_pk_mul_f32 v[74:75], v[74:75], v[132:133] op_sel_hi:[1,0]
	v_pk_mul_f32 v[54:55], v[54:55], v[130:131] op_sel_hi:[1,0]
	v_pk_mul_f32 v[90:91], v[84:85], v[134:135] op_sel_hi:[1,0]
	v_pk_mul_f32 v[84:85], v[82:83], v[134:135] op_sel_hi:[1,0]
	v_cvt_pk_bf16_f32 v83, v88, v89
	v_add_co_u32_e32 v88, vcc, s4, v126
	v_cvt_pk_bf16_f32 v82, v86, v87
	v_cvt_pk_bf16_f32 v84, v84, v85
	v_cvt_pk_bf16_f32 v85, v90, v91
	v_addc_co_u32_e32 v89, vcc, 0, v127, vcc
	s_mov_b32 s4, 0xa0000
	global_store_dwordx4 v[88:89], v[82:85], off
	v_pk_mul_f32 v[56:57], v[56:57], v[130:131] op_sel_hi:[1,0]
	v_pk_mul_f32 v[24:25], v[24:25], v[134:135] op_sel_hi:[1,0]
	v_pk_mul_f32 v[82:83], v[68:69], v[132:133] op_sel_hi:[1,0]
	v_pk_mul_f32 v[68:69], v[66:67], v[132:133] op_sel_hi:[1,0]
	v_cvt_pk_bf16_f32 v67, v76, v77
	v_add_co_u32_e32 v76, vcc, s4, v126
	v_cvt_pk_bf16_f32 v66, v74, v75
	v_cvt_pk_bf16_f32 v68, v68, v69
	v_cvt_pk_bf16_f32 v69, v82, v83
	v_addc_co_u32_e32 v77, vcc, 0, v127, vcc
	global_store_dwordx4 v[76:77], v[66:69], off
	v_pk_mul_f32 v[22:23], v[22:23], v[134:135] op_sel_hi:[1,0]
	v_lshl_add_u64 v[86:87], v[126:127], 0, s[6:7]
	v_pk_mul_f32 v[66:67], v[52:53], v[130:131] op_sel_hi:[1,0]
	v_pk_mul_f32 v[52:53], v[50:51], v[130:131] op_sel_hi:[1,0]
	v_cvt_pk_bf16_f32 v50, v54, v55
	v_lshlrev_b64 v[54:55], 12, v[156:157]
	v_lshl_add_u64 v[54:55], s[10:11], 0, v[54:55]
	v_lshl_add_u64 v[54:55], v[54:55], 0, s[0:1]
	v_cvt_pk_bf16_f32 v51, v56, v57
	v_cvt_pk_bf16_f32 v52, v52, v53
	v_cvt_pk_bf16_f32 v53, v66, v67
	v_lshl_add_u64 v[54:55], v[54:55], 0, v[0:1]
	global_store_dwordx4 v[54:55], v[50:53], off
	v_pk_mul_f32 v[56:57], v[72:73], v[166:167] op_sel_hi:[1,0]
	v_pk_mul_f32 v[66:67], v[70:71], v[166:167] op_sel_hi:[1,0]
	v_pk_mul_f32 v[52:53], v[80:81], v[166:167] op_sel_hi:[1,0]
	v_pk_mul_f32 v[50:51], v[78:79], v[166:167] op_sel_hi:[1,0]
	s_mov_b64 s[6:7], 0xa0000
	v_cvt_pk_bf16_f32 v50, v50, v51
	v_cvt_pk_bf16_f32 v51, v52, v53
	v_cvt_pk_bf16_f32 v52, v66, v67
	v_cvt_pk_bf16_f32 v53, v56, v57
	global_store_dwordx4 v[126:127], v[50:53], off offset:256
	v_pk_mul_f32 v[56:57], v[60:61], v[164:165] op_sel_hi:[1,0]
	v_pk_mul_f32 v[16:17], v[16:17], v[132:133] op_sel_hi:[1,0]
	v_pk_mul_f32 v[52:53], v[64:65], v[164:165] op_sel_hi:[1,0]
	v_pk_mul_f32 v[50:51], v[62:63], v[164:165] op_sel_hi:[1,0]
	v_pk_mul_f32 v[14:15], v[14:15], v[132:133] op_sel_hi:[1,0]
	v_cvt_pk_bf16_f32 v50, v50, v51
	v_cvt_pk_bf16_f32 v51, v52, v53
	v_cvt_pk_bf16_f32 v52, v58, v59
	v_cvt_pk_bf16_f32 v53, v56, v57
	global_store_dwordx4 v[118:119], v[50:53], off offset:256
	v_lshl_add_u64 v[74:75], v[126:127], 0, s[6:7]
	v_pk_mul_f32 v[8:9], v[8:9], v[130:131] op_sel_hi:[1,0]
	v_pk_mul_f32 v[50:51], v[44:45], v[162:163] op_sel_hi:[1,0]
	v_pk_mul_f32 v[44:45], v[42:43], v[162:163] op_sel_hi:[1,0]
	v_cvt_pk_bf16_f32 v42, v46, v47
	v_cvt_pk_bf16_f32 v43, v48, v49
	v_cvt_pk_bf16_f32 v44, v44, v45
	v_cvt_pk_bf16_f32 v45, v50, v51
	global_store_dwordx4 v[110:111], v[42:45], off offset:256
	v_pk_mul_f32 v[6:7], v[6:7], v[130:131] op_sel_hi:[1,0]
	s_mov_b64 s[0:1], -1
	v_pk_mul_f32 v[42:43], v[36:37], v[160:161] op_sel_hi:[1,0]
	v_pk_mul_f32 v[36:37], v[34:35], v[160:161] op_sel_hi:[1,0]
	v_cvt_pk_bf16_f32 v34, v38, v39
	v_cvt_pk_bf16_f32 v35, v40, v41
	v_cvt_pk_bf16_f32 v36, v36, v37
	v_cvt_pk_bf16_f32 v37, v42, v43
	global_store_dwordx4 v[102:103], v[34:37], off offset:256
	s_and_b64 vcc, exec, s[46:47]
	s_nop 0
	v_pk_mul_f32 v[34:35], v[28:29], v[158:159] op_sel_hi:[1,0]
	v_pk_mul_f32 v[28:29], v[26:27], v[158:159] op_sel_hi:[1,0]
	v_cvt_pk_bf16_f32 v26, v30, v31
	v_cvt_pk_bf16_f32 v27, v32, v33
	v_cvt_pk_bf16_f32 v28, v28, v29
	v_cvt_pk_bf16_f32 v29, v34, v35
	global_store_dwordx4 v[94:95], v[26:29], off offset:256
	s_nop 1
	v_pk_mul_f32 v[26:27], v[20:21], v[134:135] op_sel_hi:[1,0]
	v_pk_mul_f32 v[20:21], v[18:19], v[134:135] op_sel_hi:[1,0]
	v_cvt_pk_bf16_f32 v18, v22, v23
	v_cvt_pk_bf16_f32 v19, v24, v25
	v_cvt_pk_bf16_f32 v20, v20, v21
	v_cvt_pk_bf16_f32 v21, v26, v27
	global_store_dwordx4 v[86:87], v[18:21], off offset:256
	s_nop 1
	v_pk_mul_f32 v[18:19], v[12:13], v[132:133] op_sel_hi:[1,0]
	v_pk_mul_f32 v[12:13], v[10:11], v[132:133] op_sel_hi:[1,0]
	v_cvt_pk_bf16_f32 v10, v14, v15
	v_cvt_pk_bf16_f32 v11, v16, v17
	v_cvt_pk_bf16_f32 v12, v12, v13
	v_cvt_pk_bf16_f32 v13, v18, v19
	global_store_dwordx4 v[74:75], v[10:13], off offset:256
	s_nop 1
	v_pk_mul_f32 v[10:11], v[4:5], v[130:131] op_sel_hi:[1,0]
	v_pk_mul_f32 v[4:5], v[2:3], v[130:131] op_sel_hi:[1,0]
	v_cvt_pk_bf16_f32 v2, v6, v7
	v_cvt_pk_bf16_f32 v3, v8, v9
	v_cvt_pk_bf16_f32 v4, v4, v5
	v_cvt_pk_bf16_f32 v5, v10, v11
	global_store_dwordx4 v[54:55], v[2:5], off offset:256
	s_cbranch_vccnz .LBB0_625
	v_readlane_b32 s0, v254, 22
	v_readlane_b32 s1, v254, 23
	s_andn2_b64 vcc, exec, s[0:1]
	s_cbranch_vccnz .LBB0_624
	s_barrier
	s_branch .LBB0_624

; __device__ __forceinline__ int fresh_tid(int wave_s) { return wave_s * 64 + lane_id(); }
;     ...
;     const float inv = 1.f / lt;
; #pragma unroll
;     for (int db = 0; db < NDB; ++db)
; #pragma unroll
;         for (int r = 0; r < 16; ++r) o[db][r] *= inv;
; __global__ void __launch_bounds__(512) fwd_megakernel(Args a) {
;     ...
;                     float ss = 0.f;
;                     const int t3 = fresh_tid(wave_s), l3 = t3 & 63;
;                     const f32x4* scr = (const f32x4*)(scr_blk + (size_t)t3 * 64);
; #pragma unroll
;                     for (int db = 0; db < 4; ++db)
;                     {
; #pragma unroll
;                       for (int j = 0; j < 4; ++j) { const f32x4 t4 = scr[db * 4 + j];
; #pragma unroll
;                             for (int e = 0; e < 4; ++e) { const float v = t4[e] - lam * o[db][4 * j + e]; o[db][4 * j + e] = v; ss += v * v; } }
;                       __builtin_amdgcn_sched_barrier(0); }
;                     ss += __shfl_xor(ss, 32);
;                     const float rs = rsqrtf(ss * (1.f / 128.f) + EPS) * lut[520];
;                     const int hl = l3 >> 5;
; #pragma unroll
;                     for (int db = 0; db < 4; ++db)
;                     {
; #pragma unroll
;                       for (int rg = 0; rg < 4; ++rg) { const f32x4 gn = *(const f32x4*)(subln + 32 * db + 8 * rg + 4 * hl);
; #pragma unroll
;                             for (int e = 0; e < 4; ++e) o[db][4 * rg + e] *= rs * gn[e]; }
;                       __builtin_amdgcn_sched_barrier(0); }
;                     bf16_t* row = ACT + (tok0 + q0 + 32 * wave + (l3 & 31)) * INP;
;                     attn_store<128, true>(o, row + C_GC + 128 * hh, row + C_GA + 128 * hh, hl);
.LBB0_892:
	v_div_scale_f32 v0, s[0:1], v144, v144, 1.0
	v_rcp_f32_e32 v2, v0
	v_readlane_b32 s0, v252, 32
	v_readlane_b32 s1, v252, 33
	v_fma_f32 v3, -v0, v2, 1.0
	v_fmac_f32_e32 v2, v3, v2
	v_div_scale_f32 v3, vcc, 1.0, v144, 1.0
	v_mul_f32_e32 v4, v3, v2
	v_fma_f32 v5, -v0, v4, v3
	v_fmac_f32_e32 v4, v5, v2
	v_fma_f32 v0, -v0, v4, v3
	v_div_fmas_f32 v0, v0, v2, v4
	v_div_fixup_f32 v206, v0, v144, 1.0
	v_mbcnt_lo_u32_b32 v0, -1, 0
	v_mbcnt_hi_u32_b32 v0, -1, v0
	s_nop 0
	v_add_u32_e32 v2, s92, v0
	v_ashrrev_i32_e32 v3, 31, v2
	v_lshlrev_b64 v[2:3], 8, v[2:3]
	v_lshl_add_u64 v[6:7], s[0:1], 0, v[2:3]
	global_load_dwordx4 v[172:175], v[6:7], off offset:48
	global_load_dwordx4 v[176:179], v[6:7], off offset:32
	global_load_dwordx4 v[180:183], v[6:7], off offset:16
	global_load_dwordx4 v[184:187], v[6:7], off
	global_load_dwordx4 v[152:155], v[6:7], off offset:112
	global_load_dwordx4 v[160:163], v[6:7], off offset:96
	global_load_dwordx4 v[164:167], v[6:7], off offset:80
	global_load_dwordx4 v[168:171], v[6:7], off offset:64
	global_load_dwordx4 v[136:139], v[6:7], off offset:176
	global_load_dwordx4 v[144:147], v[6:7], off offset:160
	global_load_dwordx4 v[148:151], v[6:7], off offset:144
	global_load_dwordx4 v[156:159], v[6:7], off offset:128
	global_load_dwordx4 v[2:5], v[6:7], off offset:240
	global_load_dwordx4 v[128:131], v[6:7], off offset:224
	global_load_dwordx4 v[132:135], v[6:7], off offset:208
	global_load_dwordx4 v[140:143], v[6:7], off offset:192
	v_pk_mul_f32 v[6:7], v[206:207], v[28:29] op_sel_hi:[0,1]
	v_pk_mul_f32 v[8:9], v[206:207], v[30:31] op_sel_hi:[0,1]
	s_waitcnt vmcnt(3)
	v_pk_fma_f32 v[188:189], s[50:51], v[6:7], v[2:3] neg_lo:[1,0,0] neg_hi:[1,0,0]
	v_pk_fma_f32 v[14:15], s[50:51], v[8:9], v[4:5] neg_lo:[1,0,0] neg_hi:[1,0,0]
	v_pk_mul_f32 v[194:195], v[188:189], v[188:189]
	v_pk_mul_f32 v[192:193], v[14:15], v[14:15]
	v_and_b32_e32 v3, 64, v241
	v_xor_b32_e32 v2, 32, v241
	v_add_u32_e32 v3, 64, v3
	v_cmp_lt_i32_e32 vcc, v2, v3
	ds_read_b32 v245, v1 offset:63520
	s_nop 0
	v_cndmask_b32_e32 v2, v241, v2, vcc
	v_lshlrev_b32_e32 v246, 2, v2
	v_lshrrev_b32_e32 v2, 3, v0
	v_and_b32_e32 v196, 4, v2
	v_lshlrev_b32_e32 v2, 2, v196
	global_load_dwordx4 v[96:99], v2, s[54:55]
	global_load_dwordx4 v[88:91], v2, s[54:55] offset:32
	global_load_dwordx4 v[80:83], v2, s[54:55] offset:64
	global_load_dwordx4 v[10:13], v2, s[54:55] offset:96
	global_load_dwordx4 v[124:127], v2, s[54:55] offset:128
	global_load_dwordx4 v[120:123], v2, s[54:55] offset:160
	global_load_dwordx4 v[116:119], v2, s[54:55] offset:192
	global_load_dwordx4 v[112:115], v2, s[54:55] offset:224
	global_load_dwordx4 v[108:111], v2, s[54:55] offset:256
	global_load_dwordx4 v[104:107], v2, s[54:55] offset:288
	global_load_dwordx4 v[100:103], v2, s[54:55] offset:320
	global_load_dwordx4 v[92:95], v2, s[54:55] offset:352
	global_load_dwordx4 v[84:87], v2, s[54:55] offset:384
	global_load_dwordx4 v[28:31], v2, s[54:55] offset:416
	global_load_dwordx4 v[6:9], v2, s[54:55] offset:448
	s_nop 0
	global_load_dwordx4 v[2:5], v2, s[54:55] offset:480
	s_add_u32 s0, s12, s43
	s_addc_u32 s1, s13, 0
	v_and_or_b32 v0, v0, 31, s0
	v_mov_b64_e32 v[190:191], s[96:97]
	s_movk_i32 s0, 0x4200
	s_mul_i32 s4, s1, 0x4200
	v_mad_u64_u32 v[190:191], s[0:1], v0, s0, v[190:191]
	v_add_u32_e32 v191, s4, v191
	s_lshl_b32 s40, s25, 1
	v_lshl_add_u64 v[190:191], v[190:191], 0, s[40:41]
	v_lshlrev_b32_e32 v0, 1, v196
	v_lshl_add_u64 v[208:209], v[190:191], 0, v[0:1]
	s_mov_b64 s[0:1], 0x3a00
	v_lshl_add_u64 v[190:191], v[208:209], 0, s[0:1]
	s_movk_i32 s0, 0x3000
	v_add_co_u32_e32 v212, vcc, s0, v208
	s_mov_b64 s[0:1], 0x2a00
	v_pk_mul_f32 v[218:219], v[206:207], v[32:33] op_sel_hi:[0,1]
	v_lshl_add_u64 v[32:33], v[208:209], 0, s[0:1]
	v_addc_co_u32_e32 v213, vcc, 0, v209, vcc
	v_pk_mul_f32 v[236:237], v[206:207], v[74:75] op_sel_hi:[0,1]
	v_pk_mul_f32 v[196:197], v[206:207], v[72:73] op_sel_hi:[0,1]
	v_pk_mul_f32 v[72:73], v[206:207], v[78:79] op_sel_hi:[0,1]
	v_pk_mul_f32 v[78:79], v[206:207], v[76:77] op_sel_hi:[0,1]
	v_pk_mul_f32 v[74:75], v[206:207], v[56:57] op_sel_hi:[0,1]
	v_pk_mul_f32 v[76:77], v[206:207], v[62:63] op_sel_hi:[0,1]
	global_load_dwordx2 v[56:57], v[190:191], off offset:16
	global_load_dwordx2 v[62:63], v[32:33], off offset:16
	global_load_dwordx2 v[198:199], v[212:213], off offset:2560
	global_load_dwordx2 v[200:201], v[190:191], off offset:32
	s_movk_i32 s0, 0x2000
	v_pk_mul_f32 v[216:217], v[206:207], v[64:65] op_sel_hi:[0,1]
	v_pk_mul_f32 v[64:65], v[206:207], v[48:49] op_sel_hi:[0,1]
	v_add_co_u32_e32 v48, vcc, s0, v208
	v_pk_mul_f32 v[220:221], v[206:207], v[40:41] op_sel_hi:[0,1]
	s_nop 0
	v_addc_co_u32_e32 v49, vcc, 0, v209, vcc
	global_load_dwordx2 v[202:203], v[48:49], off offset:2560
	global_load_dwordx2 v[208:209], v[32:33], off offset:32
	global_load_dwordx2 v[40:41], v[190:191], off offset:48
	v_pk_mul_f32 v[210:211], v[206:207], v[66:67] op_sel_hi:[0,1]
	v_pk_mul_f32 v[234:235], v[206:207], v[68:69] op_sel_hi:[0,1]
	v_pk_mul_f32 v[222:223], v[206:207], v[26:27] op_sel_hi:[0,1]
	v_pk_fma_f32 v[26:27], s[50:51], v[216:217], v[184:185] neg_lo:[1,0,0] neg_hi:[1,0,0]
	v_pk_mul_f32 v[70:71], v[206:207], v[70:71] op_sel_hi:[0,1]
	v_pk_mul_f32 v[50:51], v[206:207], v[50:51] op_sel_hi:[0,1]
	v_pk_mul_f32 v[54:55], v[206:207], v[54:55] op_sel_hi:[0,1]
	v_pk_mul_f32 v[66:67], v[206:207], v[52:53] op_sel_hi:[0,1]
	v_pk_mul_f32 v[68:69], v[206:207], v[58:59] op_sel_hi:[0,1]
	v_pk_mul_f32 v[214:215], v[206:207], v[60:61] op_sel_hi:[0,1]
	v_pk_mul_f32 v[34:35], v[206:207], v[34:35] op_sel_hi:[0,1]
	v_pk_mul_f32 v[38:39], v[206:207], v[38:39] op_sel_hi:[0,1]
;     ...
;     const float inv = 1.f / lt;
; #pragma unroll
;     for (int db = 0; db < NDB; ++db)
; #pragma unroll
;         for (int r = 0; r < 16; ++r) o[db][r] *= inv;
; __global__ void __launch_bounds__(512) fwd_megakernel(Args a) {
;     ...
;                       for (int j = 0; j < 4; ++j) { const f32x4 t4 = scr[db * 4 + j];
; #pragma unroll
;                             for (int e = 0; e < 4; ++e) { const float v = t4[e] - lam * o[db][4 * j + e]; o[db][4 * j + e] = v; ss += v * v; } }
;                       __builtin_amdgcn_sched_barrier(0); }
;                     ss += __shfl_xor(ss, 32);
	v_pk_mul_f32 v[36:37], v[206:207], v[36:37] op_sel_hi:[0,1]
	v_pk_mul_f32 v[42:43], v[206:207], v[42:43] op_sel_hi:[0,1]
	v_pk_mul_f32 v[46:47], v[206:207], v[46:47] op_sel_hi:[0,1]
	v_pk_mul_f32 v[228:229], v[206:207], v[44:45] op_sel_hi:[0,1]
	v_pk_mul_f32 v[230:231], v[206:207], v[18:19] op_sel_hi:[0,1]
	v_pk_mul_f32 v[232:233], v[206:207], v[16:17] op_sel_hi:[0,1]
	v_pk_mul_f32 v[224:225], v[206:207], v[22:23] op_sel_hi:[0,1]
	v_pk_mul_f32 v[226:227], v[206:207], v[20:21] op_sel_hi:[0,1]
	v_pk_mul_f32 v[206:207], v[206:207], v[24:25] op_sel_hi:[0,1]
	v_pk_fma_f32 v[22:23], s[50:51], v[210:211], v[186:187] neg_lo:[1,0,0] neg_hi:[1,0,0]
	v_pk_fma_f32 v[24:25], s[50:51], v[234:235], v[180:181] neg_lo:[1,0,0] neg_hi:[1,0,0]
	v_pk_mul_f32 v[180:181], v[26:27], v[26:27]
	v_pk_fma_f32 v[16:17], s[50:51], v[236:237], v[178:179] neg_lo:[1,0,0] neg_hi:[1,0,0]
	v_pk_mul_f32 v[178:179], v[22:23], v[22:23]
	v_add_f32_e32 v0, v180, v181
	v_add_f32_e32 v0, v0, v178
	v_pk_mul_f32 v[184:185], v[24:25], v[24:25]
	v_add_f32_e32 v0, v0, v179
	v_pk_fma_f32 v[18:19], s[50:51], v[70:71], v[182:183] neg_lo:[1,0,0] neg_hi:[1,0,0]
	v_add_f32_e32 v0, v0, v184
	v_pk_mul_f32 v[182:183], v[18:19], v[18:19]
	v_add_f32_e32 v0, v0, v185
	v_pk_fma_f32 v[20:21], s[50:51], v[196:197], v[176:177] neg_lo:[1,0,0] neg_hi:[1,0,0]
	v_add_f32_e32 v0, v0, v182
	v_pk_fma_f32 v[44:45], s[50:51], v[72:73], v[174:175] neg_lo:[1,0,0] neg_hi:[1,0,0]
	v_pk_fma_f32 v[176:177], s[50:51], v[78:79], v[172:173] neg_lo:[1,0,0] neg_hi:[1,0,0]
	v_add_f32_e32 v0, v0, v183
	v_pk_mul_f32 v[186:187], v[16:17], v[16:17]
	v_pk_fma_f32 v[74:75], s[50:51], v[74:75], v[160:161] neg_lo:[1,0,0] neg_hi:[1,0,0]
	v_pk_mul_f32 v[160:161], v[176:177], v[176:177]
	v_pk_fma_f32 v[66:67], s[50:51], v[66:67], v[164:165] neg_lo:[1,0,0] neg_hi:[1,0,0]
	v_pk_mul_f32 v[164:165], v[44:45], v[44:45]
	v_pk_fma_f32 v[64:65], s[50:51], v[64:65], v[168:169] neg_lo:[1,0,0] neg_hi:[1,0,0]
	v_pk_fma_f32 v[76:77], s[50:51], v[76:77], v[154:155] neg_lo:[1,0,0] neg_hi:[1,0,0]
	v_pk_mul_f32 v[154:155], v[64:65], v[64:65]
	v_pk_fma_f32 v[50:51], s[50:51], v[50:51], v[170:171] neg_lo:[1,0,0] neg_hi:[1,0,0]
	v_pk_fma_f32 v[68:69], s[50:51], v[68:69], v[162:163] neg_lo:[1,0,0] neg_hi:[1,0,0]
	v_pk_mul_f32 v[162:163], v[50:51], v[50:51]
	v_pk_fma_f32 v[34:35], s[50:51], v[34:35], v[158:159] neg_lo:[1,0,0] neg_hi:[1,0,0]
	v_pk_mul_f32 v[158:159], v[66:67], v[66:67]
	v_pk_fma_f32 v[54:55], s[50:51], v[54:55], v[166:167] neg_lo:[1,0,0] neg_hi:[1,0,0]
	v_pk_fma_f32 v[150:151], s[50:51], v[38:39], v[150:151] neg_lo:[1,0,0] neg_hi:[1,0,0]
	v_pk_mul_f32 v[38:39], v[74:75], v[74:75]
	v_pk_fma_f32 v[152:153], s[50:51], v[214:215], v[152:153] neg_lo:[1,0,0] neg_hi:[1,0,0]
	global_load_dwordx2 v[196:197], v[32:33], off offset:48
	v_pk_fma_f32 v[146:147], s[50:51], v[42:43], v[146:147] neg_lo:[1,0,0] neg_hi:[1,0,0]
	v_pk_mul_f32 v[42:43], v[152:153], v[152:153]
	v_pk_fma_f32 v[36:37], s[50:51], v[36:37], v[148:149] neg_lo:[1,0,0] neg_hi:[1,0,0]
	v_pk_mul_f32 v[148:149], v[76:77], v[76:77]
	v_pk_fma_f32 v[156:157], s[50:51], v[218:219], v[156:157] neg_lo:[1,0,0] neg_hi:[1,0,0]
	v_pk_fma_f32 v[138:139], s[50:51], v[46:47], v[138:139] neg_lo:[1,0,0] neg_hi:[1,0,0]
	v_pk_mul_f32 v[46:47], v[156:157], v[156:157]
	v_pk_mul_f32 v[212:213], v[36:37], v[36:37]
	v_pk_mul_f32 v[210:211], v[150:151], v[150:151]
	v_pk_fma_f32 v[144:145], s[50:51], v[220:221], v[144:145] neg_lo:[1,0,0] neg_hi:[1,0,0]
	v_pk_mul_f32 v[214:215], v[146:147], v[146:147]
	s_waitcnt vmcnt(7)
	v_lshlrev_b32_e32 v52, 16, v57
	s_waitcnt vmcnt(5)
	v_lshlrev_b32_e32 v72, 16, v199
	v_and_b32_e32 v73, 0xffff0000, v199
	v_lshlrev_b32_e32 v78, 16, v198
	v_and_b32_e32 v79, 0xffff0000, v198
	v_pk_mul_f32 v[198:199], v[20:21], v[20:21]
	v_and_b32_e32 v53, 0xffff0000, v57
	v_add_f32_e32 v0, v0, v198
	v_add_f32_e32 v0, v0, v199
	v_add_f32_e32 v0, v0, v186
	v_add_f32_e32 v0, v0, v187
	v_add_f32_e32 v0, v0, v160
	v_add_f32_e32 v0, v0, v161
	v_add_f32_e32 v0, v0, v164
	v_add_f32_e32 v0, v0, v165
	v_add_f32_e32 v0, v0, v154
	v_add_f32_e32 v0, v0, v155
	v_add_f32_e32 v0, v0, v162
	v_add_f32_e32 v0, v0, v163
	v_add_f32_e32 v0, v0, v158
	v_lshlrev_b32_e32 v58, 16, v56
	v_and_b32_e32 v59, 0xffff0000, v56
	s_waitcnt vmcnt(4)
	v_lshlrev_b32_e32 v56, 16, v201
	v_and_b32_e32 v57, 0xffff0000, v201
	v_lshlrev_b32_e32 v70, 16, v200
	v_and_b32_e32 v71, 0xffff0000, v200
	v_pk_mul_f32 v[200:201], v[54:55], v[54:55]
	v_add_f32_e32 v0, v0, v159
	v_add_f32_e32 v0, v0, v200
	v_add_f32_e32 v0, v0, v201
	v_add_f32_e32 v0, v0, v38
	s_waitcnt vmcnt(3)
	v_lshlrev_b32_e32 v172, 16, v202
	v_and_b32_e32 v173, 0xffff0000, v202
	v_lshlrev_b32_e32 v174, 16, v203
	v_and_b32_e32 v175, 0xffff0000, v203
	v_pk_mul_f32 v[202:203], v[68:69], v[68:69]
	v_add_f32_e32 v0, v0, v39
	v_add_f32_e32 v0, v0, v202
	v_add_f32_e32 v0, v0, v203
	v_add_f32_e32 v0, v0, v42
	v_add_f32_e32 v0, v0, v43
	v_add_f32_e32 v0, v0, v148
	v_add_f32_e32 v0, v0, v149
	v_add_f32_e32 v0, v0, v46
	s_waitcnt vmcnt(2)
; __global__ void __launch_bounds__(512) fwd_megakernel(Args a) {
;     ...
;                       for (int j = 0; j < 4; ++j) { const f32x4 t4 = scr[db * 4 + j];
; #pragma unroll
;                             for (int e = 0; e < 4; ++e) { const float v = t4[e] - lam * o[db][4 * j + e]; o[db][4 * j + e] = v; ss += v * v; } }
;                       __builtin_amdgcn_sched_barrier(0); }
;                     ss += __shfl_xor(ss, 32);
;                     const float rs = rsqrtf(ss * (1.f / 128.f) + EPS) * lut[520];
;                     const int hl = l3 >> 5;
; #pragma unroll
;                     for (int db = 0; db < 4; ++db)
;                     {
; #pragma unroll
;                       for (int rg = 0; rg < 4; ++rg) { const f32x4 gn = *(const f32x4*)(subln + 32 * db + 8 * rg + 4 * hl);
; #pragma unroll
;                             for (int e = 0; e < 4; ++e) o[db][4 * rg + e] *= rs * gn[e]; }
	v_lshlrev_b32_e32 v168, 16, v208
	v_and_b32_e32 v169, 0xffff0000, v208
	v_lshlrev_b32_e32 v170, 16, v209
	v_and_b32_e32 v171, 0xffff0000, v209
	v_pk_mul_f32 v[208:209], v[34:35], v[34:35]
	v_add_f32_e32 v0, v0, v47
	v_add_f32_e32 v0, v0, v208
	v_add_f32_e32 v0, v0, v209
	v_add_f32_e32 v0, v0, v212
	v_add_f32_e32 v0, v0, v213
	v_add_f32_e32 v0, v0, v210
	v_pk_mul_f32 v[216:217], v[144:145], v[144:145]
	v_add_f32_e32 v0, v0, v211
	v_add_f32_e32 v0, v0, v216
	v_add_f32_e32 v0, v0, v217
	v_pk_fma_f32 v[136:137], s[50:51], v[228:229], v[136:137] neg_lo:[1,0,0] neg_hi:[1,0,0]
	v_add_f32_e32 v0, v0, v214
	v_pk_fma_f32 v[128:129], s[50:51], v[206:207], v[128:129] neg_lo:[1,0,0] neg_hi:[1,0,0]
	v_pk_mul_f32 v[206:207], v[136:137], v[136:137]
	v_add_f32_e32 v0, v0, v215
	v_add_f32_e32 v0, v0, v206
	v_pk_mul_f32 v[218:219], v[138:139], v[138:139]
	v_add_f32_e32 v0, v0, v207
	v_pk_fma_f32 v[140:141], s[50:51], v[232:233], v[140:141] neg_lo:[1,0,0] neg_hi:[1,0,0]
	v_add_f32_e32 v0, v0, v218
	v_pk_mul_f32 v[178:179], v[140:141], v[140:141]
	v_add_f32_e32 v0, v0, v219
	v_pk_fma_f32 v[142:143], s[50:51], v[230:231], v[142:143] neg_lo:[1,0,0] neg_hi:[1,0,0]
	v_add_f32_e32 v0, v0, v178
	v_pk_mul_f32 v[220:221], v[142:143], v[142:143]
	v_add_f32_e32 v0, v0, v179
	v_pk_fma_f32 v[132:133], s[50:51], v[226:227], v[132:133] neg_lo:[1,0,0] neg_hi:[1,0,0]
	v_add_f32_e32 v0, v0, v220
	v_pk_mul_f32 v[182:183], v[132:133], v[132:133]
	v_add_f32_e32 v0, v0, v221
	v_pk_fma_f32 v[134:135], s[50:51], v[224:225], v[134:135] neg_lo:[1,0,0] neg_hi:[1,0,0]
	v_add_f32_e32 v0, v0, v182
	v_pk_mul_f32 v[180:181], v[134:135], v[134:135]
	v_add_f32_e32 v0, v0, v183
	v_add_f32_e32 v0, v0, v180
	v_pk_mul_f32 v[186:187], v[128:129], v[128:129]
	v_add_f32_e32 v0, v0, v181
	v_pk_fma_f32 v[130:131], s[50:51], v[222:223], v[130:131] neg_lo:[1,0,0] neg_hi:[1,0,0]
	v_add_f32_e32 v0, v0, v186
	v_pk_mul_f32 v[184:185], v[130:131], v[130:131]
	v_add_f32_e32 v0, v0, v187
	v_add_f32_e32 v0, v0, v184
	v_add_f32_e32 v0, v0, v185
	v_add_f32_e32 v0, v0, v194
	v_add_f32_e32 v0, v0, v195
	v_add_f32_e32 v0, v0, v192
	v_add_f32_e32 v0, v0, v193
	ds_bpermute_b32 v38, v246, v0
	s_waitcnt vmcnt(1)
	v_lshlrev_b32_e32 v166, 16, v41
	v_and_b32_e32 v167, 0xffff0000, v41
	v_lshlrev_b32_e32 v148, 16, v40
	v_and_b32_e32 v149, 0xffff0000, v40
	s_waitcnt lgkmcnt(0)
	v_add_f32_e32 v0, v0, v38
	v_fmamk_f32 v0, v0, 0x3c000000, v239
	v_lshlrev_b32_e32 v60, 16, v62
	v_and_b32_e32 v61, 0xffff0000, v62
	v_rsq_f32_e32 v0, v0
	s_nop 0
	v_lshlrev_b32_e32 v62, 16, v63
	v_and_b32_e32 v63, 0xffff0000, v63
	s_waitcnt vmcnt(0)
	v_lshlrev_b32_e32 v154, 16, v196
	v_mul_f32_e32 v0, v245, v0
	v_pk_mul_f32 v[10:11], v[0:1], v[10:11] op_sel_hi:[0,1]
	v_pk_mul_f32 v[160:161], v[10:11], v[176:177]
	v_pk_mul_f32 v[10:11], v[0:1], v[12:13] op_sel_hi:[0,1]
	v_pk_mul_f32 v[162:163], v[10:11], v[44:45]
	v_pk_mul_f32 v[10:11], v[0:1], v[124:125] op_sel_hi:[0,1]
	v_pk_mul_f32 v[64:65], v[10:11], v[64:65]
	v_pk_mul_f32 v[10:11], v[0:1], v[126:127] op_sel_hi:[0,1]
	v_pk_mul_f32 v[50:51], v[10:11], v[50:51]
	v_pk_mul_f32 v[10:11], v[0:1], v[120:121] op_sel_hi:[0,1]
	v_pk_mul_f32 v[66:67], v[10:11], v[66:67]
	v_pk_mul_f32 v[10:11], v[0:1], v[122:123] op_sel_hi:[0,1]
	v_pk_mul_f32 v[54:55], v[10:11], v[54:55]
	v_pk_mul_f32 v[10:11], v[0:1], v[116:117] op_sel_hi:[0,1]
	v_pk_mul_f32 v[74:75], v[10:11], v[74:75]
	v_pk_mul_f32 v[10:11], v[0:1], v[118:119] op_sel_hi:[0,1]
	v_pk_mul_f32 v[68:69], v[10:11], v[68:69]
	v_pk_mul_f32 v[10:11], v[0:1], v[112:113] op_sel_hi:[0,1]
	v_pk_mul_f32 v[46:47], v[10:11], v[152:153]
	v_pk_mul_f32 v[10:11], v[0:1], v[114:115] op_sel_hi:[0,1]
	v_pk_mul_f32 v[44:45], v[10:11], v[76:77]
	v_pk_mul_f32 v[10:11], v[0:1], v[108:109] op_sel_hi:[0,1]
	v_pk_mul_f32 v[42:43], v[10:11], v[156:157]
	v_pk_mul_f32 v[10:11], v[0:1], v[110:111] op_sel_hi:[0,1]
	v_pk_mul_f32 v[38:39], v[0:1], v[96:97] op_sel_hi:[0,1]
	v_pk_mul_f32 v[40:41], v[10:11], v[34:35]
	v_pk_mul_f32 v[10:11], v[0:1], v[104:105] op_sel_hi:[0,1]
	v_pk_mul_f32 v[96:97], v[38:39], v[26:27]
	v_pk_mul_f32 v[38:39], v[10:11], v[36:37]
	v_pk_mul_f32 v[10:11], v[0:1], v[106:107] op_sel_hi:[0,1]
	v_pk_mul_f32 v[36:37], v[10:11], v[150:151]
	v_pk_mul_f32 v[10:11], v[0:1], v[100:101] op_sel_hi:[0,1]
	v_pk_mul_f32 v[26:27], v[0:1], v[98:99] op_sel_hi:[0,1]
	v_pk_mul_f32 v[34:35], v[10:11], v[144:145]
	v_pk_mul_f32 v[10:11], v[0:1], v[102:103] op_sel_hi:[0,1]
	v_pk_mul_f32 v[98:99], v[26:27], v[22:23]
	v_pk_mul_f32 v[22:23], v[0:1], v[88:89] op_sel_hi:[0,1]
	v_pk_mul_f32 v[26:27], v[10:11], v[146:147]
	v_pk_mul_f32 v[10:11], v[0:1], v[92:93] op_sel_hi:[0,1]
	v_pk_mul_f32 v[88:89], v[22:23], v[24:25]
	v_pk_mul_f32 v[22:23], v[0:1], v[90:91] op_sel_hi:[0,1]
	v_pk_mul_f32 v[24:25], v[10:11], v[136:137]
	v_pk_mul_f32 v[10:11], v[0:1], v[94:95] op_sel_hi:[0,1]
	v_pk_mul_f32 v[90:91], v[22:23], v[18:19]
	v_pk_mul_f32 v[18:19], v[0:1], v[80:81] op_sel_hi:[0,1]
	v_pk_mul_f32 v[22:23], v[10:11], v[138:139]
	v_pk_mul_f32 v[10:11], v[0:1], v[84:85] op_sel_hi:[0,1]
	v_pk_mul_f32 v[80:81], v[18:19], v[20:21]
	v_pk_mul_f32 v[18:19], v[0:1], v[82:83] op_sel_hi:[0,1]
	v_pk_mul_f32 v[20:21], v[10:11], v[140:141]
	v_pk_mul_f32 v[10:11], v[0:1], v[86:87] op_sel_hi:[0,1]
	v_pk_mul_f32 v[82:83], v[18:19], v[16:17]
	v_pk_mul_f32 v[18:19], v[10:11], v[142:143]
	v_pk_mul_f32 v[10:11], v[0:1], v[28:29] op_sel_hi:[0,1]
	v_pk_mul_f32 v[16:17], v[10:11], v[132:133]
	v_pk_mul_f32 v[10:11], v[0:1], v[30:31] op_sel_hi:[0,1]
	v_pk_mul_f32 v[6:7], v[0:1], v[6:7] op_sel_hi:[0,1]
	v_pk_mul_f32 v[12:13], v[10:11], v[134:135]
	v_pk_mul_f32 v[10:11], v[6:7], v[128:129]
	v_pk_mul_f32 v[6:7], v[0:1], v[8:9] op_sel_hi:[0,1]
; __device__ __forceinline__ unsigned pk2(float lo, float hi) { f32x2_t v = {lo, hi}; bf16x2_t b = __builtin_convertvector(v, bf16x2_t); return __builtin_bit_cast(unsigned, b); }
; __device__ __forceinline__ float bflo(unsigned u) { return __uint_as_float(u << 16); }
; __device__ __forceinline__ float bfhi(unsigned u) { return __uint_as_float(u & 0xffff0000u); }
; template <int DV, bool ACCUM>
; __device__ __forceinline__ void attn_store(const f32x16 (&o)[DV / 32], const bf16_t* gate_row, bf16_t* merged_row, int h) {
; #pragma unroll
;     for (int db = 0; db < DV / 32; ++db)
; #pragma unroll
;         for (int rg = 0; rg < 4; ++rg) {
;             const int d = 32 * db + 8 * rg + 4 * h;
;             const u32x2 g = *(const u32x2*)(gate_row + d);
;             float v0 = o[db][4 * rg + 0] * bflo(g.x), v1 = o[db][4 * rg + 1] * bfhi(g.x), v2 = o[db][4 * rg + 2] * bflo(g.y), v3 = o[db][4 * rg + 3] * bfhi(g.y);
;             if (ACCUM) { const u32x2 mm = *(const u32x2*)(merged_row + d); v0 += bflo(mm.x); v1 += bfhi(mm.x); v2 += bflo(mm.y); v3 += bfhi(mm.y); }
;             u32x2 w; w.x = pk2(v0, v1); w.y = pk2(v2, v3);
;             *(u32x2*)(merged_row + d) = w;
;             if (rg == 3) __builtin_amdgcn_sched_barrier(0);
;         }
	v_pk_fma_f32 v[8:9], v[96:97], v[78:79], v[172:173]
	v_pk_fma_f32 v[28:29], v[98:99], v[72:73], v[174:175]
	v_cvt_pk_bf16_f32 v8, v8, v9
	v_cvt_pk_bf16_f32 v9, v28, v29
	global_store_dwordx2 v[48:49], v[8:9], off offset:2560
	v_pk_fma_f32 v[8:9], v[88:89], v[58:59], v[60:61]
	v_pk_fma_f32 v[28:29], v[90:91], v[52:53], v[62:63]
	v_cvt_pk_bf16_f32 v8, v8, v9
	v_cvt_pk_bf16_f32 v9, v28, v29
	global_store_dwordx2 v[32:33], v[8:9], off offset:16
	v_pk_fma_f32 v[8:9], v[80:81], v[70:71], v[168:169]
	v_pk_fma_f32 v[28:29], v[82:83], v[56:57], v[170:171]
	v_and_b32_e32 v155, 0xffff0000, v196
	v_lshlrev_b32_e32 v158, 16, v197
	v_and_b32_e32 v159, 0xffff0000, v197
	v_cvt_pk_bf16_f32 v8, v8, v9
	v_cvt_pk_bf16_f32 v9, v28, v29
	global_store_dwordx2 v[32:33], v[8:9], off offset:32
	v_pk_fma_f32 v[8:9], v[160:161], v[148:149], v[154:155]
	v_pk_fma_f32 v[28:29], v[162:163], v[166:167], v[158:159]
	v_cvt_pk_bf16_f32 v8, v8, v9
	v_cvt_pk_bf16_f32 v9, v28, v29
	v_pk_mul_f32 v[6:7], v[6:7], v[130:131]
	global_store_dwordx2 v[32:33], v[8:9], off offset:48
	global_load_dwordx2 v[100:101], v[190:191], off offset:64
	global_load_dwordx2 v[102:103], v[32:33], off offset:64
	global_load_dwordx2 v[104:105], v[190:191], off offset:80
	global_load_dwordx2 v[106:107], v[32:33], off offset:80
	global_load_dwordx2 v[108:109], v[190:191], off offset:96
	global_load_dwordx2 v[110:111], v[32:33], off offset:96
	global_load_dwordx2 v[112:113], v[190:191], off offset:112
	global_load_dwordx2 v[114:115], v[32:33], off offset:112
	global_load_dwordx2 v[116:117], v[190:191], off offset:128
	global_load_dwordx2 v[118:119], v[32:33], off offset:128
	global_load_dwordx2 v[120:121], v[190:191], off offset:144
	global_load_dwordx2 v[122:123], v[32:33], off offset:144
	global_load_dwordx2 v[124:125], v[190:191], off offset:160
	global_load_dwordx2 v[126:127], v[32:33], off offset:160
	global_load_dwordx2 v[128:129], v[190:191], off offset:176
	global_load_dwordx2 v[130:131], v[32:33], off offset:176
	global_load_dwordx2 v[132:133], v[190:191], off offset:192
	global_load_dwordx2 v[134:135], v[32:33], off offset:192
	global_load_dwordx2 v[136:137], v[190:191], off offset:208
	global_load_dwordx2 v[138:139], v[32:33], off offset:208
	global_load_dwordx2 v[140:141], v[190:191], off offset:224
	global_load_dwordx2 v[142:143], v[32:33], off offset:224
	global_load_dwordx2 v[144:145], v[190:191], off offset:240
	global_load_dwordx2 v[146:147], v[32:33], off offset:240
	s_waitcnt vmcnt(22)
	s_nop 0
	v_mov_b32_e32 v8, v100
	v_mov_b32_e32 v9, v101
	s_nop 0
	v_mov_b32_e32 v30, v102
	v_mov_b32_e32 v31, v103
	v_lshlrev_b32_e32 v28, 16, v8
	v_and_b32_e32 v29, 0xffff0000, v8
	v_lshlrev_b32_e32 v8, 16, v9
	v_and_b32_e32 v9, 0xffff0000, v9
	v_lshlrev_b32_e32 v48, 16, v30
	v_and_b32_e32 v49, 0xffff0000, v30
	v_lshlrev_b32_e32 v30, 16, v31
	v_and_b32_e32 v31, 0xffff0000, v31
	v_pk_fma_f32 v[28:29], v[64:65], v[28:29], v[48:49]
	v_pk_fma_f32 v[8:9], v[50:51], v[8:9], v[30:31]
	v_cvt_pk_bf16_f32 v28, v28, v29
	v_cvt_pk_bf16_f32 v29, v8, v9
	s_waitcnt vmcnt(20)
	s_nop 0
	v_mov_b32_e32 v8, v104
	v_mov_b32_e32 v9, v105
	v_mov_b32_e32 v30, v106
	v_mov_b32_e32 v31, v107
	v_lshlrev_b32_e32 v48, 16, v30
	global_store_dwordx2 v[32:33], v[28:29], off offset:64
	v_lshlrev_b32_e32 v28, 16, v8
	v_and_b32_e32 v29, 0xffff0000, v8
	v_lshlrev_b32_e32 v8, 16, v9
	v_and_b32_e32 v9, 0xffff0000, v9
	v_and_b32_e32 v49, 0xffff0000, v30
	v_lshlrev_b32_e32 v30, 16, v31
	v_and_b32_e32 v31, 0xffff0000, v31
	v_pk_fma_f32 v[28:29], v[66:67], v[28:29], v[48:49]
	v_pk_fma_f32 v[8:9], v[54:55], v[8:9], v[30:31]
	v_cvt_pk_bf16_f32 v28, v28, v29
	v_cvt_pk_bf16_f32 v29, v8, v9
	s_waitcnt vmcnt(19)
	s_nop 0
	v_mov_b32_e32 v8, v108
	v_mov_b32_e32 v9, v109
	v_mov_b32_e32 v30, v110
	v_mov_b32_e32 v31, v111
	v_lshlrev_b32_e32 v48, 16, v30
	global_store_dwordx2 v[32:33], v[28:29], off offset:80
	v_lshlrev_b32_e32 v28, 16, v8
	v_and_b32_e32 v29, 0xffff0000, v8
	v_lshlrev_b32_e32 v8, 16, v9
	v_and_b32_e32 v9, 0xffff0000, v9
	v_and_b32_e32 v49, 0xffff0000, v30
	v_lshlrev_b32_e32 v30, 16, v31
	v_and_b32_e32 v31, 0xffff0000, v31
	v_pk_fma_f32 v[28:29], v[74:75], v[28:29], v[48:49]
	v_pk_fma_f32 v[8:9], v[68:69], v[8:9], v[30:31]
	v_cvt_pk_bf16_f32 v28, v28, v29
	v_cvt_pk_bf16_f32 v29, v8, v9
	s_waitcnt vmcnt(18)
	s_nop 0
	v_mov_b32_e32 v8, v112
	v_mov_b32_e32 v9, v113
	v_mov_b32_e32 v30, v114
	v_mov_b32_e32 v31, v115
	v_lshlrev_b32_e32 v48, 16, v30
	global_store_dwordx2 v[32:33], v[28:29], off offset:96
	v_lshlrev_b32_e32 v28, 16, v8
	v_and_b32_e32 v29, 0xffff0000, v8
	v_lshlrev_b32_e32 v8, 16, v9
	v_and_b32_e32 v9, 0xffff0000, v9
	v_and_b32_e32 v49, 0xffff0000, v30
	v_lshlrev_b32_e32 v30, 16, v31
	v_and_b32_e32 v31, 0xffff0000, v31
	v_pk_fma_f32 v[28:29], v[46:47], v[28:29], v[48:49]
	v_pk_fma_f32 v[8:9], v[44:45], v[8:9], v[30:31]
	v_cvt_pk_bf16_f32 v28, v28, v29
	v_cvt_pk_bf16_f32 v29, v8, v9
	global_store_dwordx2 v[32:33], v[28:29], off offset:112
	s_waitcnt vmcnt(18)
; __device__ __forceinline__ unsigned pk2(float lo, float hi) { f32x2_t v = {lo, hi}; bf16x2_t b = __builtin_convertvector(v, bf16x2_t); return __builtin_bit_cast(unsigned, b); }
; __device__ __forceinline__ float bflo(unsigned u) { return __uint_as_float(u << 16); }
; __device__ __forceinline__ float bfhi(unsigned u) { return __uint_as_float(u & 0xffff0000u); }
; template <int DV, bool ACCUM>
; __device__ __forceinline__ void attn_store(const f32x16 (&o)[DV / 32], const bf16_t* gate_row, bf16_t* merged_row, int h) {
; #pragma unroll
;     for (int db = 0; db < DV / 32; ++db)
; #pragma unroll
;         for (int rg = 0; rg < 4; ++rg) {
;             const int d = 32 * db + 8 * rg + 4 * h;
;             const u32x2 g = *(const u32x2*)(gate_row + d);
;             float v0 = o[db][4 * rg + 0] * bflo(g.x), v1 = o[db][4 * rg + 1] * bfhi(g.x), v2 = o[db][4 * rg + 2] * bflo(g.y), v3 = o[db][4 * rg + 3] * bfhi(g.y);
;             if (ACCUM) { const u32x2 mm = *(const u32x2*)(merged_row + d); v0 += bflo(mm.x); v1 += bfhi(mm.x); v2 += bflo(mm.y); v3 += bfhi(mm.y); }
;             u32x2 w; w.x = pk2(v0, v1); w.y = pk2(v2, v3);
;             *(u32x2*)(merged_row + d) = w;
;             if (rg == 3) __builtin_amdgcn_sched_barrier(0);
;         }
; __global__ void __launch_bounds__(512) fwd_megakernel(Args a) {
;     ...
;                 for (int u = vcu; u < NB_CHUNK * 8 * 8; u += G) {
;                     const int qb = u & 7, hh = (u >> 3) & 7, b = u >> 6; const size_t tok0 = (size_t)b * SEQ; const int q0 = 256 * qb;
	s_nop 0
	v_mov_b32_e32 v8, v116
	v_mov_b32_e32 v9, v117
	v_mov_b32_e32 v30, v118
	v_mov_b32_e32 v31, v119
	v_lshlrev_b32_e32 v28, 16, v8
	v_and_b32_e32 v29, 0xffff0000, v8
	v_lshlrev_b32_e32 v8, 16, v9
	v_and_b32_e32 v9, 0xffff0000, v9
	v_lshlrev_b32_e32 v44, 16, v30
	v_and_b32_e32 v45, 0xffff0000, v30
	v_lshlrev_b32_e32 v30, 16, v31
	v_and_b32_e32 v31, 0xffff0000, v31
	v_pk_fma_f32 v[28:29], v[42:43], v[28:29], v[44:45]
	v_pk_fma_f32 v[8:9], v[40:41], v[8:9], v[30:31]
	v_cvt_pk_bf16_f32 v28, v28, v29
	v_cvt_pk_bf16_f32 v29, v8, v9
	s_waitcnt vmcnt(16)
	s_nop 0
	v_mov_b32_e32 v8, v120
	v_mov_b32_e32 v9, v121
	v_mov_b32_e32 v30, v122
	v_mov_b32_e32 v31, v123
	v_lshlrev_b32_e32 v40, 16, v30
	global_store_dwordx2 v[32:33], v[28:29], off offset:128
	v_lshlrev_b32_e32 v28, 16, v8
	v_and_b32_e32 v29, 0xffff0000, v8
	v_lshlrev_b32_e32 v8, 16, v9
	v_and_b32_e32 v9, 0xffff0000, v9
	v_and_b32_e32 v41, 0xffff0000, v30
	v_lshlrev_b32_e32 v30, 16, v31
	v_and_b32_e32 v31, 0xffff0000, v31
	v_pk_fma_f32 v[28:29], v[38:39], v[28:29], v[40:41]
	v_pk_fma_f32 v[8:9], v[36:37], v[8:9], v[30:31]
	v_cvt_pk_bf16_f32 v28, v28, v29
	v_cvt_pk_bf16_f32 v29, v8, v9
	s_waitcnt vmcnt(15)
	s_nop 0
	v_mov_b32_e32 v8, v124
	v_mov_b32_e32 v9, v125
	v_mov_b32_e32 v30, v126
	v_mov_b32_e32 v31, v127
	v_lshlrev_b32_e32 v36, 16, v30
	global_store_dwordx2 v[32:33], v[28:29], off offset:144
	v_lshlrev_b32_e32 v28, 16, v8
	v_and_b32_e32 v29, 0xffff0000, v8
	v_lshlrev_b32_e32 v8, 16, v9
	v_and_b32_e32 v9, 0xffff0000, v9
	v_and_b32_e32 v37, 0xffff0000, v30
	v_lshlrev_b32_e32 v30, 16, v31
	v_and_b32_e32 v31, 0xffff0000, v31
	v_pk_fma_f32 v[28:29], v[34:35], v[28:29], v[36:37]
	v_pk_fma_f32 v[8:9], v[26:27], v[8:9], v[30:31]
	v_cvt_pk_bf16_f32 v26, v28, v29
	v_cvt_pk_bf16_f32 v27, v8, v9
	s_waitcnt vmcnt(14)
	s_nop 0
	v_mov_b32_e32 v8, v128
	v_mov_b32_e32 v9, v129
	v_mov_b32_e32 v28, v130
	v_mov_b32_e32 v29, v131
	v_lshlrev_b32_e32 v30, 16, v28
	global_store_dwordx2 v[32:33], v[26:27], off offset:160
	v_lshlrev_b32_e32 v26, 16, v8
	v_and_b32_e32 v27, 0xffff0000, v8
	v_and_b32_e32 v31, 0xffff0000, v28
	v_lshlrev_b32_e32 v8, 16, v9
	v_and_b32_e32 v9, 0xffff0000, v9
	v_pk_fma_f32 v[24:25], v[24:25], v[26:27], v[30:31]
	v_lshlrev_b32_e32 v26, 16, v29
	v_and_b32_e32 v27, 0xffff0000, v29
	v_pk_fma_f32 v[8:9], v[22:23], v[8:9], v[26:27]
	v_cvt_pk_bf16_f32 v22, v24, v25
	v_cvt_pk_bf16_f32 v23, v8, v9
	global_store_dwordx2 v[32:33], v[22:23], off offset:176
	s_waitcnt vmcnt(14)
	s_nop 0
	v_mov_b32_e32 v8, v132
	v_mov_b32_e32 v9, v133
	v_mov_b32_e32 v24, v134
	v_mov_b32_e32 v25, v135
	v_pk_mul_f32 v[2:3], v[0:1], v[2:3] op_sel_hi:[0,1]
	v_pk_mul_f32 v[4:5], v[0:1], v[4:5] op_sel_hi:[0,1]
	v_pk_mul_f32 v[2:3], v[2:3], v[188:189]
	v_pk_mul_f32 v[4:5], v[4:5], v[14:15]
	v_lshlrev_b32_e32 v22, 16, v8
	v_and_b32_e32 v23, 0xffff0000, v8
	v_lshlrev_b32_e32 v26, 16, v24
	v_and_b32_e32 v27, 0xffff0000, v24
	v_lshlrev_b32_e32 v8, 16, v9
	v_and_b32_e32 v9, 0xffff0000, v9
	v_pk_fma_f32 v[20:21], v[20:21], v[22:23], v[26:27]
	v_lshlrev_b32_e32 v22, 16, v25
	v_and_b32_e32 v23, 0xffff0000, v25
	v_pk_fma_f32 v[8:9], v[18:19], v[8:9], v[22:23]
	v_cvt_pk_bf16_f32 v18, v20, v21
	v_cvt_pk_bf16_f32 v19, v8, v9
	s_waitcnt vmcnt(12)
	s_nop 0
	v_mov_b32_e32 v8, v136
	v_mov_b32_e32 v9, v137
	v_mov_b32_e32 v20, v138
	v_mov_b32_e32 v21, v139
	v_lshlrev_b32_e32 v22, 16, v20
	global_store_dwordx2 v[32:33], v[18:19], off offset:192
	v_lshlrev_b32_e32 v18, 16, v8
	v_and_b32_e32 v19, 0xffff0000, v8
	v_and_b32_e32 v23, 0xffff0000, v20
	v_lshlrev_b32_e32 v8, 16, v9
	v_and_b32_e32 v9, 0xffff0000, v9
	v_pk_fma_f32 v[16:17], v[16:17], v[18:19], v[22:23]
	v_lshlrev_b32_e32 v18, 16, v21
	v_and_b32_e32 v19, 0xffff0000, v21
	v_pk_fma_f32 v[8:9], v[12:13], v[8:9], v[18:19]
	v_cvt_pk_bf16_f32 v12, v16, v17
	v_cvt_pk_bf16_f32 v13, v8, v9
	s_waitcnt vmcnt(11)
	s_nop 0
	v_mov_b32_e32 v8, v140
	v_mov_b32_e32 v9, v141
	v_mov_b32_e32 v16, v142
	v_mov_b32_e32 v17, v143
	v_lshlrev_b32_e32 v18, 16, v16
	global_store_dwordx2 v[32:33], v[12:13], off offset:208
	v_lshlrev_b32_e32 v12, 16, v8
	v_and_b32_e32 v13, 0xffff0000, v8
	v_and_b32_e32 v19, 0xffff0000, v16
	v_lshlrev_b32_e32 v8, 16, v9
	v_and_b32_e32 v9, 0xffff0000, v9
	v_pk_fma_f32 v[10:11], v[10:11], v[12:13], v[18:19]
	v_lshlrev_b32_e32 v12, 16, v17
	v_and_b32_e32 v13, 0xffff0000, v17
	v_pk_fma_f32 v[6:7], v[6:7], v[8:9], v[12:13]
	v_cvt_pk_bf16_f32 v8, v10, v11
	v_cvt_pk_bf16_f32 v9, v6, v7
	global_store_dwordx2 v[32:33], v[8:9], off offset:224
	s_waitcnt vmcnt(11)
	s_nop 0
	v_mov_b32_e32 v6, v144
	v_mov_b32_e32 v7, v145
	s_nop 0
	v_mov_b32_e32 v8, v146
	v_mov_b32_e32 v9, v147
	v_lshlrev_b32_e32 v10, 16, v6
	v_and_b32_e32 v11, 0xffff0000, v6
	v_lshlrev_b32_e32 v12, 16, v8
	v_and_b32_e32 v13, 0xffff0000, v8
	v_lshlrev_b32_e32 v6, 16, v7
	v_and_b32_e32 v7, 0xffff0000, v7
	v_lshlrev_b32_e32 v8, 16, v9
	v_and_b32_e32 v9, 0xffff0000, v9
	v_pk_fma_f32 v[2:3], v[2:3], v[10:11], v[12:13]
	v_pk_fma_f32 v[4:5], v[4:5], v[6:7], v[8:9]
	v_cvt_pk_bf16_f32 v2, v2, v3
	v_cvt_pk_bf16_f32 v3, v4, v5
	global_store_dwordx2 v[32:33], v[2:3], off offset:240
	v_readlane_b32 s0, v254, 0
	s_add_i32 s24, s24, s30
	s_add_i32 s23, s23, s0
	s_cmpk_gt_i32 s24, 0x3ff
	s_cbranch_scc1 .LBB0_1001

; __device__ __forceinline__ float row_ssq(const float* part, int pitch, int n4, int row, int fq) {
;     f32x4 v = (f32x4){0.f, 0.f, 0.f, 0.f};
;     if (fq < n4) v = *(const f32x4*)(part + (size_t)row * pitch + 4 * fq);
;     float s = (v[0] + v[1]) + (v[2] + v[3]);
;     s += __shfl_xor(s, 16); s += __shfl_xor(s, 32);
;     return s;
; }
;     __device__ __forceinline__ void operator()(const f32x4 (&acc)[2][2][4][2], const Unit& u, int wr, int wc, int fr, int fq) const {
;     ...
;             for (int m = 0; m < 4; ++m) {
;                 const int row = row0 + ai * HALF + m * 16;
;                 const float rs = rsqrtf(row_ssq(ssq, 16, 4, row, fq) * (1.f / 1024.f) + EPS);
.LBB0_1154:
	v_and_b32_e32 v145, 64, v241
	v_xor_b32_e32 v143, 16, v241
	v_add_u32_e32 v145, 64, v145
	v_cmp_lt_i32_e32 vcc, v143, v145
	v_lshl_add_u32 v144, s39, 8, v146
	v_lshl_or_b32 v142, s4, 7, v148
	v_cndmask_b32_e32 v143, v241, v143, vcc
	v_lshlrev_b32_e32 v150, 2, v143
	v_xor_b32_e32 v143, 32, v241
	v_cmp_lt_i32_e32 vcc, v143, v145
	v_ashrrev_i32_e32 v145, 31, v144
	v_and_b32_e32 v166, 48, v241
	v_lshl_add_u32 v166, v146, 6, v166
	v_add_u32_e32 v166, 0x24000, v166
	ds_read_b128 v[168:171], v166
	ds_read_b128 v[172:175], v166 offset:1024
	ds_read_b128 v[176:179], v166 offset:2048
	ds_read_b128 v[180:183], v166 offset:3072
	v_cndmask_b32_e32 v143, v241, v143, vcc
	v_lshlrev_b32_e32 v151, 2, v143
	ds_read_b128 v[184:187], v166 offset:8192
	ds_read_b128 v[188:191], v166 offset:9216
	ds_read_b128 v[192:195], v166 offset:10240
	ds_read_b128 v[196:199], v166 offset:11264
	v_ashrrev_i32_e32 v143, 31, v142
	v_lshl_add_u64 v[142:143], v[142:143], 1, s[96:97]
	s_movk_i32 s4, 0x1600
	s_mov_b64 s[22:23], -1
	s_waitcnt lgkmcnt(7)
	v_add_f32_e32 v168, v169, v168
	v_add_f32_e32 v170, v170, v171
	v_add_f32_e32 v168, v168, v170
	v_mov_b32_e32 v169, v168
	s_nop 1
	v_permlane16_swap_b32_e32 v168, v169
	s_waitcnt lgkmcnt(6)
	v_add_f32_e32 v172, v173, v172
	v_add_f32_e32 v174, v174, v175
	v_add_f32_e32 v172, v172, v174
	v_mov_b32_e32 v173, v172
	s_nop 1
	v_permlane16_swap_b32_e32 v172, v173
	s_waitcnt lgkmcnt(5)
	v_add_f32_e32 v176, v177, v176
	v_add_f32_e32 v178, v178, v179
	v_add_f32_e32 v176, v176, v178
	v_mov_b32_e32 v177, v176
	s_nop 1
	v_permlane16_swap_b32_e32 v176, v177
	s_waitcnt lgkmcnt(4)
	v_add_f32_e32 v180, v181, v180
	v_add_f32_e32 v182, v182, v183
	v_add_f32_e32 v180, v180, v182
	v_mov_b32_e32 v181, v180
	s_nop 1
	v_permlane16_swap_b32_e32 v180, v181
	s_waitcnt lgkmcnt(3)
	v_add_f32_e32 v184, v185, v184
	v_add_f32_e32 v186, v186, v187
	v_add_f32_e32 v184, v184, v186
	v_mov_b32_e32 v185, v184
	s_nop 1
	v_permlane16_swap_b32_e32 v184, v185
	s_waitcnt lgkmcnt(2)
	v_add_f32_e32 v188, v189, v188
	v_add_f32_e32 v190, v190, v191
	v_add_f32_e32 v188, v188, v190
	v_mov_b32_e32 v189, v188
	s_nop 1
	v_permlane16_swap_b32_e32 v188, v189
	s_waitcnt lgkmcnt(1)
	v_add_f32_e32 v192, v193, v192
	v_add_f32_e32 v194, v194, v195
	v_add_f32_e32 v192, v192, v194
	v_mov_b32_e32 v193, v192
	s_nop 1
	v_permlane16_swap_b32_e32 v192, v193
	s_waitcnt lgkmcnt(0)
	v_add_f32_e32 v196, v197, v196
	v_add_f32_e32 v198, v198, v199
	v_add_f32_e32 v196, v196, v198
	v_mov_b32_e32 v197, v196
	s_nop 1
	v_permlane16_swap_b32_e32 v196, v197
	s_waitcnt lgkmcnt(7)
	v_add_f32_e32 v168, v168, v169
	v_mov_b32_e32 v169, v168
	s_nop 1
	v_permlane32_swap_b32_e32 v168, v169
	s_waitcnt lgkmcnt(7)
	v_add_f32_e32 v172, v172, v173
	v_mov_b32_e32 v173, v172
	s_nop 1
	v_permlane32_swap_b32_e32 v172, v173
	s_waitcnt lgkmcnt(7)
	v_add_f32_e32 v176, v176, v177
	v_mov_b32_e32 v177, v176
	s_nop 1
	v_permlane32_swap_b32_e32 v176, v177
	s_waitcnt lgkmcnt(7)
	v_add_f32_e32 v180, v180, v181
	v_mov_b32_e32 v181, v180
	s_nop 1
	v_permlane32_swap_b32_e32 v180, v181
	s_waitcnt lgkmcnt(7)
	v_add_f32_e32 v184, v184, v185
	v_mov_b32_e32 v185, v184
	s_nop 1
	v_permlane32_swap_b32_e32 v184, v185
	s_waitcnt lgkmcnt(7)
	v_add_f32_e32 v188, v188, v189
	v_mov_b32_e32 v189, v188
	s_nop 1
	v_permlane32_swap_b32_e32 v188, v189
	s_waitcnt lgkmcnt(7)
	v_add_f32_e32 v192, v192, v193
	v_mov_b32_e32 v193, v192
	s_nop 1
	v_permlane32_swap_b32_e32 v192, v193
	s_waitcnt lgkmcnt(7)
	v_add_f32_e32 v196, v196, v197
	v_mov_b32_e32 v197, v196
	s_nop 1
	v_permlane32_swap_b32_e32 v196, v197
	s_waitcnt lgkmcnt(7)
	v_add_f32_e32 v168, v168, v169
	v_fmamk_f32 v168, v168, 0x3a800000, v239
	s_waitcnt lgkmcnt(6)
	v_add_f32_e32 v172, v172, v173
	v_fmamk_f32 v172, v172, 0x3a800000, v239
	s_waitcnt lgkmcnt(5)
	v_add_f32_e32 v176, v176, v177
	v_fmamk_f32 v176, v176, 0x3a800000, v239
	s_waitcnt lgkmcnt(4)
	v_add_f32_e32 v180, v180, v181
	v_fmamk_f32 v180, v180, 0x3a800000, v239
	s_waitcnt lgkmcnt(3)
	v_add_f32_e32 v184, v184, v185
	v_fmamk_f32 v184, v184, 0x3a800000, v239
	s_waitcnt lgkmcnt(2)
	v_add_f32_e32 v188, v188, v189
	v_fmamk_f32 v188, v188, 0x3a800000, v239
	s_waitcnt lgkmcnt(1)
	v_add_f32_e32 v192, v192, v193
	v_fmamk_f32 v192, v192, 0x3a800000, v239
	s_waitcnt lgkmcnt(0)
; __device__ __forceinline__ unsigned pk2(float lo, float hi) { f32x2_t v = {lo, hi}; bf16x2_t b = __builtin_convertvector(v, bf16x2_t); return __builtin_bit_cast(unsigned, b); }
; __device__ __forceinline__ float fast_sigmoid(float x) { return __builtin_amdgcn_rcpf(1.f + __expf(-x)); }
;     __device__ __forceinline__ void operator()(const f32x4 (&acc)[2][2][4][2], const Unit& u, int wr, int wc, int fr, int fq) const {
;     ...
;                 const float rs = rsqrtf(row_ssq(ssq, 16, 4, row, fq) * (1.f / 1024.f) + EPS);
;                 float r[8];
; #pragma unroll
;                 for (int n = 0; n < 2; ++n)
; #pragma unroll
;                     for (int e = 0; e < 4; ++e) { const float gv = acc[ai][0][m][n][e] * rs, uv = acc[ai][1][m][n][e] * rs; r[n * 4 + e] = gv * fast_sigmoid(gv) * uv; }
;                 u32x4 w; w.x = pk2(r[0], r[1]); w.y = pk2(r[2], r[3]); w.z = pk2(r[4], r[5]); w.w = pk2(r[6], r[7]);
;                 *(u32x4*)(O + (size_t)row * DFF + col0) = w;
	v_add_f32_e32 v196, v196, v197
	v_fmamk_f32 v196, v196, 0x3a800000, v239
	s_nop 0
	v_rsq_f32_e32 v158, v168
	s_nop 0
	s_nop 0
	s_nop 0
	v_rsq_f32_e32 v159, v172
	s_nop 0
	s_nop 0
	s_nop 0
	v_rsq_f32_e32 v160, v176
	s_nop 0
	s_nop 0
	s_nop 0
	v_rsq_f32_e32 v161, v180
	s_nop 0
	s_nop 0
	s_nop 0
	v_rsq_f32_e32 v162, v184
	s_nop 0
	s_nop 0
	s_nop 0
	v_rsq_f32_e32 v163, v188
	s_nop 0
	s_nop 0
	s_nop 0
	v_rsq_f32_e32 v164, v192
	s_nop 0
	s_nop 0
	s_nop 0
	v_rsq_f32_e32 v165, v196
	s_nop 0
	s_nop 0
	v_mov_b32_e32 v152, v158
	v_pk_mul_f32 v[126:127], v[126:127], v[152:153] op_sel_hi:[1,0]
	v_pk_mul_f32 v[118:119], v[118:119], v[152:153] op_sel_hi:[1,0]
	v_mul_f32_e32 v145, 0xbfb8aa3b, v126
	v_exp_f32_e32 v145, v145
	v_pk_mul_f32 v[120:121], v[120:121], v[152:153] op_sel_hi:[1,0]
	v_pk_mul_f32 v[122:123], v[122:123], v[152:153] op_sel_hi:[1,0]
	v_pk_mul_f32 v[114:115], v[114:115], v[152:153] op_sel_hi:[1,0]
	v_add_f32_e32 v145, 1.0, v145
	v_rcp_f32_e32 v154, v145
	v_mul_f32_e32 v145, 0xbfb8aa3b, v127
	v_exp_f32_e32 v145, v145
	v_pk_mul_f32 v[116:117], v[116:117], v[152:153] op_sel_hi:[1,0]
	v_add_f32_e32 v145, 1.0, v145
	v_rcp_f32_e32 v155, v145
	s_nop 0
	v_pk_mul_f32 v[126:127], v[126:127], v[154:155]
	s_nop 0
	v_pk_mul_f32 v[118:119], v[118:119], v[126:127]
	v_pk_mul_f32 v[126:127], v[128:129], v[152:153] op_sel_hi:[1,0]
	s_nop 0
	v_mul_f32_e32 v128, 0xbfb8aa3b, v126
	v_mul_f32_e32 v129, 0xbfb8aa3b, v127
	v_exp_f32_e32 v128, v128
	v_exp_f32_e32 v129, v129
	v_add_f32_e32 v128, 1.0, v128
	v_add_f32_e32 v129, 1.0, v129
	v_rcp_f32_e32 v128, v128
	v_rcp_f32_e32 v129, v129
	s_nop 0
	v_pk_mul_f32 v[126:127], v[126:127], v[128:129]
	s_nop 0
	v_pk_mul_f32 v[120:121], v[120:121], v[126:127]
	v_mul_f32_e32 v126, 0xbfb8aa3b, v122
	v_mul_f32_e32 v127, 0xbfb8aa3b, v123
	v_exp_f32_e32 v126, v126
	v_exp_f32_e32 v127, v127
	v_add_f32_e32 v126, 1.0, v126
	v_add_f32_e32 v127, 1.0, v127
	v_rcp_f32_e32 v126, v126
	v_rcp_f32_e32 v127, v127
	s_nop 0
	v_pk_mul_f32 v[122:123], v[122:123], v[126:127]
	s_nop 0
	v_pk_mul_f32 v[122:123], v[114:115], v[122:123]
	v_pk_mul_f32 v[114:115], v[124:125], v[152:153] op_sel_hi:[1,0]
	s_nop 0
	v_mul_f32_e32 v124, 0xbfb8aa3b, v114
	v_mul_f32_e32 v125, 0xbfb8aa3b, v115
	v_exp_f32_e32 v124, v124
	v_exp_f32_e32 v125, v125
	v_add_f32_e32 v124, 1.0, v124
	v_add_f32_e32 v125, 1.0, v125
	v_rcp_f32_e32 v124, v124
	v_rcp_f32_e32 v125, v125
	s_nop 0
	v_pk_mul_f32 v[114:115], v[114:115], v[124:125]
	s_nop 0
	v_pk_mul_f32 v[124:125], v[116:117], v[114:115]
	v_cvt_pk_bf16_f32 v114, v118, v119
	v_cvt_pk_bf16_f32 v115, v120, v121
	v_cvt_pk_bf16_f32 v116, v122, v123
	v_cvt_pk_bf16_f32 v117, v124, v125
	v_mad_i64_i32 v[118:119], s[6:7], v144, s4, v[142:143]
	global_store_dwordx4 v[118:119], v[114:117], off
	s_nop 1
	v_or_b32_e32 v114, 16, v144
	v_mov_b32_e32 v116, v159
	v_pk_mul_f32 v[110:111], v[110:111], v[116:117] op_sel_hi:[1,0]
	v_pk_mul_f32 v[102:103], v[102:103], v[116:117] op_sel_hi:[1,0]
	v_mul_f32_e32 v115, 0xbfb8aa3b, v110
	v_exp_f32_e32 v115, v115
	v_pk_mul_f32 v[104:105], v[104:105], v[116:117] op_sel_hi:[1,0]
	v_pk_mul_f32 v[106:107], v[106:107], v[116:117] op_sel_hi:[1,0]
	v_pk_mul_f32 v[98:99], v[98:99], v[116:117] op_sel_hi:[1,0]
	v_add_f32_e32 v115, 1.0, v115
	v_rcp_f32_e32 v118, v115
	v_mul_f32_e32 v115, 0xbfb8aa3b, v111
	v_exp_f32_e32 v115, v115
	v_pk_mul_f32 v[100:101], v[100:101], v[116:117] op_sel_hi:[1,0]
	v_add_f32_e32 v115, 1.0, v115
	v_rcp_f32_e32 v119, v115
	s_nop 0
	v_pk_mul_f32 v[110:111], v[110:111], v[118:119]
	s_nop 0
	v_pk_mul_f32 v[102:103], v[102:103], v[110:111]
	v_pk_mul_f32 v[110:111], v[112:113], v[116:117] op_sel_hi:[1,0]
	s_nop 0
	v_mul_f32_e32 v112, 0xbfb8aa3b, v110
	v_mul_f32_e32 v113, 0xbfb8aa3b, v111
	v_exp_f32_e32 v112, v112
	v_exp_f32_e32 v113, v113
	v_add_f32_e32 v112, 1.0, v112
	v_add_f32_e32 v113, 1.0, v113
	v_rcp_f32_e32 v112, v112
	v_rcp_f32_e32 v113, v113
	s_nop 0
	v_pk_mul_f32 v[110:111], v[110:111], v[112:113]
	s_nop 0
	v_pk_mul_f32 v[104:105], v[104:105], v[110:111]
	v_mul_f32_e32 v110, 0xbfb8aa3b, v106
	v_mul_f32_e32 v111, 0xbfb8aa3b, v107
	v_exp_f32_e32 v110, v110
	v_exp_f32_e32 v111, v111
	v_add_f32_e32 v110, 1.0, v110
	v_add_f32_e32 v111, 1.0, v111
	v_rcp_f32_e32 v110, v110
	v_rcp_f32_e32 v111, v111
	s_nop 0
	v_pk_mul_f32 v[106:107], v[106:107], v[110:111]
	s_nop 0
	v_pk_mul_f32 v[106:107], v[98:99], v[106:107]
	v_pk_mul_f32 v[98:99], v[108:109], v[116:117] op_sel_hi:[1,0]
	s_nop 0
	v_mul_f32_e32 v108, 0xbfb8aa3b, v98
	v_mul_f32_e32 v109, 0xbfb8aa3b, v99
	v_exp_f32_e32 v108, v108
	v_exp_f32_e32 v109, v109
	v_add_f32_e32 v108, 1.0, v108
	v_add_f32_e32 v109, 1.0, v109
	v_rcp_f32_e32 v108, v108
	v_rcp_f32_e32 v109, v109
	s_nop 0
	v_pk_mul_f32 v[98:99], v[98:99], v[108:109]
	s_nop 0
	v_pk_mul_f32 v[108:109], v[100:101], v[98:99]
	v_cvt_pk_bf16_f32 v98, v102, v103
	v_cvt_pk_bf16_f32 v99, v104, v105
	v_cvt_pk_bf16_f32 v100, v106, v107
	v_cvt_pk_bf16_f32 v101, v108, v109
	v_mad_i64_i32 v[102:103], s[6:7], v114, s4, v[142:143]
	global_store_dwordx4 v[102:103], v[98:101], off
	s_nop 1
	v_or_b32_e32 v98, 32, v144
	v_mov_b32_e32 v100, v160
	v_pk_mul_f32 v[94:95], v[94:95], v[100:101] op_sel_hi:[1,0]
	v_pk_mul_f32 v[86:87], v[86:87], v[100:101] op_sel_hi:[1,0]
	v_mul_f32_e32 v99, 0xbfb8aa3b, v94
	v_exp_f32_e32 v99, v99
	v_pk_mul_f32 v[88:89], v[88:89], v[100:101] op_sel_hi:[1,0]
	v_pk_mul_f32 v[90:91], v[90:91], v[100:101] op_sel_hi:[1,0]
	v_pk_mul_f32 v[82:83], v[82:83], v[100:101] op_sel_hi:[1,0]
	v_add_f32_e32 v99, 1.0, v99
	v_rcp_f32_e32 v102, v99
	v_mul_f32_e32 v99, 0xbfb8aa3b, v95
	v_exp_f32_e32 v99, v99
	v_pk_mul_f32 v[84:85], v[84:85], v[100:101] op_sel_hi:[1,0]
	v_add_f32_e32 v99, 1.0, v99
; __device__ __forceinline__ unsigned pk2(float lo, float hi) { f32x2_t v = {lo, hi}; bf16x2_t b = __builtin_convertvector(v, bf16x2_t); return __builtin_bit_cast(unsigned, b); }
; __device__ __forceinline__ float fast_sigmoid(float x) { return __builtin_amdgcn_rcpf(1.f + __expf(-x)); }
;     __device__ __forceinline__ void operator()(const f32x4 (&acc)[2][2][4][2], const Unit& u, int wr, int wc, int fr, int fq) const {
;     ...
;                 for (int n = 0; n < 2; ++n)
; #pragma unroll
;                     for (int e = 0; e < 4; ++e) { const float gv = acc[ai][0][m][n][e] * rs, uv = acc[ai][1][m][n][e] * rs; r[n * 4 + e] = gv * fast_sigmoid(gv) * uv; }
;                 u32x4 w; w.x = pk2(r[0], r[1]); w.y = pk2(r[2], r[3]); w.z = pk2(r[4], r[5]); w.w = pk2(r[6], r[7]);
;                 *(u32x4*)(O + (size_t)row * DFF + col0) = w;
	v_rcp_f32_e32 v103, v99
	s_nop 0
	v_pk_mul_f32 v[94:95], v[94:95], v[102:103]
	s_nop 0
	v_pk_mul_f32 v[86:87], v[86:87], v[94:95]
	v_pk_mul_f32 v[94:95], v[96:97], v[100:101] op_sel_hi:[1,0]
	s_nop 0
	v_mul_f32_e32 v96, 0xbfb8aa3b, v94
	v_mul_f32_e32 v97, 0xbfb8aa3b, v95
	v_exp_f32_e32 v96, v96
	v_exp_f32_e32 v97, v97
	v_add_f32_e32 v96, 1.0, v96
	v_add_f32_e32 v97, 1.0, v97
	v_rcp_f32_e32 v96, v96
	v_rcp_f32_e32 v97, v97
	s_nop 0
	v_pk_mul_f32 v[94:95], v[94:95], v[96:97]
	s_nop 0
	v_pk_mul_f32 v[88:89], v[88:89], v[94:95]
	v_mul_f32_e32 v94, 0xbfb8aa3b, v90
	v_mul_f32_e32 v95, 0xbfb8aa3b, v91
	v_exp_f32_e32 v94, v94
	v_exp_f32_e32 v95, v95
	v_add_f32_e32 v94, 1.0, v94
	v_add_f32_e32 v95, 1.0, v95
	v_rcp_f32_e32 v94, v94
	v_rcp_f32_e32 v95, v95
	s_nop 0
	v_pk_mul_f32 v[90:91], v[90:91], v[94:95]
	s_nop 0
	v_pk_mul_f32 v[90:91], v[82:83], v[90:91]
	v_pk_mul_f32 v[82:83], v[92:93], v[100:101] op_sel_hi:[1,0]
	s_nop 0
	v_mul_f32_e32 v92, 0xbfb8aa3b, v82
	v_mul_f32_e32 v93, 0xbfb8aa3b, v83
	v_exp_f32_e32 v92, v92
	v_exp_f32_e32 v93, v93
	v_add_f32_e32 v92, 1.0, v92
	v_add_f32_e32 v93, 1.0, v93
	v_rcp_f32_e32 v92, v92
	v_rcp_f32_e32 v93, v93
	s_nop 0
	v_pk_mul_f32 v[82:83], v[82:83], v[92:93]
	s_nop 0
	v_pk_mul_f32 v[92:93], v[84:85], v[82:83]
	v_cvt_pk_bf16_f32 v82, v86, v87
	v_cvt_pk_bf16_f32 v83, v88, v89
	v_cvt_pk_bf16_f32 v84, v90, v91
	v_cvt_pk_bf16_f32 v85, v92, v93
	v_mad_i64_i32 v[86:87], s[6:7], v98, s4, v[142:143]
	global_store_dwordx4 v[86:87], v[82:85], off
	s_nop 1
	v_or_b32_e32 v82, 48, v144
	v_mov_b32_e32 v84, v161
	v_pk_mul_f32 v[78:79], v[78:79], v[84:85] op_sel_hi:[1,0]
	v_pk_mul_f32 v[70:71], v[70:71], v[84:85] op_sel_hi:[1,0]
	v_mul_f32_e32 v83, 0xbfb8aa3b, v78
	v_exp_f32_e32 v83, v83
	v_pk_mul_f32 v[72:73], v[72:73], v[84:85] op_sel_hi:[1,0]
	v_pk_mul_f32 v[74:75], v[74:75], v[84:85] op_sel_hi:[1,0]
	v_pk_mul_f32 v[66:67], v[66:67], v[84:85] op_sel_hi:[1,0]
	v_add_f32_e32 v83, 1.0, v83
	v_rcp_f32_e32 v86, v83
	v_mul_f32_e32 v83, 0xbfb8aa3b, v79
	v_exp_f32_e32 v83, v83
	v_pk_mul_f32 v[68:69], v[68:69], v[84:85] op_sel_hi:[1,0]
	v_add_f32_e32 v83, 1.0, v83
	v_rcp_f32_e32 v87, v83
	s_nop 0
	v_pk_mul_f32 v[78:79], v[78:79], v[86:87]
	s_nop 0
	v_pk_mul_f32 v[70:71], v[70:71], v[78:79]
	v_pk_mul_f32 v[78:79], v[80:81], v[84:85] op_sel_hi:[1,0]
	s_nop 0
	v_mul_f32_e32 v80, 0xbfb8aa3b, v78
	v_mul_f32_e32 v81, 0xbfb8aa3b, v79
	v_exp_f32_e32 v80, v80
	v_exp_f32_e32 v81, v81
	v_add_f32_e32 v80, 1.0, v80
	v_add_f32_e32 v81, 1.0, v81
	v_rcp_f32_e32 v80, v80
	v_rcp_f32_e32 v81, v81
	s_nop 0
	v_pk_mul_f32 v[78:79], v[78:79], v[80:81]
	s_nop 0
	v_pk_mul_f32 v[72:73], v[72:73], v[78:79]
	v_mul_f32_e32 v78, 0xbfb8aa3b, v74
	v_mul_f32_e32 v79, 0xbfb8aa3b, v75
	v_exp_f32_e32 v78, v78
	v_exp_f32_e32 v79, v79
	v_add_f32_e32 v78, 1.0, v78
	v_add_f32_e32 v79, 1.0, v79
	v_rcp_f32_e32 v78, v78
	v_rcp_f32_e32 v79, v79
	s_nop 0
	v_pk_mul_f32 v[74:75], v[74:75], v[78:79]
	s_nop 0
	v_pk_mul_f32 v[74:75], v[66:67], v[74:75]
	v_pk_mul_f32 v[66:67], v[76:77], v[84:85] op_sel_hi:[1,0]
	s_nop 0
	v_mul_f32_e32 v76, 0xbfb8aa3b, v66
	v_mul_f32_e32 v77, 0xbfb8aa3b, v67
	v_exp_f32_e32 v76, v76
	v_exp_f32_e32 v77, v77
	v_add_f32_e32 v76, 1.0, v76
	v_add_f32_e32 v77, 1.0, v77
	v_rcp_f32_e32 v76, v76
	v_rcp_f32_e32 v77, v77
	s_nop 0
	v_pk_mul_f32 v[66:67], v[66:67], v[76:77]
	s_nop 0
	v_pk_mul_f32 v[76:77], v[68:69], v[66:67]
	v_cvt_pk_bf16_f32 v66, v70, v71
	v_cvt_pk_bf16_f32 v67, v72, v73
	v_cvt_pk_bf16_f32 v68, v74, v75
	v_cvt_pk_bf16_f32 v69, v76, v77
	v_mad_i64_i32 v[70:71], s[6:7], v82, s4, v[142:143]
	global_store_dwordx4 v[70:71], v[66:69], off
	s_nop 1
	v_add_u32_e32 v66, 0x80, v144
	v_mov_b32_e32 v68, v162
	v_pk_mul_f32 v[62:63], v[62:63], v[68:69] op_sel_hi:[1,0]
	v_pk_mul_f32 v[54:55], v[54:55], v[68:69] op_sel_hi:[1,0]
	v_mul_f32_e32 v67, 0xbfb8aa3b, v62
	v_exp_f32_e32 v67, v67
	v_pk_mul_f32 v[56:57], v[56:57], v[68:69] op_sel_hi:[1,0]
	v_pk_mul_f32 v[58:59], v[58:59], v[68:69] op_sel_hi:[1,0]
	v_pk_mul_f32 v[50:51], v[50:51], v[68:69] op_sel_hi:[1,0]
	v_add_f32_e32 v67, 1.0, v67
	v_rcp_f32_e32 v70, v67
	v_mul_f32_e32 v67, 0xbfb8aa3b, v63
	v_exp_f32_e32 v67, v67
	v_pk_mul_f32 v[52:53], v[52:53], v[68:69] op_sel_hi:[1,0]
	v_add_f32_e32 v67, 1.0, v67
	v_rcp_f32_e32 v71, v67
	s_nop 0
	v_pk_mul_f32 v[62:63], v[62:63], v[70:71]
	s_nop 0
	v_pk_mul_f32 v[54:55], v[54:55], v[62:63]
	v_pk_mul_f32 v[62:63], v[64:65], v[68:69] op_sel_hi:[1,0]
	s_nop 0
	v_mul_f32_e32 v64, 0xbfb8aa3b, v62
	v_mul_f32_e32 v65, 0xbfb8aa3b, v63
	v_exp_f32_e32 v64, v64
	v_exp_f32_e32 v65, v65
	v_add_f32_e32 v64, 1.0, v64
	v_add_f32_e32 v65, 1.0, v65
	v_rcp_f32_e32 v64, v64
	v_rcp_f32_e32 v65, v65
	s_nop 0
	v_pk_mul_f32 v[62:63], v[62:63], v[64:65]
	s_nop 0
	v_pk_mul_f32 v[56:57], v[56:57], v[62:63]
	v_mul_f32_e32 v62, 0xbfb8aa3b, v58
	v_mul_f32_e32 v63, 0xbfb8aa3b, v59
	v_exp_f32_e32 v62, v62
	v_exp_f32_e32 v63, v63
	v_add_f32_e32 v62, 1.0, v62
	v_add_f32_e32 v63, 1.0, v63
	v_rcp_f32_e32 v62, v62
	v_rcp_f32_e32 v63, v63
	s_nop 0
	v_pk_mul_f32 v[58:59], v[58:59], v[62:63]
	s_nop 0
	v_pk_mul_f32 v[58:59], v[50:51], v[58:59]
	v_pk_mul_f32 v[50:51], v[60:61], v[68:69] op_sel_hi:[1,0]
	s_nop 0
	v_mul_f32_e32 v60, 0xbfb8aa3b, v50
	v_mul_f32_e32 v61, 0xbfb8aa3b, v51
	v_exp_f32_e32 v60, v60
	v_exp_f32_e32 v61, v61
	v_add_f32_e32 v60, 1.0, v60
	v_add_f32_e32 v61, 1.0, v61
	v_rcp_f32_e32 v60, v60
	v_rcp_f32_e32 v61, v61
	s_nop 0
	v_pk_mul_f32 v[50:51], v[50:51], v[60:61]
	s_nop 0
	v_pk_mul_f32 v[60:61], v[52:53], v[50:51]
	v_cvt_pk_bf16_f32 v50, v54, v55
	v_cvt_pk_bf16_f32 v51, v56, v57
	v_cvt_pk_bf16_f32 v52, v58, v59
	v_cvt_pk_bf16_f32 v53, v60, v61
	v_mad_i64_i32 v[54:55], s[6:7], v66, s4, v[142:143]
; __device__ __forceinline__ unsigned pk2(float lo, float hi) { f32x2_t v = {lo, hi}; bf16x2_t b = __builtin_convertvector(v, bf16x2_t); return __builtin_bit_cast(unsigned, b); }
; __device__ __forceinline__ float fast_sigmoid(float x) { return __builtin_amdgcn_rcpf(1.f + __expf(-x)); }
; #define PG8_BAR __builtin_amdgcn_s_barrier()
; template <class Epi>
; __device__ __forceinline__ void gemm_phase(LAS unsigned char* lds, int wave_s, const Gemm g, const StaticOrder S, const Epi E) {
;     ...
;         if (wr == 0) PG8_BAR;
;         E(acc, cur, wr, wc, fr, fq);
;         if (!has_next) break;
; #pragma unroll
;         for (int a = 0; a < 2; ++a)
; #pragma unroll
;             for (int b = 0; b < 2; ++b)
; #pragma unroll
;                 for (int m = 0; m < 4; ++m)
; #pragma unroll
;                     for (int n = 0; n < 2; ++n) acc[a][b][m][n] = (f32x4){0.f, 0.f, 0.f, 0.f};
;         cur = nxt; cA = nA; cB = nB; ++ui;
;         if (wr == 1) PG8_BAR;
;     __device__ __forceinline__ void operator()(const f32x4 (&acc)[2][2][4][2], const Unit& u, int wr, int wc, int fr, int fq) const {
;     ...
;                 for (int n = 0; n < 2; ++n)
; #pragma unroll
;                     for (int e = 0; e < 4; ++e) { const float gv = acc[ai][0][m][n][e] * rs, uv = acc[ai][1][m][n][e] * rs; r[n * 4 + e] = gv * fast_sigmoid(gv) * uv; }
;                 u32x4 w; w.x = pk2(r[0], r[1]); w.y = pk2(r[2], r[3]); w.z = pk2(r[4], r[5]); w.w = pk2(r[6], r[7]);
;                 *(u32x4*)(O + (size_t)row * DFF + col0) = w;
	global_store_dwordx4 v[54:55], v[50:53], off
	s_nop 1
	v_add_u32_e32 v50, 0x90, v144
	v_mov_b32_e32 v52, v163
	v_pk_mul_f32 v[46:47], v[46:47], v[52:53] op_sel_hi:[1,0]
	v_pk_mul_f32 v[38:39], v[38:39], v[52:53] op_sel_hi:[1,0]
	v_mul_f32_e32 v51, 0xbfb8aa3b, v46
	v_exp_f32_e32 v51, v51
	v_pk_mul_f32 v[40:41], v[40:41], v[52:53] op_sel_hi:[1,0]
	v_pk_mul_f32 v[42:43], v[42:43], v[52:53] op_sel_hi:[1,0]
	v_pk_mul_f32 v[34:35], v[34:35], v[52:53] op_sel_hi:[1,0]
	v_add_f32_e32 v51, 1.0, v51
	v_rcp_f32_e32 v54, v51
	v_mul_f32_e32 v51, 0xbfb8aa3b, v47
	v_exp_f32_e32 v51, v51
	v_pk_mul_f32 v[36:37], v[36:37], v[52:53] op_sel_hi:[1,0]
	v_add_f32_e32 v51, 1.0, v51
	v_rcp_f32_e32 v55, v51
	s_nop 0
	v_pk_mul_f32 v[46:47], v[46:47], v[54:55]
	s_nop 0
	v_pk_mul_f32 v[38:39], v[38:39], v[46:47]
	v_pk_mul_f32 v[46:47], v[48:49], v[52:53] op_sel_hi:[1,0]
	s_nop 0
	v_mul_f32_e32 v48, 0xbfb8aa3b, v46
	v_mul_f32_e32 v49, 0xbfb8aa3b, v47
	v_exp_f32_e32 v48, v48
	v_exp_f32_e32 v49, v49
	v_add_f32_e32 v48, 1.0, v48
	v_add_f32_e32 v49, 1.0, v49
	v_rcp_f32_e32 v48, v48
	v_rcp_f32_e32 v49, v49
	s_nop 0
	v_pk_mul_f32 v[46:47], v[46:47], v[48:49]
	s_nop 0
	v_pk_mul_f32 v[40:41], v[40:41], v[46:47]
	v_mul_f32_e32 v46, 0xbfb8aa3b, v42
	v_mul_f32_e32 v47, 0xbfb8aa3b, v43
	v_exp_f32_e32 v46, v46
	v_exp_f32_e32 v47, v47
	v_add_f32_e32 v46, 1.0, v46
	v_add_f32_e32 v47, 1.0, v47
	v_rcp_f32_e32 v46, v46
	v_rcp_f32_e32 v47, v47
	s_nop 0
	v_pk_mul_f32 v[42:43], v[42:43], v[46:47]
	s_nop 0
	v_pk_mul_f32 v[42:43], v[34:35], v[42:43]
	v_pk_mul_f32 v[34:35], v[44:45], v[52:53] op_sel_hi:[1,0]
	s_nop 0
	v_mul_f32_e32 v44, 0xbfb8aa3b, v34
	v_mul_f32_e32 v45, 0xbfb8aa3b, v35
	v_exp_f32_e32 v44, v44
	v_exp_f32_e32 v45, v45
	v_add_f32_e32 v44, 1.0, v44
	v_add_f32_e32 v45, 1.0, v45
	v_rcp_f32_e32 v44, v44
	v_rcp_f32_e32 v45, v45
	s_nop 0
	v_pk_mul_f32 v[34:35], v[34:35], v[44:45]
	s_nop 0
	v_pk_mul_f32 v[44:45], v[36:37], v[34:35]
	v_cvt_pk_bf16_f32 v34, v38, v39
	v_cvt_pk_bf16_f32 v35, v40, v41
	v_cvt_pk_bf16_f32 v36, v42, v43
	v_cvt_pk_bf16_f32 v37, v44, v45
	v_mad_i64_i32 v[38:39], s[6:7], v50, s4, v[142:143]
	global_store_dwordx4 v[38:39], v[34:37], off
	s_nop 1
	v_add_u32_e32 v34, 0xa0, v144
	v_mov_b32_e32 v36, v164
	v_pk_mul_f32 v[30:31], v[30:31], v[36:37] op_sel_hi:[1,0]
	v_pk_mul_f32 v[22:23], v[22:23], v[36:37] op_sel_hi:[1,0]
	v_mul_f32_e32 v35, 0xbfb8aa3b, v30
	v_exp_f32_e32 v35, v35
	v_pk_mul_f32 v[24:25], v[24:25], v[36:37] op_sel_hi:[1,0]
	v_pk_mul_f32 v[26:27], v[26:27], v[36:37] op_sel_hi:[1,0]
	v_pk_mul_f32 v[18:19], v[18:19], v[36:37] op_sel_hi:[1,0]
	v_add_f32_e32 v35, 1.0, v35
	v_rcp_f32_e32 v38, v35
	v_mul_f32_e32 v35, 0xbfb8aa3b, v31
	v_exp_f32_e32 v35, v35
	v_pk_mul_f32 v[20:21], v[20:21], v[36:37] op_sel_hi:[1,0]
	v_add_f32_e32 v35, 1.0, v35
	v_rcp_f32_e32 v39, v35
	s_nop 0
	v_pk_mul_f32 v[30:31], v[30:31], v[38:39]
	s_nop 0
	v_pk_mul_f32 v[22:23], v[22:23], v[30:31]
	v_pk_mul_f32 v[30:31], v[32:33], v[36:37] op_sel_hi:[1,0]
	s_nop 0
	v_mul_f32_e32 v32, 0xbfb8aa3b, v30
	v_mul_f32_e32 v33, 0xbfb8aa3b, v31
	v_exp_f32_e32 v32, v32
	v_exp_f32_e32 v33, v33
	v_add_f32_e32 v32, 1.0, v32
	v_add_f32_e32 v33, 1.0, v33
	v_rcp_f32_e32 v32, v32
	v_rcp_f32_e32 v33, v33
	s_nop 0
	v_pk_mul_f32 v[30:31], v[30:31], v[32:33]
	s_nop 0
	v_pk_mul_f32 v[24:25], v[24:25], v[30:31]
	v_mul_f32_e32 v30, 0xbfb8aa3b, v26
	v_mul_f32_e32 v31, 0xbfb8aa3b, v27
	v_exp_f32_e32 v30, v30
	v_exp_f32_e32 v31, v31
	v_add_f32_e32 v30, 1.0, v30
	v_add_f32_e32 v31, 1.0, v31
	v_rcp_f32_e32 v30, v30
	v_rcp_f32_e32 v31, v31
	s_nop 0
	v_pk_mul_f32 v[26:27], v[26:27], v[30:31]
	s_nop 0
	v_pk_mul_f32 v[26:27], v[18:19], v[26:27]
	v_pk_mul_f32 v[18:19], v[28:29], v[36:37] op_sel_hi:[1,0]
	s_nop 0
	v_mul_f32_e32 v28, 0xbfb8aa3b, v18
	v_mul_f32_e32 v29, 0xbfb8aa3b, v19
	v_exp_f32_e32 v28, v28
	v_exp_f32_e32 v29, v29
	v_add_f32_e32 v28, 1.0, v28
	v_add_f32_e32 v29, 1.0, v29
	v_rcp_f32_e32 v28, v28
	v_rcp_f32_e32 v29, v29
	s_nop 0
	v_pk_mul_f32 v[18:19], v[18:19], v[28:29]
	s_nop 0
	v_pk_mul_f32 v[28:29], v[20:21], v[18:19]
	v_cvt_pk_bf16_f32 v18, v22, v23
	v_cvt_pk_bf16_f32 v19, v24, v25
	v_cvt_pk_bf16_f32 v20, v26, v27
	v_cvt_pk_bf16_f32 v21, v28, v29
	v_mad_i64_i32 v[22:23], s[6:7], v34, s4, v[142:143]
	global_store_dwordx4 v[22:23], v[18:21], off
	s_nop 1
	v_add_u32_e32 v18, 0xb0, v144
	v_mov_b32_e32 v20, v165
	v_pk_mul_f32 v[14:15], v[14:15], v[20:21] op_sel_hi:[1,0]
	v_pk_mul_f32 v[6:7], v[6:7], v[20:21] op_sel_hi:[1,0]
	v_mul_f32_e32 v19, 0xbfb8aa3b, v14
	v_exp_f32_e32 v19, v19
	v_pk_mul_f32 v[8:9], v[8:9], v[20:21] op_sel_hi:[1,0]
	v_pk_mul_f32 v[10:11], v[10:11], v[20:21] op_sel_hi:[1,0]
	v_pk_mul_f32 v[2:3], v[2:3], v[20:21] op_sel_hi:[1,0]
	v_add_f32_e32 v19, 1.0, v19
	v_rcp_f32_e32 v22, v19
	v_mul_f32_e32 v19, 0xbfb8aa3b, v15
	v_exp_f32_e32 v19, v19
	v_pk_mul_f32 v[4:5], v[4:5], v[20:21] op_sel_hi:[1,0]
	s_andn2_b64 vcc, exec, s[42:43]
	v_add_f32_e32 v19, 1.0, v19
	v_rcp_f32_e32 v23, v19
	s_nop 0
	v_pk_mul_f32 v[14:15], v[14:15], v[22:23]
	s_nop 0
	v_pk_mul_f32 v[6:7], v[6:7], v[14:15]
	v_pk_mul_f32 v[14:15], v[16:17], v[20:21] op_sel_hi:[1,0]
	s_nop 0
	v_mul_f32_e32 v16, 0xbfb8aa3b, v14
	v_mul_f32_e32 v17, 0xbfb8aa3b, v15
	v_exp_f32_e32 v16, v16
	v_exp_f32_e32 v17, v17
	v_add_f32_e32 v16, 1.0, v16
	v_add_f32_e32 v17, 1.0, v17
	v_rcp_f32_e32 v16, v16
	v_rcp_f32_e32 v17, v17
	s_nop 0
	v_pk_mul_f32 v[14:15], v[14:15], v[16:17]
	s_nop 0
	v_pk_mul_f32 v[8:9], v[8:9], v[14:15]
	v_mul_f32_e32 v14, 0xbfb8aa3b, v10
	v_mul_f32_e32 v15, 0xbfb8aa3b, v11
	v_exp_f32_e32 v14, v14
	v_exp_f32_e32 v15, v15
	v_add_f32_e32 v14, 1.0, v14
	v_add_f32_e32 v15, 1.0, v15
	v_rcp_f32_e32 v14, v14
	v_rcp_f32_e32 v15, v15
	s_nop 0
	v_pk_mul_f32 v[10:11], v[10:11], v[14:15]
	s_nop 0
	v_pk_mul_f32 v[10:11], v[2:3], v[10:11]
	v_pk_mul_f32 v[2:3], v[12:13], v[20:21] op_sel_hi:[1,0]
	s_nop 0
	v_mul_f32_e32 v12, 0xbfb8aa3b, v2
	v_mul_f32_e32 v13, 0xbfb8aa3b, v3
	v_exp_f32_e32 v12, v12
	v_exp_f32_e32 v13, v13
	v_add_f32_e32 v12, 1.0, v12
	v_add_f32_e32 v13, 1.0, v13
	v_rcp_f32_e32 v12, v12
	v_rcp_f32_e32 v13, v13
	s_nop 0
	v_pk_mul_f32 v[2:3], v[2:3], v[12:13]
	s_nop 0
	v_pk_mul_f32 v[12:13], v[4:5], v[2:3]
	v_cvt_pk_bf16_f32 v2, v6, v7
	v_cvt_pk_bf16_f32 v3, v8, v9
	v_cvt_pk_bf16_f32 v4, v10, v11
	v_cvt_pk_bf16_f32 v5, v12, v13
	v_mad_i64_i32 v[6:7], s[6:7], v18, s4, v[142:143]
	global_store_dwordx4 v[6:7], v[2:5], off
	s_cbranch_vccnz .LBB0_1147
	s_andn2_b64 vcc, exec, s[0:1]
	s_cbranch_vccnz .LBB0_1146
	s_barrier
	s_branch .LBB0_1146

; __device__ __forceinline__ float bflo(unsigned u) { return __uint_as_float(u << 16); }
;     __device__ __forceinline__ void operator()(const f32x4 (&acc)[2][2][4][2], const Unit& u, int wr, int wc, int fr, int fq) const {
;     ...
;                 const int row = row0 + ai * HALF + m * 16;
;                 float rs = 0.f; if (GATED) rs = rsqrtf(row_ssq(ssq_in, 16, 4, row, fq) * (1.f / 1024.f) + EPS);
;                 float sq = 0.f;
; #pragma unroll
;                 for (int bj = 0; bj < 2; ++bj) {
;                     const size_t off = (size_t)row * DM + col0 + bj * HALF;
;                     const u32x4 hh = *(const u32x4*)(HI + off), ll = *(const u32x4*)(LO + off);
;                     float hv[8] = {bflo(hh.x) + bflo(ll.x), bfhi(hh.x) + bfhi(ll.x), bflo(hh.y) + bflo(ll.y), bfhi(hh.y) + bfhi(ll.y),
;                                    bflo(hh.z) + bflo(ll.z), bfhi(hh.z) + bfhi(ll.z), bflo(hh.w) + bflo(ll.w), bfhi(hh.w) + bfhi(ll.w)};
;                     float av[8] = {acc[ai][bj][m][0][0], acc[ai][bj][m][0][1], acc[ai][bj][m][0][2], acc[ai][bj][m][0][3], acc[ai][bj][m][1][0], acc[ai][bj][m][1][1], acc[ai][bj][m][1][2], acc[ai][bj][m][1][3]};
;                     if (GATED) { const u32x4 pp = *(const u32x4*)(PP + off);
;                         const float pv[8] = {bflo(pp.x), bfhi(pp.x), bflo(pp.y), bfhi(pp.y), bflo(pp.z), bfhi(pp.z), bflo(pp.w), bfhi(pp.w)};
; #pragma unroll
;                         for (int e = 0; e < 8; ++e) av[e] = fast_sigmoid(av[e] * rs) * pv[e]; }
;                     else {
; #pragma unroll
;                         for (int e = 0; e < 8; ++e) av[e] *= alpha; }
;                     float lo[8];
; #pragma unroll
;                     for (int e = 0; e < 8; ++e) { hv[e] += av[e]; sq += hv[e] * hv[e]; }
;                     u32x4 wh; wh.x = pk2(hv[0], hv[1]); wh.y = pk2(hv[2], hv[3]); wh.z = pk2(hv[4], hv[5]); wh.w = pk2(hv[6], hv[7]);
;                     lo[0] = hv[0] - bflo(wh.x); lo[1] = hv[1] - bfhi(wh.x); lo[2] = hv[2] - bflo(wh.y); lo[3] = hv[3] - bfhi(wh.y);
;                     lo[4] = hv[4] - bflo(wh.z); lo[5] = hv[5] - bfhi(wh.z); lo[6] = hv[6] - bflo(wh.w); lo[7] = hv[7] - bfhi(wh.w);
;                     u32x4 wl; wl.x = pk2(lo[0], lo[1]); wl.y = pk2(lo[2], lo[3]); wl.z = pk2(lo[4], lo[5]); wl.w = pk2(lo[6], lo[7]);
;                     *(u32x4*)(HO + off) = wh; *(u32x4*)(LO + off) = wl;
.LBB0_1340:
	s_or_b64 exec, exec, s[12:13]
	v_or_b32_e32 v120, 16, v144
	v_ashrrev_i32_e32 v121, 31, v120
	v_lshlrev_b64 v[118:119], 6, v[120:121]
	s_waitcnt lgkmcnt(0)
	v_lshl_add_u64 v[114:115], v[136:137], 0, v[118:119]
	global_load_dwordx4 v[114:117], v[114:115], off
	v_readlane_b32 s10, v253, 35
	v_readlane_b32 s11, v253, 36
	v_readlane_b32 s6, v250, 49
	v_readlane_b32 s7, v250, 50
	s_waitcnt vmcnt(0)
	v_mov_b32_e32 v122, v115
	v_mov_b32_e32 v123, v116
	v_mov_b32_e32 v115, v117
	v_pk_add_f32 v[114:115], v[122:123], v[114:115]
	s_nop 0
	v_add_f32_e32 v114, v114, v115
	v_mov_b32_e32 v115, v114
	s_nop 1
	v_permlane16_swap_b32_e32 v114, v115
	s_waitcnt lgkmcnt(0)
	v_add_f32_e32 v114, v114, v115
	v_mov_b32_e32 v115, v114
	s_nop 1
	v_permlane32_swap_b32_e32 v114, v115
	s_waitcnt lgkmcnt(0)
	v_add_f32_e32 v114, v114, v115
	v_fmamk_f32 v114, v114, 0x3a800000, v239
	s_nop 0
	v_rsq_f32_e32 v152, v114
	s_nop 0
	s_nop 0
	v_lshlrev_b64 v[114:115], 10, v[120:121]
	v_lshl_add_u64 v[114:115], v[114:115], 0, v[142:143]
	v_lshlrev_b64 v[120:121], 1, v[114:115]
	v_lshl_add_u64 v[114:115], s[10:11], 0, v[120:121]
	v_lshl_add_u64 v[116:117], s[14:15], 0, v[120:121]
	global_load_dwordx4 v[126:129], v[114:115], off
	global_load_dwordx4 v[160:163], v[116:117], off
	v_lshl_add_u64 v[114:115], s[6:7], 0, v[120:121]
	global_load_dwordx4 v[146:149], v[114:115], off
	v_mul_f32_e32 v106, v106, v152
	v_mul_f32_e32 v106, 0xbfb8aa3b, v106
	v_exp_f32_e32 v106, v106
	v_mul_f32_e32 v110, v110, v152
	v_mul_f32_e32 v111, v111, v152
	v_mul_f32_e32 v110, 0xbfb8aa3b, v110
	v_add_f32_e32 v106, 1.0, v106
	v_rcp_f32_e32 v116, v106
	v_mul_f32_e32 v106, v107, v152
	v_mul_f32_e32 v106, 0xbfb8aa3b, v106
	v_exp_f32_e32 v106, v106
	v_mul_f32_e32 v111, 0xbfb8aa3b, v111
	v_exp_f32_e32 v110, v110
	v_exp_f32_e32 v111, v111
	v_add_f32_e32 v106, 1.0, v106
	v_rcp_f32_e32 v117, v106
	v_mul_f32_e32 v106, v108, v152
	v_mul_f32_e32 v106, 0xbfb8aa3b, v106
	v_exp_f32_e32 v106, v106
	v_mul_f32_e32 v112, v112, v152
	v_mul_f32_e32 v113, v113, v152
	v_add_f32_e32 v110, 1.0, v110
	v_add_f32_e32 v106, 1.0, v106
	v_rcp_f32_e32 v150, v106
	v_mul_f32_e32 v106, v109, v152
	v_mul_f32_e32 v106, 0xbfb8aa3b, v106
	v_exp_f32_e32 v106, v106
	v_add_f32_e32 v111, 1.0, v111
	v_mul_f32_e32 v112, 0xbfb8aa3b, v112
	v_mul_f32_e32 v113, 0xbfb8aa3b, v113
	v_rcp_f32_e32 v110, v110
	v_rcp_f32_e32 v111, v111
	v_exp_f32_e32 v112, v112
	v_exp_f32_e32 v113, v113
	v_add_f32_e32 v106, 1.0, v106
	v_rcp_f32_e32 v151, v106
	v_add_f32_e32 v112, 1.0, v112
	v_add_f32_e32 v113, 1.0, v113
	v_rcp_f32_e32 v112, v112
	v_rcp_f32_e32 v113, v113
	v_mul_f32_e32 v102, v102, v152
	v_mul_f32_e32 v102, 0xbfb8aa3b, v102
	v_exp_f32_e32 v102, v102
	v_mul_f32_e32 v98, v98, v152
	v_mul_f32_e32 v98, 0xbfb8aa3b, v98
	v_exp_f32_e32 v98, v98
	v_add_f32_e32 v102, 1.0, v102
	v_add_f32_e32 v98, 1.0, v98
	s_waitcnt vmcnt(2)
	v_lshlrev_b32_e32 v106, 16, v126
	v_and_b32_e32 v107, 0xffff0000, v126
	s_waitcnt vmcnt(0)
	v_lshlrev_b32_e32 v108, 16, v146
	v_and_b32_e32 v109, 0xffff0000, v146
	v_pk_add_f32 v[106:107], v[106:107], v[108:109]
	v_lshlrev_b32_e32 v108, 16, v160
	v_and_b32_e32 v109, 0xffff0000, v160
	v_pk_fma_f32 v[108:109], v[110:111], v[108:109], v[106:107]
	v_lshlrev_b32_e32 v124, 16, v147
	v_cvt_pk_bf16_f32 v106, v108, v109
	v_lshlrev_b32_e32 v110, 16, v106
	v_and_b32_e32 v111, 0xffff0000, v106
	v_pk_mul_f32 v[122:123], v[108:109], v[108:109]
	v_pk_add_f32 v[110:111], v[108:109], v[110:111] neg_lo:[0,1] neg_hi:[0,1]
	v_lshlrev_b32_e32 v108, 16, v127
	v_and_b32_e32 v109, 0xffff0000, v127
	v_and_b32_e32 v125, 0xffff0000, v147
	v_pk_add_f32 v[108:109], v[108:109], v[124:125]
	v_lshlrev_b32_e32 v124, 16, v161
	v_and_b32_e32 v125, 0xffff0000, v161
	v_pk_fma_f32 v[108:109], v[112:113], v[124:125], v[108:109]
	v_lshlrev_b32_e32 v126, 16, v148
	v_cvt_pk_bf16_f32 v107, v108, v109
	v_lshlrev_b32_e32 v112, 16, v107
	v_and_b32_e32 v113, 0xffff0000, v107
	v_pk_mul_f32 v[124:125], v[108:109], v[108:109]
	v_pk_add_f32 v[112:113], v[108:109], v[112:113] neg_lo:[0,1] neg_hi:[0,1]
	v_lshlrev_b32_e32 v108, 16, v128
	v_and_b32_e32 v109, 0xffff0000, v128
	v_and_b32_e32 v127, 0xffff0000, v148
	v_pk_add_f32 v[108:109], v[108:109], v[126:127]
	v_lshlrev_b32_e32 v126, 16, v162
	v_and_b32_e32 v127, 0xffff0000, v162
	v_pk_fma_f32 v[116:117], v[116:117], v[126:127], v[108:109]
	v_lshlrev_b32_e32 v128, 16, v129
	v_cvt_pk_bf16_f32 v108, v116, v117
	v_lshlrev_b32_e32 v146, 16, v108
	v_and_b32_e32 v147, 0xffff0000, v108
	v_pk_mul_f32 v[126:127], v[116:117], v[116:117]
	v_pk_add_f32 v[116:117], v[116:117], v[146:147] neg_lo:[0,1] neg_hi:[0,1]
	v_and_b32_e32 v129, 0xffff0000, v129
	v_lshlrev_b32_e32 v146, 16, v149
	v_and_b32_e32 v147, 0xffff0000, v149
	v_pk_add_f32 v[128:129], v[128:129], v[146:147]
	v_lshlrev_b32_e32 v146, 16, v163
	v_and_b32_e32 v147, 0xffff0000, v163
	v_pk_fma_f32 v[146:147], v[150:151], v[146:147], v[128:129]
	v_cvt_pk_bf16_f32 v110, v110, v111
	v_cvt_pk_bf16_f32 v109, v146, v147
	v_lshlrev_b32_e32 v148, 16, v109
	v_and_b32_e32 v149, 0xffff0000, v109
	v_pk_mul_f32 v[128:129], v[146:147], v[146:147]
	v_pk_add_f32 v[146:147], v[146:147], v[148:149] neg_lo:[0,1] neg_hi:[0,1]
	v_cvt_pk_bf16_f32 v111, v112, v113
	v_cvt_pk_bf16_f32 v112, v116, v117
	v_lshl_add_u64 v[116:117], s[58:59], 0, v[120:121]
	v_or_b32_e32 v120, 0x100, v120
	v_cvt_pk_bf16_f32 v113, v146, v147
	global_store_dwordx4 v[116:117], v[106:109], off
	global_store_dwordx4 v[114:115], v[110:113], off
	v_lshl_add_u64 v[146:147], s[6:7], 0, v[120:121]
	v_lshl_add_u64 v[106:107], s[10:11], 0, v[120:121]
	global_load_dwordx4 v[106:109], v[106:107], off
	v_lshl_add_u64 v[114:115], s[14:15], 0, v[120:121]
	global_load_dwordx4 v[110:113], v[146:147], off
	v_rcp_f32_e32 v150, v102
	global_load_dwordx4 v[114:117], v[114:115], off
	v_mul_f32_e32 v102, v103, v152
	v_mul_f32_e32 v102, 0xbfb8aa3b, v102
	v_exp_f32_e32 v102, v102
	s_nop 0
	v_add_f32_e32 v102, 1.0, v102
	v_rcp_f32_e32 v151, v102
	v_mul_f32_e32 v102, v104, v152
	v_rcp_f32_e32 v104, v98
	v_mul_f32_e32 v98, v99, v152
	v_mul_f32_e32 v102, 0xbfb8aa3b, v102
	v_mul_f32_e32 v98, 0xbfb8aa3b, v98
	v_exp_f32_e32 v102, v102
	v_exp_f32_e32 v98, v98
	v_add_f32_e32 v102, 1.0, v102
	v_add_f32_e32 v98, 1.0, v98
	v_rcp_f32_e32 v148, v102
	v_mul_f32_e32 v102, v105, v152
	v_rcp_f32_e32 v105, v98
	v_mul_f32_e32 v98, v100, v152
	v_mul_f32_e32 v102, 0xbfb8aa3b, v102
	v_mul_f32_e32 v98, 0xbfb8aa3b, v98
	v_exp_f32_e32 v102, v102
	v_exp_f32_e32 v98, v98
	v_add_f32_e32 v102, 1.0, v102
	v_add_f32_e32 v98, 1.0, v98
	v_rcp_f32_e32 v149, v102
	v_rcp_f32_e32 v102, v98
	v_mul_f32_e32 v98, v101, v152
	v_mul_f32_e32 v98, 0xbfb8aa3b, v98
	v_exp_f32_e32 v98, v98
	s_waitcnt vmcnt(2)
;     __device__ __forceinline__ void operator()(const f32x4 (&acc)[2][2][4][2], const Unit& u, int wr, int wc, int fr, int fq) const {
;     ...
;                 const int row = row0 + ai * HALF + m * 16;
;                 float rs = 0.f; if (GATED) rs = rsqrtf(row_ssq(ssq_in, 16, 4, row, fq) * (1.f / 1024.f) + EPS);
;                 float sq = 0.f;
; #pragma unroll
;                 for (int bj = 0; bj < 2; ++bj) {
;                     const size_t off = (size_t)row * DM + col0 + bj * HALF;
;                     const u32x4 hh = *(const u32x4*)(HI + off), ll = *(const u32x4*)(LO + off);
;                     float hv[8] = {bflo(hh.x) + bflo(ll.x), bfhi(hh.x) + bfhi(ll.x), bflo(hh.y) + bflo(ll.y), bfhi(hh.y) + bfhi(ll.y),
;                                    bflo(hh.z) + bflo(ll.z), bfhi(hh.z) + bfhi(ll.z), bflo(hh.w) + bflo(ll.w), bfhi(hh.w) + bfhi(ll.w)};
;                     float av[8] = {acc[ai][bj][m][0][0], acc[ai][bj][m][0][1], acc[ai][bj][m][0][2], acc[ai][bj][m][0][3], acc[ai][bj][m][1][0], acc[ai][bj][m][1][1], acc[ai][bj][m][1][2], acc[ai][bj][m][1][3]};
;                     if (GATED) { const u32x4 pp = *(const u32x4*)(PP + off);
;                         const float pv[8] = {bflo(pp.x), bfhi(pp.x), bflo(pp.y), bfhi(pp.y), bflo(pp.z), bfhi(pp.z), bflo(pp.w), bfhi(pp.w)};
; #pragma unroll
;                         for (int e = 0; e < 8; ++e) av[e] = fast_sigmoid(av[e] * rs) * pv[e]; }
;                     else {
; #pragma unroll
;                         for (int e = 0; e < 8; ++e) av[e] *= alpha; }
;                     float lo[8];
; #pragma unroll
;                     for (int e = 0; e < 8; ++e) { hv[e] += av[e]; sq += hv[e] * hv[e]; }
;                     u32x4 wh; wh.x = pk2(hv[0], hv[1]); wh.y = pk2(hv[2], hv[3]); wh.z = pk2(hv[4], hv[5]); wh.w = pk2(hv[6], hv[7]);
;                     lo[0] = hv[0] - bflo(wh.x); lo[1] = hv[1] - bfhi(wh.x); lo[2] = hv[2] - bflo(wh.y); lo[3] = hv[3] - bfhi(wh.y);
;                     lo[4] = hv[4] - bflo(wh.z); lo[5] = hv[5] - bfhi(wh.z); lo[6] = hv[6] - bflo(wh.w); lo[7] = hv[7] - bfhi(wh.w);
;                     u32x4 wl; wl.x = pk2(lo[0], lo[1]); wl.y = pk2(lo[2], lo[3]); wl.z = pk2(lo[4], lo[5]); wl.w = pk2(lo[6], lo[7]);
;                     *(u32x4*)(HO + off) = wh; *(u32x4*)(LO + off) = wl;
;                 }
;                 sq += __shfl_xor(sq, 16); sq += __shfl_xor(sq, 32);
	v_and_b32_e32 v99, 0xffff0000, v106
	v_add_f32_e32 v98, 1.0, v98
	v_rcp_f32_e32 v103, v98
	v_lshlrev_b32_e32 v98, 16, v106
	s_waitcnt vmcnt(1)
	v_lshlrev_b32_e32 v100, 16, v110
	v_and_b32_e32 v101, 0xffff0000, v110
	v_pk_add_f32 v[98:99], v[98:99], v[100:101]
	s_waitcnt vmcnt(0)
	v_lshlrev_b32_e32 v100, 16, v114
	v_and_b32_e32 v101, 0xffff0000, v114
	v_pk_fma_f32 v[100:101], v[150:151], v[100:101], v[98:99]
	v_lshlrev_b32_e32 v106, 16, v111
	v_cvt_pk_bf16_f32 v98, v100, v101
	v_lshlrev_b32_e32 v150, 16, v98
	v_and_b32_e32 v151, 0xffff0000, v98
	v_pk_mul_f32 v[152:153], v[100:101], v[100:101]
	v_pk_add_f32 v[150:151], v[100:101], v[150:151] neg_lo:[0,1] neg_hi:[0,1]
	v_lshlrev_b32_e32 v100, 16, v107
	v_and_b32_e32 v101, 0xffff0000, v107
	v_and_b32_e32 v107, 0xffff0000, v111
	v_pk_add_f32 v[100:101], v[100:101], v[106:107]
	v_lshlrev_b32_e32 v106, 16, v115
	v_and_b32_e32 v107, 0xffff0000, v115
	v_pk_fma_f32 v[100:101], v[148:149], v[106:107], v[100:101]
	v_lshlrev_b32_e32 v114, 16, v112
	v_cvt_pk_bf16_f32 v99, v100, v101
	v_lshlrev_b32_e32 v110, 16, v99
	v_and_b32_e32 v111, 0xffff0000, v99
	v_pk_mul_f32 v[106:107], v[100:101], v[100:101]
	v_pk_add_f32 v[110:111], v[100:101], v[110:111] neg_lo:[0,1] neg_hi:[0,1]
	v_lshlrev_b32_e32 v100, 16, v108
	v_and_b32_e32 v101, 0xffff0000, v108
	v_and_b32_e32 v115, 0xffff0000, v112
	v_pk_add_f32 v[100:101], v[100:101], v[114:115]
	v_lshlrev_b32_e32 v114, 16, v116
	v_and_b32_e32 v115, 0xffff0000, v116
	v_pk_fma_f32 v[104:105], v[104:105], v[114:115], v[100:101]
	v_add_f32_e32 v101, v122, v123
	v_add_f32_e32 v101, v124, v101
	v_add_f32_e32 v101, v125, v101
	v_add_f32_e32 v101, v126, v101
	v_add_f32_e32 v101, v127, v101
	v_add_f32_e32 v101, v128, v101
	v_add_f32_e32 v101, v129, v101
	v_add_f32_e32 v101, v152, v101
	v_add_f32_e32 v101, v153, v101
	v_lshlrev_b32_e32 v108, 16, v109
	v_and_b32_e32 v109, 0xffff0000, v109
	v_lshlrev_b32_e32 v112, 16, v113
	v_and_b32_e32 v113, 0xffff0000, v113
	v_add_f32_e32 v101, v106, v101
	v_pk_mul_f32 v[114:115], v[104:105], v[104:105]
	v_pk_add_f32 v[108:109], v[108:109], v[112:113]
	v_lshlrev_b32_e32 v112, 16, v117
	v_and_b32_e32 v113, 0xffff0000, v117
	v_add_f32_e32 v101, v107, v101
	v_pk_fma_f32 v[102:103], v[102:103], v[112:113], v[108:109]
	v_add_f32_e32 v101, v114, v101
	v_pk_mul_f32 v[108:109], v[102:103], v[102:103]
	v_add_f32_e32 v101, v115, v101
	v_add_f32_e32 v101, v108, v101
	v_cvt_pk_bf16_f32 v100, v104, v105
	v_add_f32_e32 v108, v109, v101
	v_cvt_pk_bf16_f32 v101, v102, v103
	v_lshlrev_b32_e32 v148, 16, v100
	v_and_b32_e32 v149, 0xffff0000, v100
	v_lshlrev_b32_e32 v106, 16, v101
	v_and_b32_e32 v107, 0xffff0000, v101
	v_pk_add_f32 v[104:105], v[104:105], v[148:149] neg_lo:[0,1] neg_hi:[0,1]
	v_pk_add_f32 v[106:107], v[102:103], v[106:107] neg_lo:[0,1] neg_hi:[0,1]
	v_cvt_pk_bf16_f32 v104, v104, v105
	v_cvt_pk_bf16_f32 v105, v106, v107
	v_lshl_add_u64 v[106:107], s[58:59], 0, v[120:121]
	v_cvt_pk_bf16_f32 v102, v150, v151
	v_cvt_pk_bf16_f32 v103, v110, v111
	global_store_dwordx4 v[106:107], v[98:101], off
	global_store_dwordx4 v[146:147], v[102:105], off
	v_mov_b32_e32 v98, v108
	s_nop 1
	v_permlane16_swap_b32_e32 v108, v98
	s_waitcnt lgkmcnt(0)
	v_add_f32_e32 v98, v108, v98
	ds_bpermute_b32 v99, v145, v98
	s_and_saveexec_b64 s[12:13], s[0:1]
	s_cbranch_execz .LBB0_1342
	v_readlane_b32 s44, v250, 8
	v_readlane_b32 s46, v250, 10
	v_readlane_b32 s47, v250, 11
	s_waitcnt lgkmcnt(0)
	v_add_f32_e32 v100, v98, v99
	s_lshl_b32 s40, s25, 2
	v_lshl_add_u64 v[98:99], s[46:47], 0, v[118:119]
	v_lshl_add_u64 v[98:99], s[54:55], 2, v[98:99]
	v_lshl_add_u64 v[98:99], v[98:99], 0, s[40:41]
	v_readlane_b32 s45, v250, 9
	global_store_dword v[98:99], v100, off
.LBB0_1342:
	s_or_b64 exec, exec, s[12:13]
	v_or_b32_e32 v104, 32, v144
	v_ashrrev_i32_e32 v105, 31, v104
	v_lshlrev_b64 v[102:103], 6, v[104:105]
	s_waitcnt lgkmcnt(0)
	v_lshl_add_u64 v[98:99], v[136:137], 0, v[102:103]
	global_load_dwordx4 v[98:101], v[98:99], off
	v_readlane_b32 s10, v253, 35
	v_readlane_b32 s11, v253, 36
	v_readlane_b32 s6, v250, 49
	v_readlane_b32 s7, v250, 50
	s_waitcnt vmcnt(0)
	v_mov_b32_e32 v106, v99
	v_mov_b32_e32 v107, v100
	v_mov_b32_e32 v99, v101
	v_pk_add_f32 v[98:99], v[106:107], v[98:99]
	s_nop 0
	v_add_f32_e32 v98, v98, v99
	v_mov_b32_e32 v99, v98
	s_nop 1
	v_permlane16_swap_b32_e32 v98, v99
	s_waitcnt lgkmcnt(0)
	v_add_f32_e32 v98, v98, v99
	v_mov_b32_e32 v99, v98
	s_nop 1
	v_permlane32_swap_b32_e32 v98, v99
	s_waitcnt lgkmcnt(0)
	v_add_f32_e32 v98, v98, v99
	v_fmamk_f32 v98, v98, 0x3a800000, v239
	s_nop 0
	v_rsq_f32_e32 v120, v98
	s_nop 0
	s_nop 0
	v_lshlrev_b64 v[98:99], 10, v[104:105]
	v_lshl_add_u64 v[98:99], v[98:99], 0, v[142:143]
	v_lshlrev_b64 v[104:105], 1, v[98:99]
	v_lshl_add_u64 v[98:99], s[10:11], 0, v[104:105]
	v_lshl_add_u64 v[100:101], s[14:15], 0, v[104:105]
	global_load_dwordx4 v[110:113], v[98:99], off
	global_load_dwordx4 v[122:125], v[100:101], off
	v_lshl_add_u64 v[98:99], s[6:7], 0, v[104:105]
	global_load_dwordx4 v[114:117], v[98:99], off
	v_mul_f32_e32 v90, v90, v120
	v_mul_f32_e32 v90, 0xbfb8aa3b, v90
	v_exp_f32_e32 v90, v90
	v_mul_f32_e32 v94, v94, v120
	v_mul_f32_e32 v95, v95, v120
	v_mul_f32_e32 v94, 0xbfb8aa3b, v94
	v_add_f32_e32 v90, 1.0, v90
	v_rcp_f32_e32 v100, v90
	v_mul_f32_e32 v90, v91, v120
	v_mul_f32_e32 v90, 0xbfb8aa3b, v90
	v_exp_f32_e32 v90, v90
	v_mul_f32_e32 v95, 0xbfb8aa3b, v95
	v_exp_f32_e32 v94, v94
	v_exp_f32_e32 v95, v95
	v_add_f32_e32 v90, 1.0, v90
	v_rcp_f32_e32 v101, v90
	v_mul_f32_e32 v90, v92, v120
	v_mul_f32_e32 v90, 0xbfb8aa3b, v90
	v_exp_f32_e32 v90, v90
	v_mul_f32_e32 v96, v96, v120
	v_mul_f32_e32 v97, v97, v120
	v_add_f32_e32 v94, 1.0, v94
	v_add_f32_e32 v90, 1.0, v90
	v_rcp_f32_e32 v118, v90
	v_mul_f32_e32 v90, v93, v120
	v_mul_f32_e32 v90, 0xbfb8aa3b, v90
	v_exp_f32_e32 v90, v90
	v_add_f32_e32 v95, 1.0, v95
	v_mul_f32_e32 v96, 0xbfb8aa3b, v96
	v_mul_f32_e32 v97, 0xbfb8aa3b, v97
	v_rcp_f32_e32 v94, v94
	v_rcp_f32_e32 v95, v95
	v_exp_f32_e32 v96, v96
	v_exp_f32_e32 v97, v97
	v_add_f32_e32 v90, 1.0, v90
	v_rcp_f32_e32 v119, v90
	v_add_f32_e32 v96, 1.0, v96
	v_add_f32_e32 v97, 1.0, v97
	v_rcp_f32_e32 v96, v96
	v_rcp_f32_e32 v97, v97
	v_mul_f32_e32 v86, v86, v120
	v_mul_f32_e32 v86, 0xbfb8aa3b, v86
	v_exp_f32_e32 v86, v86
	v_mul_f32_e32 v82, v82, v120
	v_mul_f32_e32 v82, 0xbfb8aa3b, v82
	v_exp_f32_e32 v82, v82
	v_add_f32_e32 v86, 1.0, v86
	v_add_f32_e32 v82, 1.0, v82
	s_waitcnt vmcnt(2)
; __device__ __forceinline__ float bflo(unsigned u) { return __uint_as_float(u << 16); }
;     __device__ __forceinline__ void operator()(const f32x4 (&acc)[2][2][4][2], const Unit& u, int wr, int wc, int fr, int fq) const {
;     ...
;                 for (int bj = 0; bj < 2; ++bj) {
;                     const size_t off = (size_t)row * DM + col0 + bj * HALF;
;                     const u32x4 hh = *(const u32x4*)(HI + off), ll = *(const u32x4*)(LO + off);
;                     float hv[8] = {bflo(hh.x) + bflo(ll.x), bfhi(hh.x) + bfhi(ll.x), bflo(hh.y) + bflo(ll.y), bfhi(hh.y) + bfhi(ll.y),
;                                    bflo(hh.z) + bflo(ll.z), bfhi(hh.z) + bfhi(ll.z), bflo(hh.w) + bflo(ll.w), bfhi(hh.w) + bfhi(ll.w)};
;                     float av[8] = {acc[ai][bj][m][0][0], acc[ai][bj][m][0][1], acc[ai][bj][m][0][2], acc[ai][bj][m][0][3], acc[ai][bj][m][1][0], acc[ai][bj][m][1][1], acc[ai][bj][m][1][2], acc[ai][bj][m][1][3]};
;                     if (GATED) { const u32x4 pp = *(const u32x4*)(PP + off);
;                         const float pv[8] = {bflo(pp.x), bfhi(pp.x), bflo(pp.y), bfhi(pp.y), bflo(pp.z), bfhi(pp.z), bflo(pp.w), bfhi(pp.w)};
; #pragma unroll
;                         for (int e = 0; e < 8; ++e) av[e] = fast_sigmoid(av[e] * rs) * pv[e]; }
;                     else {
; #pragma unroll
;                         for (int e = 0; e < 8; ++e) av[e] *= alpha; }
;                     float lo[8];
; #pragma unroll
;                     for (int e = 0; e < 8; ++e) { hv[e] += av[e]; sq += hv[e] * hv[e]; }
;                     u32x4 wh; wh.x = pk2(hv[0], hv[1]); wh.y = pk2(hv[2], hv[3]); wh.z = pk2(hv[4], hv[5]); wh.w = pk2(hv[6], hv[7]);
;                     lo[0] = hv[0] - bflo(wh.x); lo[1] = hv[1] - bfhi(wh.x); lo[2] = hv[2] - bflo(wh.y); lo[3] = hv[3] - bfhi(wh.y);
;                     lo[4] = hv[4] - bflo(wh.z); lo[5] = hv[5] - bfhi(wh.z); lo[6] = hv[6] - bflo(wh.w); lo[7] = hv[7] - bfhi(wh.w);
;                     u32x4 wl; wl.x = pk2(lo[0], lo[1]); wl.y = pk2(lo[2], lo[3]); wl.z = pk2(lo[4], lo[5]); wl.w = pk2(lo[6], lo[7]);
;                     *(u32x4*)(HO + off) = wh; *(u32x4*)(LO + off) = wl;
;                 }
;                 sq += __shfl_xor(sq, 16); sq += __shfl_xor(sq, 32);
;                 if (fq == 0) ssq_out[(size_t)row * 16 + 4 * u.pn + wc] = sq;
	v_lshlrev_b32_e32 v90, 16, v110
	v_and_b32_e32 v91, 0xffff0000, v110
	s_waitcnt vmcnt(0)
	v_lshlrev_b32_e32 v92, 16, v114
	v_and_b32_e32 v93, 0xffff0000, v114
	v_pk_add_f32 v[90:91], v[90:91], v[92:93]
	v_lshlrev_b32_e32 v92, 16, v122
	v_and_b32_e32 v93, 0xffff0000, v122
	v_pk_fma_f32 v[92:93], v[94:95], v[92:93], v[90:91]
	v_lshlrev_b32_e32 v108, 16, v115
	v_cvt_pk_bf16_f32 v90, v92, v93
	v_lshlrev_b32_e32 v94, 16, v90
	v_and_b32_e32 v95, 0xffff0000, v90
	v_pk_mul_f32 v[106:107], v[92:93], v[92:93]
	v_pk_add_f32 v[94:95], v[92:93], v[94:95] neg_lo:[0,1] neg_hi:[0,1]
	v_lshlrev_b32_e32 v92, 16, v111
	v_and_b32_e32 v93, 0xffff0000, v111
	v_and_b32_e32 v109, 0xffff0000, v115
	v_pk_add_f32 v[92:93], v[92:93], v[108:109]
	v_lshlrev_b32_e32 v108, 16, v123
	v_and_b32_e32 v109, 0xffff0000, v123
	v_pk_fma_f32 v[92:93], v[96:97], v[108:109], v[92:93]
	v_lshlrev_b32_e32 v110, 16, v116
	v_cvt_pk_bf16_f32 v91, v92, v93
	v_lshlrev_b32_e32 v96, 16, v91
	v_and_b32_e32 v97, 0xffff0000, v91
	v_pk_mul_f32 v[108:109], v[92:93], v[92:93]
	v_pk_add_f32 v[96:97], v[92:93], v[96:97] neg_lo:[0,1] neg_hi:[0,1]
	v_lshlrev_b32_e32 v92, 16, v112
	v_and_b32_e32 v93, 0xffff0000, v112
	v_and_b32_e32 v111, 0xffff0000, v116
	v_pk_add_f32 v[92:93], v[92:93], v[110:111]
	v_lshlrev_b32_e32 v110, 16, v124
	v_and_b32_e32 v111, 0xffff0000, v124
	v_pk_fma_f32 v[100:101], v[100:101], v[110:111], v[92:93]
	v_lshlrev_b32_e32 v112, 16, v113
	v_cvt_pk_bf16_f32 v92, v100, v101
	v_lshlrev_b32_e32 v114, 16, v92
	v_and_b32_e32 v115, 0xffff0000, v92
	v_pk_mul_f32 v[110:111], v[100:101], v[100:101]
	v_pk_add_f32 v[100:101], v[100:101], v[114:115] neg_lo:[0,1] neg_hi:[0,1]
	v_and_b32_e32 v113, 0xffff0000, v113
	v_lshlrev_b32_e32 v114, 16, v117
	v_and_b32_e32 v115, 0xffff0000, v117
	v_pk_add_f32 v[112:113], v[112:113], v[114:115]
	v_lshlrev_b32_e32 v114, 16, v125
	v_and_b32_e32 v115, 0xffff0000, v125
	v_pk_fma_f32 v[114:115], v[118:119], v[114:115], v[112:113]
	v_cvt_pk_bf16_f32 v94, v94, v95
	v_cvt_pk_bf16_f32 v93, v114, v115
	v_lshlrev_b32_e32 v116, 16, v93
	v_and_b32_e32 v117, 0xffff0000, v93
	v_pk_mul_f32 v[112:113], v[114:115], v[114:115]
	v_pk_add_f32 v[114:115], v[114:115], v[116:117] neg_lo:[0,1] neg_hi:[0,1]
	v_cvt_pk_bf16_f32 v95, v96, v97
	v_cvt_pk_bf16_f32 v96, v100, v101
	v_lshl_add_u64 v[100:101], s[58:59], 0, v[104:105]
	v_or_b32_e32 v104, 0x100, v104
	v_cvt_pk_bf16_f32 v97, v114, v115
	global_store_dwordx4 v[100:101], v[90:93], off
	global_store_dwordx4 v[98:99], v[94:97], off
	v_lshl_add_u64 v[114:115], s[6:7], 0, v[104:105]
	v_lshl_add_u64 v[90:91], s[10:11], 0, v[104:105]
	global_load_dwordx4 v[90:93], v[90:91], off
	v_lshl_add_u64 v[98:99], s[14:15], 0, v[104:105]
	global_load_dwordx4 v[94:97], v[114:115], off
	v_rcp_f32_e32 v118, v86
	global_load_dwordx4 v[98:101], v[98:99], off
	v_mul_f32_e32 v86, v87, v120
	v_mul_f32_e32 v86, 0xbfb8aa3b, v86
	v_exp_f32_e32 v86, v86
	s_nop 0
	v_add_f32_e32 v86, 1.0, v86
	v_rcp_f32_e32 v119, v86
	v_mul_f32_e32 v86, v88, v120
	v_rcp_f32_e32 v88, v82
	v_mul_f32_e32 v82, v83, v120
	v_mul_f32_e32 v86, 0xbfb8aa3b, v86
	v_mul_f32_e32 v82, 0xbfb8aa3b, v82
	v_exp_f32_e32 v86, v86
	v_exp_f32_e32 v82, v82
	v_add_f32_e32 v86, 1.0, v86
	v_add_f32_e32 v82, 1.0, v82
	v_rcp_f32_e32 v116, v86
	v_mul_f32_e32 v86, v89, v120
	v_rcp_f32_e32 v89, v82
	v_mul_f32_e32 v82, v84, v120
	v_mul_f32_e32 v86, 0xbfb8aa3b, v86
	v_mul_f32_e32 v82, 0xbfb8aa3b, v82
	v_exp_f32_e32 v86, v86
	v_exp_f32_e32 v82, v82
	v_add_f32_e32 v86, 1.0, v86
	v_add_f32_e32 v82, 1.0, v82
	v_rcp_f32_e32 v117, v86
	v_rcp_f32_e32 v86, v82
	v_mul_f32_e32 v82, v85, v120
	v_mul_f32_e32 v82, 0xbfb8aa3b, v82
	v_exp_f32_e32 v82, v82
	s_waitcnt vmcnt(2)
	v_and_b32_e32 v83, 0xffff0000, v90
	v_add_f32_e32 v82, 1.0, v82
	v_rcp_f32_e32 v87, v82
	v_lshlrev_b32_e32 v82, 16, v90
	s_waitcnt vmcnt(1)
	v_lshlrev_b32_e32 v84, 16, v94
	v_and_b32_e32 v85, 0xffff0000, v94
	v_pk_add_f32 v[82:83], v[82:83], v[84:85]
	s_waitcnt vmcnt(0)
	v_lshlrev_b32_e32 v84, 16, v98
	v_and_b32_e32 v85, 0xffff0000, v98
	v_pk_fma_f32 v[84:85], v[118:119], v[84:85], v[82:83]
	v_lshlrev_b32_e32 v90, 16, v95
	v_cvt_pk_bf16_f32 v82, v84, v85
	v_lshlrev_b32_e32 v118, 16, v82
	v_and_b32_e32 v119, 0xffff0000, v82
	v_pk_mul_f32 v[120:121], v[84:85], v[84:85]
	v_pk_add_f32 v[118:119], v[84:85], v[118:119] neg_lo:[0,1] neg_hi:[0,1]
	v_lshlrev_b32_e32 v84, 16, v91
	v_and_b32_e32 v85, 0xffff0000, v91
	v_and_b32_e32 v91, 0xffff0000, v95
	v_pk_add_f32 v[84:85], v[84:85], v[90:91]
	v_lshlrev_b32_e32 v90, 16, v99
	v_and_b32_e32 v91, 0xffff0000, v99
	v_pk_fma_f32 v[84:85], v[116:117], v[90:91], v[84:85]
	v_lshlrev_b32_e32 v98, 16, v96
	v_cvt_pk_bf16_f32 v83, v84, v85
	v_lshlrev_b32_e32 v94, 16, v83
	v_and_b32_e32 v95, 0xffff0000, v83
	v_pk_mul_f32 v[90:91], v[84:85], v[84:85]
	v_pk_add_f32 v[94:95], v[84:85], v[94:95] neg_lo:[0,1] neg_hi:[0,1]
	v_lshlrev_b32_e32 v84, 16, v92
	v_and_b32_e32 v85, 0xffff0000, v92
	v_and_b32_e32 v99, 0xffff0000, v96
	v_pk_add_f32 v[84:85], v[84:85], v[98:99]
	v_lshlrev_b32_e32 v98, 16, v100
	v_and_b32_e32 v99, 0xffff0000, v100
	v_pk_fma_f32 v[88:89], v[88:89], v[98:99], v[84:85]
	v_add_f32_e32 v85, v106, v107
	v_add_f32_e32 v85, v108, v85
	v_add_f32_e32 v85, v109, v85
	v_add_f32_e32 v85, v110, v85
	v_add_f32_e32 v85, v111, v85
	v_add_f32_e32 v85, v112, v85
	v_add_f32_e32 v85, v113, v85
	v_add_f32_e32 v85, v120, v85
	v_add_f32_e32 v85, v121, v85
	v_lshlrev_b32_e32 v92, 16, v93
	v_and_b32_e32 v93, 0xffff0000, v93
	v_lshlrev_b32_e32 v96, 16, v97
	v_and_b32_e32 v97, 0xffff0000, v97
	v_add_f32_e32 v85, v90, v85
	v_pk_mul_f32 v[98:99], v[88:89], v[88:89]
	v_pk_add_f32 v[92:93], v[92:93], v[96:97]
	v_lshlrev_b32_e32 v96, 16, v101
	v_and_b32_e32 v97, 0xffff0000, v101
	v_add_f32_e32 v85, v91, v85
	v_pk_fma_f32 v[86:87], v[86:87], v[96:97], v[92:93]
	v_add_f32_e32 v85, v98, v85
	v_pk_mul_f32 v[92:93], v[86:87], v[86:87]
	v_add_f32_e32 v85, v99, v85
	v_add_f32_e32 v85, v92, v85
	v_cvt_pk_bf16_f32 v84, v88, v89
	v_add_f32_e32 v92, v93, v85
	v_cvt_pk_bf16_f32 v85, v86, v87
	v_lshlrev_b32_e32 v116, 16, v84
	v_and_b32_e32 v117, 0xffff0000, v84
	v_lshlrev_b32_e32 v90, 16, v85
	v_and_b32_e32 v91, 0xffff0000, v85
	v_pk_add_f32 v[88:89], v[88:89], v[116:117] neg_lo:[0,1] neg_hi:[0,1]
	v_pk_add_f32 v[90:91], v[86:87], v[90:91] neg_lo:[0,1] neg_hi:[0,1]
	v_cvt_pk_bf16_f32 v88, v88, v89
	v_cvt_pk_bf16_f32 v89, v90, v91
	v_lshl_add_u64 v[90:91], s[58:59], 0, v[104:105]
	v_cvt_pk_bf16_f32 v86, v118, v119
	v_cvt_pk_bf16_f32 v87, v94, v95
	global_store_dwordx4 v[90:91], v[82:85], off
	global_store_dwordx4 v[114:115], v[86:89], off
	v_mov_b32_e32 v82, v92
	s_nop 1
	v_permlane16_swap_b32_e32 v92, v82
	s_waitcnt lgkmcnt(0)
	v_add_f32_e32 v82, v92, v82
	ds_bpermute_b32 v83, v145, v82
	s_and_saveexec_b64 s[12:13], s[0:1]
	s_cbranch_execz .LBB0_1344
; __device__ __forceinline__ float bflo(unsigned u) { return __uint_as_float(u << 16); }
;     __device__ __forceinline__ void operator()(const f32x4 (&acc)[2][2][4][2], const Unit& u, int wr, int wc, int fr, int fq) const {
;     ...
;                 const int row = row0 + ai * HALF + m * 16;
;                 float rs = 0.f; if (GATED) rs = rsqrtf(row_ssq(ssq_in, 16, 4, row, fq) * (1.f / 1024.f) + EPS);
;                 float sq = 0.f;
; #pragma unroll
;                 for (int bj = 0; bj < 2; ++bj) {
;                     const size_t off = (size_t)row * DM + col0 + bj * HALF;
;                     const u32x4 hh = *(const u32x4*)(HI + off), ll = *(const u32x4*)(LO + off);
;                     float hv[8] = {bflo(hh.x) + bflo(ll.x), bfhi(hh.x) + bfhi(ll.x), bflo(hh.y) + bflo(ll.y), bfhi(hh.y) + bfhi(ll.y),
;                                    bflo(hh.z) + bflo(ll.z), bfhi(hh.z) + bfhi(ll.z), bflo(hh.w) + bflo(ll.w), bfhi(hh.w) + bfhi(ll.w)};
;                     float av[8] = {acc[ai][bj][m][0][0], acc[ai][bj][m][0][1], acc[ai][bj][m][0][2], acc[ai][bj][m][0][3], acc[ai][bj][m][1][0], acc[ai][bj][m][1][1], acc[ai][bj][m][1][2], acc[ai][bj][m][1][3]};
;                     if (GATED) { const u32x4 pp = *(const u32x4*)(PP + off);
;                         const float pv[8] = {bflo(pp.x), bfhi(pp.x), bflo(pp.y), bfhi(pp.y), bflo(pp.z), bfhi(pp.z), bflo(pp.w), bfhi(pp.w)};
; #pragma unroll
;                         for (int e = 0; e < 8; ++e) av[e] = fast_sigmoid(av[e] * rs) * pv[e]; }
;                     else {
; #pragma unroll
;                         for (int e = 0; e < 8; ++e) av[e] *= alpha; }
;                     float lo[8];
; #pragma unroll
;                     for (int e = 0; e < 8; ++e) { hv[e] += av[e]; sq += hv[e] * hv[e]; }
;                     u32x4 wh; wh.x = pk2(hv[0], hv[1]); wh.y = pk2(hv[2], hv[3]); wh.z = pk2(hv[4], hv[5]); wh.w = pk2(hv[6], hv[7]);
;                     lo[0] = hv[0] - bflo(wh.x); lo[1] = hv[1] - bfhi(wh.x); lo[2] = hv[2] - bflo(wh.y); lo[3] = hv[3] - bfhi(wh.y);
;                     lo[4] = hv[4] - bflo(wh.z); lo[5] = hv[5] - bfhi(wh.z); lo[6] = hv[6] - bflo(wh.w); lo[7] = hv[7] - bfhi(wh.w);
;                     u32x4 wl; wl.x = pk2(lo[0], lo[1]); wl.y = pk2(lo[2], lo[3]); wl.z = pk2(lo[4], lo[5]); wl.w = pk2(lo[6], lo[7]);
;                     *(u32x4*)(HO + off) = wh; *(u32x4*)(LO + off) = wl;
	v_readlane_b32 s44, v250, 8
	v_readlane_b32 s46, v250, 10
	v_readlane_b32 s47, v250, 11
	s_waitcnt lgkmcnt(0)
	v_add_f32_e32 v84, v82, v83
	s_lshl_b32 s40, s25, 2
	v_lshl_add_u64 v[82:83], s[46:47], 0, v[102:103]
	v_lshl_add_u64 v[82:83], s[54:55], 2, v[82:83]
	v_lshl_add_u64 v[82:83], v[82:83], 0, s[40:41]
	v_readlane_b32 s45, v250, 9
	global_store_dword v[82:83], v84, off
.LBB0_1344:
	s_or_b64 exec, exec, s[12:13]
	v_or_b32_e32 v88, 48, v144
	v_ashrrev_i32_e32 v89, 31, v88
	v_lshlrev_b64 v[86:87], 6, v[88:89]
	s_waitcnt lgkmcnt(0)
	v_lshl_add_u64 v[82:83], v[136:137], 0, v[86:87]
	global_load_dwordx4 v[82:85], v[82:83], off
	v_readlane_b32 s10, v253, 35
	v_readlane_b32 s11, v253, 36
	v_readlane_b32 s6, v250, 49
	v_readlane_b32 s7, v250, 50
	s_waitcnt vmcnt(0)
	v_mov_b32_e32 v90, v83
	v_mov_b32_e32 v91, v84
	v_mov_b32_e32 v83, v85
	v_pk_add_f32 v[82:83], v[90:91], v[82:83]
	s_nop 0
	v_add_f32_e32 v82, v82, v83
	v_mov_b32_e32 v83, v82
	s_nop 1
	v_permlane16_swap_b32_e32 v82, v83
	s_waitcnt lgkmcnt(0)
	v_add_f32_e32 v82, v82, v83
	v_mov_b32_e32 v83, v82
	s_nop 1
	v_permlane32_swap_b32_e32 v82, v83
	s_waitcnt lgkmcnt(0)
	v_add_f32_e32 v82, v82, v83
	v_fmamk_f32 v82, v82, 0x3a800000, v239
	s_nop 0
	v_rsq_f32_e32 v104, v82
	s_nop 0
	s_nop 0
	v_lshlrev_b64 v[82:83], 10, v[88:89]
	v_lshl_add_u64 v[82:83], v[82:83], 0, v[142:143]
	v_lshlrev_b64 v[88:89], 1, v[82:83]
	v_lshl_add_u64 v[82:83], s[10:11], 0, v[88:89]
	v_lshl_add_u64 v[84:85], s[14:15], 0, v[88:89]
	global_load_dwordx4 v[94:97], v[82:83], off
	global_load_dwordx4 v[106:109], v[84:85], off
	v_lshl_add_u64 v[82:83], s[6:7], 0, v[88:89]
	global_load_dwordx4 v[98:101], v[82:83], off
	v_mul_f32_e32 v74, v74, v104
	v_mul_f32_e32 v74, 0xbfb8aa3b, v74
	v_exp_f32_e32 v74, v74
	v_mul_f32_e32 v78, v78, v104
	v_mul_f32_e32 v79, v79, v104
	v_mul_f32_e32 v78, 0xbfb8aa3b, v78
	v_add_f32_e32 v74, 1.0, v74
	v_rcp_f32_e32 v84, v74
	v_mul_f32_e32 v74, v75, v104
	v_mul_f32_e32 v74, 0xbfb8aa3b, v74
	v_exp_f32_e32 v74, v74
	v_mul_f32_e32 v79, 0xbfb8aa3b, v79
	v_exp_f32_e32 v78, v78
	v_exp_f32_e32 v79, v79
	v_add_f32_e32 v74, 1.0, v74
	v_rcp_f32_e32 v85, v74
	v_mul_f32_e32 v74, v76, v104
	v_mul_f32_e32 v74, 0xbfb8aa3b, v74
	v_exp_f32_e32 v74, v74
	v_mul_f32_e32 v80, v80, v104
	v_mul_f32_e32 v81, v81, v104
	v_add_f32_e32 v78, 1.0, v78
	v_add_f32_e32 v74, 1.0, v74
	v_rcp_f32_e32 v102, v74
	v_mul_f32_e32 v74, v77, v104
	v_mul_f32_e32 v74, 0xbfb8aa3b, v74
	v_exp_f32_e32 v74, v74
	v_add_f32_e32 v79, 1.0, v79
	v_mul_f32_e32 v80, 0xbfb8aa3b, v80
	v_mul_f32_e32 v81, 0xbfb8aa3b, v81
	v_rcp_f32_e32 v78, v78
	v_rcp_f32_e32 v79, v79
	v_exp_f32_e32 v80, v80
	v_exp_f32_e32 v81, v81
	v_add_f32_e32 v74, 1.0, v74
	v_rcp_f32_e32 v103, v74
	v_add_f32_e32 v80, 1.0, v80
	v_add_f32_e32 v81, 1.0, v81
	v_rcp_f32_e32 v80, v80
	v_rcp_f32_e32 v81, v81
	v_mul_f32_e32 v70, v70, v104
	v_mul_f32_e32 v70, 0xbfb8aa3b, v70
	v_exp_f32_e32 v70, v70
	v_mul_f32_e32 v66, v66, v104
	v_mul_f32_e32 v66, 0xbfb8aa3b, v66
	v_exp_f32_e32 v66, v66
	v_add_f32_e32 v70, 1.0, v70
	v_add_f32_e32 v66, 1.0, v66
	s_waitcnt vmcnt(2)
	v_lshlrev_b32_e32 v74, 16, v94
	v_and_b32_e32 v75, 0xffff0000, v94
	s_waitcnt vmcnt(0)
	v_lshlrev_b32_e32 v76, 16, v98
	v_and_b32_e32 v77, 0xffff0000, v98
	v_pk_add_f32 v[74:75], v[74:75], v[76:77]
	v_lshlrev_b32_e32 v76, 16, v106
	v_and_b32_e32 v77, 0xffff0000, v106
	v_pk_fma_f32 v[76:77], v[78:79], v[76:77], v[74:75]
	v_lshlrev_b32_e32 v92, 16, v99
	v_cvt_pk_bf16_f32 v74, v76, v77
	v_lshlrev_b32_e32 v78, 16, v74
	v_and_b32_e32 v79, 0xffff0000, v74
	v_pk_mul_f32 v[90:91], v[76:77], v[76:77]
	v_pk_add_f32 v[78:79], v[76:77], v[78:79] neg_lo:[0,1] neg_hi:[0,1]
	v_lshlrev_b32_e32 v76, 16, v95
	v_and_b32_e32 v77, 0xffff0000, v95
	v_and_b32_e32 v93, 0xffff0000, v99
	v_pk_add_f32 v[76:77], v[76:77], v[92:93]
	v_lshlrev_b32_e32 v92, 16, v107
	v_and_b32_e32 v93, 0xffff0000, v107
	v_pk_fma_f32 v[76:77], v[80:81], v[92:93], v[76:77]
	v_lshlrev_b32_e32 v94, 16, v100
	v_cvt_pk_bf16_f32 v75, v76, v77
	v_lshlrev_b32_e32 v80, 16, v75
	v_and_b32_e32 v81, 0xffff0000, v75
	v_pk_mul_f32 v[92:93], v[76:77], v[76:77]
	v_pk_add_f32 v[80:81], v[76:77], v[80:81] neg_lo:[0,1] neg_hi:[0,1]
	v_lshlrev_b32_e32 v76, 16, v96
	v_and_b32_e32 v77, 0xffff0000, v96
	v_and_b32_e32 v95, 0xffff0000, v100
	v_pk_add_f32 v[76:77], v[76:77], v[94:95]
	v_lshlrev_b32_e32 v94, 16, v108
	v_and_b32_e32 v95, 0xffff0000, v108
	v_pk_fma_f32 v[84:85], v[84:85], v[94:95], v[76:77]
	v_lshlrev_b32_e32 v96, 16, v97
	v_cvt_pk_bf16_f32 v76, v84, v85
	v_lshlrev_b32_e32 v98, 16, v76
	v_and_b32_e32 v99, 0xffff0000, v76
	v_pk_mul_f32 v[94:95], v[84:85], v[84:85]
	v_pk_add_f32 v[84:85], v[84:85], v[98:99] neg_lo:[0,1] neg_hi:[0,1]
	v_and_b32_e32 v97, 0xffff0000, v97
	v_lshlrev_b32_e32 v98, 16, v101
	v_and_b32_e32 v99, 0xffff0000, v101
	v_pk_add_f32 v[96:97], v[96:97], v[98:99]
	v_lshlrev_b32_e32 v98, 16, v109
	v_and_b32_e32 v99, 0xffff0000, v109
	v_pk_fma_f32 v[98:99], v[102:103], v[98:99], v[96:97]
	v_cvt_pk_bf16_f32 v78, v78, v79
	v_cvt_pk_bf16_f32 v77, v98, v99
	v_lshlrev_b32_e32 v100, 16, v77
	v_and_b32_e32 v101, 0xffff0000, v77
	v_pk_mul_f32 v[96:97], v[98:99], v[98:99]
	v_pk_add_f32 v[98:99], v[98:99], v[100:101] neg_lo:[0,1] neg_hi:[0,1]
	v_cvt_pk_bf16_f32 v79, v80, v81
	v_cvt_pk_bf16_f32 v80, v84, v85
	v_lshl_add_u64 v[84:85], s[58:59], 0, v[88:89]
	v_or_b32_e32 v88, 0x100, v88
	v_cvt_pk_bf16_f32 v81, v98, v99
	global_store_dwordx4 v[84:85], v[74:77], off
	global_store_dwordx4 v[82:83], v[78:81], off
	v_lshl_add_u64 v[98:99], s[6:7], 0, v[88:89]
	v_lshl_add_u64 v[74:75], s[10:11], 0, v[88:89]
	global_load_dwordx4 v[74:77], v[74:75], off
	v_lshl_add_u64 v[82:83], s[14:15], 0, v[88:89]
	global_load_dwordx4 v[78:81], v[98:99], off
	v_rcp_f32_e32 v102, v70
	global_load_dwordx4 v[82:85], v[82:83], off
	v_mul_f32_e32 v70, v71, v104
	v_mul_f32_e32 v70, 0xbfb8aa3b, v70
	v_exp_f32_e32 v70, v70
	s_nop 0
	v_add_f32_e32 v70, 1.0, v70
	v_rcp_f32_e32 v103, v70
	v_mul_f32_e32 v70, v72, v104
	v_rcp_f32_e32 v72, v66
	v_mul_f32_e32 v66, v67, v104
	v_mul_f32_e32 v70, 0xbfb8aa3b, v70
	v_mul_f32_e32 v66, 0xbfb8aa3b, v66
	v_exp_f32_e32 v70, v70
	v_exp_f32_e32 v66, v66
	v_add_f32_e32 v70, 1.0, v70
	v_add_f32_e32 v66, 1.0, v66
	v_rcp_f32_e32 v100, v70
	v_mul_f32_e32 v70, v73, v104
	v_rcp_f32_e32 v73, v66
	v_mul_f32_e32 v66, v68, v104
	v_mul_f32_e32 v70, 0xbfb8aa3b, v70
	v_mul_f32_e32 v66, 0xbfb8aa3b, v66
	v_exp_f32_e32 v70, v70
	v_exp_f32_e32 v66, v66
	v_add_f32_e32 v70, 1.0, v70
	v_add_f32_e32 v66, 1.0, v66
	v_rcp_f32_e32 v101, v70
	v_rcp_f32_e32 v70, v66
	v_mul_f32_e32 v66, v69, v104
	v_mul_f32_e32 v66, 0xbfb8aa3b, v66
	v_exp_f32_e32 v66, v66
	s_waitcnt vmcnt(2)
;     __device__ __forceinline__ void operator()(const f32x4 (&acc)[2][2][4][2], const Unit& u, int wr, int wc, int fr, int fq) const {
;     ...
;                 const int row = row0 + ai * HALF + m * 16;
;                 float rs = 0.f; if (GATED) rs = rsqrtf(row_ssq(ssq_in, 16, 4, row, fq) * (1.f / 1024.f) + EPS);
;                 float sq = 0.f;
; #pragma unroll
;                 for (int bj = 0; bj < 2; ++bj) {
;                     const size_t off = (size_t)row * DM + col0 + bj * HALF;
;                     const u32x4 hh = *(const u32x4*)(HI + off), ll = *(const u32x4*)(LO + off);
;                     float hv[8] = {bflo(hh.x) + bflo(ll.x), bfhi(hh.x) + bfhi(ll.x), bflo(hh.y) + bflo(ll.y), bfhi(hh.y) + bfhi(ll.y),
;                                    bflo(hh.z) + bflo(ll.z), bfhi(hh.z) + bfhi(ll.z), bflo(hh.w) + bflo(ll.w), bfhi(hh.w) + bfhi(ll.w)};
;                     float av[8] = {acc[ai][bj][m][0][0], acc[ai][bj][m][0][1], acc[ai][bj][m][0][2], acc[ai][bj][m][0][3], acc[ai][bj][m][1][0], acc[ai][bj][m][1][1], acc[ai][bj][m][1][2], acc[ai][bj][m][1][3]};
;                     if (GATED) { const u32x4 pp = *(const u32x4*)(PP + off);
;                         const float pv[8] = {bflo(pp.x), bfhi(pp.x), bflo(pp.y), bfhi(pp.y), bflo(pp.z), bfhi(pp.z), bflo(pp.w), bfhi(pp.w)};
; #pragma unroll
;                         for (int e = 0; e < 8; ++e) av[e] = fast_sigmoid(av[e] * rs) * pv[e]; }
;                     else {
; #pragma unroll
;                         for (int e = 0; e < 8; ++e) av[e] *= alpha; }
;                     float lo[8];
; #pragma unroll
;                     for (int e = 0; e < 8; ++e) { hv[e] += av[e]; sq += hv[e] * hv[e]; }
;                     u32x4 wh; wh.x = pk2(hv[0], hv[1]); wh.y = pk2(hv[2], hv[3]); wh.z = pk2(hv[4], hv[5]); wh.w = pk2(hv[6], hv[7]);
;                     lo[0] = hv[0] - bflo(wh.x); lo[1] = hv[1] - bfhi(wh.x); lo[2] = hv[2] - bflo(wh.y); lo[3] = hv[3] - bfhi(wh.y);
;                     lo[4] = hv[4] - bflo(wh.z); lo[5] = hv[5] - bfhi(wh.z); lo[6] = hv[6] - bflo(wh.w); lo[7] = hv[7] - bfhi(wh.w);
;                     u32x4 wl; wl.x = pk2(lo[0], lo[1]); wl.y = pk2(lo[2], lo[3]); wl.z = pk2(lo[4], lo[5]); wl.w = pk2(lo[6], lo[7]);
;                     *(u32x4*)(HO + off) = wh; *(u32x4*)(LO + off) = wl;
;                 }
;                 sq += __shfl_xor(sq, 16); sq += __shfl_xor(sq, 32);
	v_and_b32_e32 v67, 0xffff0000, v74
	v_add_f32_e32 v66, 1.0, v66
	v_rcp_f32_e32 v71, v66
	v_lshlrev_b32_e32 v66, 16, v74
	s_waitcnt vmcnt(1)
	v_lshlrev_b32_e32 v68, 16, v78
	v_and_b32_e32 v69, 0xffff0000, v78
	v_pk_add_f32 v[66:67], v[66:67], v[68:69]
	s_waitcnt vmcnt(0)
	v_lshlrev_b32_e32 v68, 16, v82
	v_and_b32_e32 v69, 0xffff0000, v82
	v_pk_fma_f32 v[68:69], v[102:103], v[68:69], v[66:67]
	v_lshlrev_b32_e32 v74, 16, v79
	v_cvt_pk_bf16_f32 v66, v68, v69
	v_lshlrev_b32_e32 v102, 16, v66
	v_and_b32_e32 v103, 0xffff0000, v66
	v_pk_mul_f32 v[104:105], v[68:69], v[68:69]
	v_pk_add_f32 v[102:103], v[68:69], v[102:103] neg_lo:[0,1] neg_hi:[0,1]
	v_lshlrev_b32_e32 v68, 16, v75
	v_and_b32_e32 v69, 0xffff0000, v75
	v_and_b32_e32 v75, 0xffff0000, v79
	v_pk_add_f32 v[68:69], v[68:69], v[74:75]
	v_lshlrev_b32_e32 v74, 16, v83
	v_and_b32_e32 v75, 0xffff0000, v83
	v_pk_fma_f32 v[68:69], v[100:101], v[74:75], v[68:69]
	v_lshlrev_b32_e32 v82, 16, v80
	v_cvt_pk_bf16_f32 v67, v68, v69
	v_lshlrev_b32_e32 v78, 16, v67
	v_and_b32_e32 v79, 0xffff0000, v67
	v_pk_mul_f32 v[74:75], v[68:69], v[68:69]
	v_pk_add_f32 v[78:79], v[68:69], v[78:79] neg_lo:[0,1] neg_hi:[0,1]
	v_lshlrev_b32_e32 v68, 16, v76
	v_and_b32_e32 v69, 0xffff0000, v76
	v_and_b32_e32 v83, 0xffff0000, v80
	v_pk_add_f32 v[68:69], v[68:69], v[82:83]
	v_lshlrev_b32_e32 v82, 16, v84
	v_and_b32_e32 v83, 0xffff0000, v84
	v_pk_fma_f32 v[72:73], v[72:73], v[82:83], v[68:69]
	v_add_f32_e32 v69, v90, v91
	v_add_f32_e32 v69, v92, v69
	v_add_f32_e32 v69, v93, v69
	v_add_f32_e32 v69, v94, v69
	v_add_f32_e32 v69, v95, v69
	v_add_f32_e32 v69, v96, v69
	v_add_f32_e32 v69, v97, v69
	v_add_f32_e32 v69, v104, v69
	v_add_f32_e32 v69, v105, v69
	v_lshlrev_b32_e32 v76, 16, v77
	v_and_b32_e32 v77, 0xffff0000, v77
	v_lshlrev_b32_e32 v80, 16, v81
	v_and_b32_e32 v81, 0xffff0000, v81
	v_add_f32_e32 v69, v74, v69
	v_pk_mul_f32 v[82:83], v[72:73], v[72:73]
	v_pk_add_f32 v[76:77], v[76:77], v[80:81]
	v_lshlrev_b32_e32 v80, 16, v85
	v_and_b32_e32 v81, 0xffff0000, v85
	v_add_f32_e32 v69, v75, v69
	v_pk_fma_f32 v[70:71], v[70:71], v[80:81], v[76:77]
	v_add_f32_e32 v69, v82, v69
	v_pk_mul_f32 v[76:77], v[70:71], v[70:71]
	v_add_f32_e32 v69, v83, v69
	v_add_f32_e32 v69, v76, v69
	v_cvt_pk_bf16_f32 v68, v72, v73
	v_add_f32_e32 v76, v77, v69
	v_cvt_pk_bf16_f32 v69, v70, v71
	v_lshlrev_b32_e32 v100, 16, v68
	v_and_b32_e32 v101, 0xffff0000, v68
	v_lshlrev_b32_e32 v74, 16, v69
	v_and_b32_e32 v75, 0xffff0000, v69
	v_pk_add_f32 v[72:73], v[72:73], v[100:101] neg_lo:[0,1] neg_hi:[0,1]
	v_pk_add_f32 v[74:75], v[70:71], v[74:75] neg_lo:[0,1] neg_hi:[0,1]
	v_cvt_pk_bf16_f32 v72, v72, v73
	v_cvt_pk_bf16_f32 v73, v74, v75
	v_lshl_add_u64 v[74:75], s[58:59], 0, v[88:89]
	v_cvt_pk_bf16_f32 v70, v102, v103
	v_cvt_pk_bf16_f32 v71, v78, v79
	global_store_dwordx4 v[74:75], v[66:69], off
	global_store_dwordx4 v[98:99], v[70:73], off
	v_mov_b32_e32 v66, v76
	s_nop 1
	v_permlane16_swap_b32_e32 v76, v66
	s_waitcnt lgkmcnt(0)
	v_add_f32_e32 v66, v76, v66
	ds_bpermute_b32 v67, v145, v66
	s_and_saveexec_b64 s[12:13], s[0:1]
	s_cbranch_execz .LBB0_1346
	v_readlane_b32 s44, v250, 8
	v_readlane_b32 s46, v250, 10
	v_readlane_b32 s47, v250, 11
	s_waitcnt lgkmcnt(0)
	v_add_f32_e32 v68, v66, v67
	s_lshl_b32 s40, s25, 2
	v_lshl_add_u64 v[66:67], s[46:47], 0, v[86:87]
	v_lshl_add_u64 v[66:67], s[54:55], 2, v[66:67]
	v_lshl_add_u64 v[66:67], v[66:67], 0, s[40:41]
	v_readlane_b32 s45, v250, 9
	global_store_dword v[66:67], v68, off
.LBB0_1346:
	s_or_b64 exec, exec, s[12:13]
	v_add_u32_e32 v72, 0x80, v144
	v_ashrrev_i32_e32 v73, 31, v72
	v_lshlrev_b64 v[70:71], 6, v[72:73]
	s_waitcnt lgkmcnt(0)
	v_lshl_add_u64 v[66:67], v[136:137], 0, v[70:71]
	global_load_dwordx4 v[66:69], v[66:67], off
	v_readlane_b32 s10, v253, 35
	v_readlane_b32 s11, v253, 36
	v_readlane_b32 s6, v250, 49
	v_readlane_b32 s7, v250, 50
	s_waitcnt vmcnt(0)
	v_mov_b32_e32 v74, v67
	v_mov_b32_e32 v75, v68
	v_mov_b32_e32 v67, v69
	v_pk_add_f32 v[66:67], v[74:75], v[66:67]
	s_nop 0
	v_add_f32_e32 v66, v66, v67
	v_mov_b32_e32 v67, v66
	s_nop 1
	v_permlane16_swap_b32_e32 v66, v67
	s_waitcnt lgkmcnt(0)
	v_add_f32_e32 v66, v66, v67
	v_mov_b32_e32 v67, v66
	s_nop 1
	v_permlane32_swap_b32_e32 v66, v67
	s_waitcnt lgkmcnt(0)
	v_add_f32_e32 v66, v66, v67
	v_fmamk_f32 v66, v66, 0x3a800000, v239
	s_nop 0
	v_rsq_f32_e32 v88, v66
	s_nop 0
	s_nop 0
	v_lshlrev_b64 v[66:67], 10, v[72:73]
	v_lshl_add_u64 v[66:67], v[66:67], 0, v[142:143]
	v_lshlrev_b64 v[72:73], 1, v[66:67]
	v_lshl_add_u64 v[66:67], s[10:11], 0, v[72:73]
	v_lshl_add_u64 v[68:69], s[14:15], 0, v[72:73]
	global_load_dwordx4 v[78:81], v[66:67], off
	global_load_dwordx4 v[90:93], v[68:69], off
	v_lshl_add_u64 v[66:67], s[6:7], 0, v[72:73]
	global_load_dwordx4 v[82:85], v[66:67], off
	v_mul_f32_e32 v58, v58, v88
	v_mul_f32_e32 v58, 0xbfb8aa3b, v58
	v_exp_f32_e32 v58, v58
	v_mul_f32_e32 v62, v62, v88
	v_mul_f32_e32 v63, v63, v88
	v_mul_f32_e32 v62, 0xbfb8aa3b, v62
	v_add_f32_e32 v58, 1.0, v58
	v_rcp_f32_e32 v68, v58
	v_mul_f32_e32 v58, v59, v88
	v_mul_f32_e32 v58, 0xbfb8aa3b, v58
	v_exp_f32_e32 v58, v58
	v_mul_f32_e32 v63, 0xbfb8aa3b, v63
	v_exp_f32_e32 v62, v62
	v_exp_f32_e32 v63, v63
	v_add_f32_e32 v58, 1.0, v58
	v_rcp_f32_e32 v69, v58
	v_mul_f32_e32 v58, v60, v88
	v_mul_f32_e32 v58, 0xbfb8aa3b, v58
	v_exp_f32_e32 v58, v58
	v_mul_f32_e32 v64, v64, v88
	v_mul_f32_e32 v65, v65, v88
	v_add_f32_e32 v62, 1.0, v62
	v_add_f32_e32 v58, 1.0, v58
	v_rcp_f32_e32 v86, v58
	v_mul_f32_e32 v58, v61, v88
	v_mul_f32_e32 v58, 0xbfb8aa3b, v58
	v_exp_f32_e32 v58, v58
	v_add_f32_e32 v63, 1.0, v63
	v_mul_f32_e32 v64, 0xbfb8aa3b, v64
	v_mul_f32_e32 v65, 0xbfb8aa3b, v65
	v_rcp_f32_e32 v62, v62
	v_rcp_f32_e32 v63, v63
	v_exp_f32_e32 v64, v64
	v_exp_f32_e32 v65, v65
	v_add_f32_e32 v58, 1.0, v58
	v_rcp_f32_e32 v87, v58
	v_add_f32_e32 v64, 1.0, v64
	v_add_f32_e32 v65, 1.0, v65
	v_rcp_f32_e32 v64, v64
	v_rcp_f32_e32 v65, v65
	v_mul_f32_e32 v54, v54, v88
	v_mul_f32_e32 v54, 0xbfb8aa3b, v54
	v_exp_f32_e32 v54, v54
	v_mul_f32_e32 v50, v50, v88
	v_mul_f32_e32 v50, 0xbfb8aa3b, v50
	v_exp_f32_e32 v50, v50
	v_add_f32_e32 v54, 1.0, v54
	v_add_f32_e32 v50, 1.0, v50
	s_waitcnt vmcnt(2)
; __device__ __forceinline__ float bflo(unsigned u) { return __uint_as_float(u << 16); }
;     __device__ __forceinline__ void operator()(const f32x4 (&acc)[2][2][4][2], const Unit& u, int wr, int wc, int fr, int fq) const {
;     ...
;                 for (int bj = 0; bj < 2; ++bj) {
;                     const size_t off = (size_t)row * DM + col0 + bj * HALF;
;                     const u32x4 hh = *(const u32x4*)(HI + off), ll = *(const u32x4*)(LO + off);
;                     float hv[8] = {bflo(hh.x) + bflo(ll.x), bfhi(hh.x) + bfhi(ll.x), bflo(hh.y) + bflo(ll.y), bfhi(hh.y) + bfhi(ll.y),
;                                    bflo(hh.z) + bflo(ll.z), bfhi(hh.z) + bfhi(ll.z), bflo(hh.w) + bflo(ll.w), bfhi(hh.w) + bfhi(ll.w)};
;                     float av[8] = {acc[ai][bj][m][0][0], acc[ai][bj][m][0][1], acc[ai][bj][m][0][2], acc[ai][bj][m][0][3], acc[ai][bj][m][1][0], acc[ai][bj][m][1][1], acc[ai][bj][m][1][2], acc[ai][bj][m][1][3]};
;                     if (GATED) { const u32x4 pp = *(const u32x4*)(PP + off);
;                         const float pv[8] = {bflo(pp.x), bfhi(pp.x), bflo(pp.y), bfhi(pp.y), bflo(pp.z), bfhi(pp.z), bflo(pp.w), bfhi(pp.w)};
; #pragma unroll
;                         for (int e = 0; e < 8; ++e) av[e] = fast_sigmoid(av[e] * rs) * pv[e]; }
;                     else {
; #pragma unroll
;                         for (int e = 0; e < 8; ++e) av[e] *= alpha; }
;                     float lo[8];
; #pragma unroll
;                     for (int e = 0; e < 8; ++e) { hv[e] += av[e]; sq += hv[e] * hv[e]; }
;                     u32x4 wh; wh.x = pk2(hv[0], hv[1]); wh.y = pk2(hv[2], hv[3]); wh.z = pk2(hv[4], hv[5]); wh.w = pk2(hv[6], hv[7]);
;                     lo[0] = hv[0] - bflo(wh.x); lo[1] = hv[1] - bfhi(wh.x); lo[2] = hv[2] - bflo(wh.y); lo[3] = hv[3] - bfhi(wh.y);
;                     lo[4] = hv[4] - bflo(wh.z); lo[5] = hv[5] - bfhi(wh.z); lo[6] = hv[6] - bflo(wh.w); lo[7] = hv[7] - bfhi(wh.w);
;                     u32x4 wl; wl.x = pk2(lo[0], lo[1]); wl.y = pk2(lo[2], lo[3]); wl.z = pk2(lo[4], lo[5]); wl.w = pk2(lo[6], lo[7]);
;                     *(u32x4*)(HO + off) = wh; *(u32x4*)(LO + off) = wl;
;                 }
;                 sq += __shfl_xor(sq, 16); sq += __shfl_xor(sq, 32);
;                 if (fq == 0) ssq_out[(size_t)row * 16 + 4 * u.pn + wc] = sq;
	v_lshlrev_b32_e32 v58, 16, v78
	v_and_b32_e32 v59, 0xffff0000, v78
	s_waitcnt vmcnt(0)
	v_lshlrev_b32_e32 v60, 16, v82
	v_and_b32_e32 v61, 0xffff0000, v82
	v_pk_add_f32 v[58:59], v[58:59], v[60:61]
	v_lshlrev_b32_e32 v60, 16, v90
	v_and_b32_e32 v61, 0xffff0000, v90
	v_pk_fma_f32 v[60:61], v[62:63], v[60:61], v[58:59]
	v_lshlrev_b32_e32 v76, 16, v83
	v_cvt_pk_bf16_f32 v58, v60, v61
	v_lshlrev_b32_e32 v62, 16, v58
	v_and_b32_e32 v63, 0xffff0000, v58
	v_pk_mul_f32 v[74:75], v[60:61], v[60:61]
	v_pk_add_f32 v[62:63], v[60:61], v[62:63] neg_lo:[0,1] neg_hi:[0,1]
	v_lshlrev_b32_e32 v60, 16, v79
	v_and_b32_e32 v61, 0xffff0000, v79
	v_and_b32_e32 v77, 0xffff0000, v83
	v_pk_add_f32 v[60:61], v[60:61], v[76:77]
	v_lshlrev_b32_e32 v76, 16, v91
	v_and_b32_e32 v77, 0xffff0000, v91
	v_pk_fma_f32 v[60:61], v[64:65], v[76:77], v[60:61]
	v_lshlrev_b32_e32 v78, 16, v84
	v_cvt_pk_bf16_f32 v59, v60, v61
	v_lshlrev_b32_e32 v64, 16, v59
	v_and_b32_e32 v65, 0xffff0000, v59
	v_pk_mul_f32 v[76:77], v[60:61], v[60:61]
	v_pk_add_f32 v[64:65], v[60:61], v[64:65] neg_lo:[0,1] neg_hi:[0,1]
	v_lshlrev_b32_e32 v60, 16, v80
	v_and_b32_e32 v61, 0xffff0000, v80
	v_and_b32_e32 v79, 0xffff0000, v84
	v_pk_add_f32 v[60:61], v[60:61], v[78:79]
	v_lshlrev_b32_e32 v78, 16, v92
	v_and_b32_e32 v79, 0xffff0000, v92
	v_pk_fma_f32 v[68:69], v[68:69], v[78:79], v[60:61]
	v_lshlrev_b32_e32 v80, 16, v81
	v_cvt_pk_bf16_f32 v60, v68, v69
	v_lshlrev_b32_e32 v82, 16, v60
	v_and_b32_e32 v83, 0xffff0000, v60
	v_pk_mul_f32 v[78:79], v[68:69], v[68:69]
	v_pk_add_f32 v[68:69], v[68:69], v[82:83] neg_lo:[0,1] neg_hi:[0,1]
	v_and_b32_e32 v81, 0xffff0000, v81
	v_lshlrev_b32_e32 v82, 16, v85
	v_and_b32_e32 v83, 0xffff0000, v85
	v_pk_add_f32 v[80:81], v[80:81], v[82:83]
	v_lshlrev_b32_e32 v82, 16, v93
	v_and_b32_e32 v83, 0xffff0000, v93
	v_pk_fma_f32 v[82:83], v[86:87], v[82:83], v[80:81]
	v_cvt_pk_bf16_f32 v62, v62, v63
	v_cvt_pk_bf16_f32 v61, v82, v83
	v_lshlrev_b32_e32 v84, 16, v61
	v_and_b32_e32 v85, 0xffff0000, v61
	v_pk_mul_f32 v[80:81], v[82:83], v[82:83]
	v_pk_add_f32 v[82:83], v[82:83], v[84:85] neg_lo:[0,1] neg_hi:[0,1]
	v_cvt_pk_bf16_f32 v63, v64, v65
	v_cvt_pk_bf16_f32 v64, v68, v69
	v_lshl_add_u64 v[68:69], s[58:59], 0, v[72:73]
	v_or_b32_e32 v72, 0x100, v72
	v_cvt_pk_bf16_f32 v65, v82, v83
	global_store_dwordx4 v[68:69], v[58:61], off
	global_store_dwordx4 v[66:67], v[62:65], off
	v_lshl_add_u64 v[82:83], s[6:7], 0, v[72:73]
	v_lshl_add_u64 v[58:59], s[10:11], 0, v[72:73]
	global_load_dwordx4 v[58:61], v[58:59], off
	v_lshl_add_u64 v[66:67], s[14:15], 0, v[72:73]
	global_load_dwordx4 v[62:65], v[82:83], off
	v_rcp_f32_e32 v86, v54
	global_load_dwordx4 v[66:69], v[66:67], off
	v_mul_f32_e32 v54, v55, v88
	v_mul_f32_e32 v54, 0xbfb8aa3b, v54
	v_exp_f32_e32 v54, v54
	s_nop 0
	v_add_f32_e32 v54, 1.0, v54
	v_rcp_f32_e32 v87, v54
	v_mul_f32_e32 v54, v56, v88
	v_rcp_f32_e32 v56, v50
	v_mul_f32_e32 v50, v51, v88
	v_mul_f32_e32 v54, 0xbfb8aa3b, v54
	v_mul_f32_e32 v50, 0xbfb8aa3b, v50
	v_exp_f32_e32 v54, v54
	v_exp_f32_e32 v50, v50
	v_add_f32_e32 v54, 1.0, v54
	v_add_f32_e32 v50, 1.0, v50
	v_rcp_f32_e32 v84, v54
	v_mul_f32_e32 v54, v57, v88
	v_rcp_f32_e32 v57, v50
	v_mul_f32_e32 v50, v52, v88
	v_mul_f32_e32 v54, 0xbfb8aa3b, v54
	v_mul_f32_e32 v50, 0xbfb8aa3b, v50
	v_exp_f32_e32 v54, v54
	v_exp_f32_e32 v50, v50
	v_add_f32_e32 v54, 1.0, v54
	v_add_f32_e32 v50, 1.0, v50
	v_rcp_f32_e32 v85, v54
	v_rcp_f32_e32 v54, v50
	v_mul_f32_e32 v50, v53, v88
	v_mul_f32_e32 v50, 0xbfb8aa3b, v50
	v_exp_f32_e32 v50, v50
	s_waitcnt vmcnt(2)
	v_and_b32_e32 v51, 0xffff0000, v58
	v_add_f32_e32 v50, 1.0, v50
	v_rcp_f32_e32 v55, v50
	v_lshlrev_b32_e32 v50, 16, v58
	s_waitcnt vmcnt(1)
	v_lshlrev_b32_e32 v52, 16, v62
	v_and_b32_e32 v53, 0xffff0000, v62
	v_pk_add_f32 v[50:51], v[50:51], v[52:53]
	s_waitcnt vmcnt(0)
	v_lshlrev_b32_e32 v52, 16, v66
	v_and_b32_e32 v53, 0xffff0000, v66
	v_pk_fma_f32 v[52:53], v[86:87], v[52:53], v[50:51]
	v_lshlrev_b32_e32 v58, 16, v63
	v_cvt_pk_bf16_f32 v50, v52, v53
	v_lshlrev_b32_e32 v86, 16, v50
	v_and_b32_e32 v87, 0xffff0000, v50
	v_pk_mul_f32 v[88:89], v[52:53], v[52:53]
	v_pk_add_f32 v[86:87], v[52:53], v[86:87] neg_lo:[0,1] neg_hi:[0,1]
	v_lshlrev_b32_e32 v52, 16, v59
	v_and_b32_e32 v53, 0xffff0000, v59
	v_and_b32_e32 v59, 0xffff0000, v63
	v_pk_add_f32 v[52:53], v[52:53], v[58:59]
	v_lshlrev_b32_e32 v58, 16, v67
	v_and_b32_e32 v59, 0xffff0000, v67
	v_pk_fma_f32 v[52:53], v[84:85], v[58:59], v[52:53]
	v_lshlrev_b32_e32 v66, 16, v64
	v_cvt_pk_bf16_f32 v51, v52, v53
	v_lshlrev_b32_e32 v62, 16, v51
	v_and_b32_e32 v63, 0xffff0000, v51
	v_pk_mul_f32 v[58:59], v[52:53], v[52:53]
	v_pk_add_f32 v[62:63], v[52:53], v[62:63] neg_lo:[0,1] neg_hi:[0,1]
	v_lshlrev_b32_e32 v52, 16, v60
	v_and_b32_e32 v53, 0xffff0000, v60
	v_and_b32_e32 v67, 0xffff0000, v64
	v_pk_add_f32 v[52:53], v[52:53], v[66:67]
	v_lshlrev_b32_e32 v66, 16, v68
	v_and_b32_e32 v67, 0xffff0000, v68
	v_pk_fma_f32 v[56:57], v[56:57], v[66:67], v[52:53]
	v_add_f32_e32 v53, v74, v75
	v_add_f32_e32 v53, v76, v53
	v_add_f32_e32 v53, v77, v53
	v_add_f32_e32 v53, v78, v53
	v_add_f32_e32 v53, v79, v53
	v_add_f32_e32 v53, v80, v53
	v_add_f32_e32 v53, v81, v53
	v_add_f32_e32 v53, v88, v53
	v_add_f32_e32 v53, v89, v53
	v_lshlrev_b32_e32 v60, 16, v61
	v_and_b32_e32 v61, 0xffff0000, v61
	v_lshlrev_b32_e32 v64, 16, v65
	v_and_b32_e32 v65, 0xffff0000, v65
	v_add_f32_e32 v53, v58, v53
	v_pk_mul_f32 v[66:67], v[56:57], v[56:57]
	v_pk_add_f32 v[60:61], v[60:61], v[64:65]
	v_lshlrev_b32_e32 v64, 16, v69
	v_and_b32_e32 v65, 0xffff0000, v69
	v_add_f32_e32 v53, v59, v53
	v_pk_fma_f32 v[54:55], v[54:55], v[64:65], v[60:61]
	v_add_f32_e32 v53, v66, v53
	v_pk_mul_f32 v[60:61], v[54:55], v[54:55]
	v_add_f32_e32 v53, v67, v53
	v_add_f32_e32 v53, v60, v53
	v_cvt_pk_bf16_f32 v52, v56, v57
	v_add_f32_e32 v60, v61, v53
	v_cvt_pk_bf16_f32 v53, v54, v55
	v_lshlrev_b32_e32 v84, 16, v52
	v_and_b32_e32 v85, 0xffff0000, v52
	v_lshlrev_b32_e32 v58, 16, v53
	v_and_b32_e32 v59, 0xffff0000, v53
	v_pk_add_f32 v[56:57], v[56:57], v[84:85] neg_lo:[0,1] neg_hi:[0,1]
	v_pk_add_f32 v[58:59], v[54:55], v[58:59] neg_lo:[0,1] neg_hi:[0,1]
	v_cvt_pk_bf16_f32 v56, v56, v57
	v_cvt_pk_bf16_f32 v57, v58, v59
	v_lshl_add_u64 v[58:59], s[58:59], 0, v[72:73]
	v_cvt_pk_bf16_f32 v54, v86, v87
	v_cvt_pk_bf16_f32 v55, v62, v63
	global_store_dwordx4 v[58:59], v[50:53], off
	global_store_dwordx4 v[82:83], v[54:57], off
	v_mov_b32_e32 v50, v60
	s_nop 1
	v_permlane16_swap_b32_e32 v60, v50
	s_waitcnt lgkmcnt(0)
	v_add_f32_e32 v50, v60, v50
	ds_bpermute_b32 v51, v145, v50
	s_and_saveexec_b64 s[12:13], s[0:1]
	s_cbranch_execz .LBB0_1348
	v_readlane_b32 s44, v250, 8
	v_readlane_b32 s46, v250, 10
	v_readlane_b32 s47, v250, 11
	s_waitcnt lgkmcnt(0)
	v_add_f32_e32 v52, v50, v51
	s_lshl_b32 s40, s25, 2
	v_lshl_add_u64 v[50:51], s[46:47], 0, v[70:71]
	v_lshl_add_u64 v[50:51], s[54:55], 2, v[50:51]
	v_lshl_add_u64 v[50:51], v[50:51], 0, s[40:41]
	v_readlane_b32 s45, v250, 9
	global_store_dword v[50:51], v52, off
; __device__ __forceinline__ float bflo(unsigned u) { return __uint_as_float(u << 16); }
;     __device__ __forceinline__ void operator()(const f32x4 (&acc)[2][2][4][2], const Unit& u, int wr, int wc, int fr, int fq) const {
;     ...
;                 const int row = row0 + ai * HALF + m * 16;
;                 float rs = 0.f; if (GATED) rs = rsqrtf(row_ssq(ssq_in, 16, 4, row, fq) * (1.f / 1024.f) + EPS);
;                 float sq = 0.f;
; #pragma unroll
;                 for (int bj = 0; bj < 2; ++bj) {
;                     const size_t off = (size_t)row * DM + col0 + bj * HALF;
;                     const u32x4 hh = *(const u32x4*)(HI + off), ll = *(const u32x4*)(LO + off);
;                     float hv[8] = {bflo(hh.x) + bflo(ll.x), bfhi(hh.x) + bfhi(ll.x), bflo(hh.y) + bflo(ll.y), bfhi(hh.y) + bfhi(ll.y),
;                                    bflo(hh.z) + bflo(ll.z), bfhi(hh.z) + bfhi(ll.z), bflo(hh.w) + bflo(ll.w), bfhi(hh.w) + bfhi(ll.w)};
;                     float av[8] = {acc[ai][bj][m][0][0], acc[ai][bj][m][0][1], acc[ai][bj][m][0][2], acc[ai][bj][m][0][3], acc[ai][bj][m][1][0], acc[ai][bj][m][1][1], acc[ai][bj][m][1][2], acc[ai][bj][m][1][3]};
;                     if (GATED) { const u32x4 pp = *(const u32x4*)(PP + off);
;                         const float pv[8] = {bflo(pp.x), bfhi(pp.x), bflo(pp.y), bfhi(pp.y), bflo(pp.z), bfhi(pp.z), bflo(pp.w), bfhi(pp.w)};
; #pragma unroll
;                         for (int e = 0; e < 8; ++e) av[e] = fast_sigmoid(av[e] * rs) * pv[e]; }
;                     else {
; #pragma unroll
;                         for (int e = 0; e < 8; ++e) av[e] *= alpha; }
;                     float lo[8];
; #pragma unroll
;                     for (int e = 0; e < 8; ++e) { hv[e] += av[e]; sq += hv[e] * hv[e]; }
;                     u32x4 wh; wh.x = pk2(hv[0], hv[1]); wh.y = pk2(hv[2], hv[3]); wh.z = pk2(hv[4], hv[5]); wh.w = pk2(hv[6], hv[7]);
;                     lo[0] = hv[0] - bflo(wh.x); lo[1] = hv[1] - bfhi(wh.x); lo[2] = hv[2] - bflo(wh.y); lo[3] = hv[3] - bfhi(wh.y);
;                     lo[4] = hv[4] - bflo(wh.z); lo[5] = hv[5] - bfhi(wh.z); lo[6] = hv[6] - bflo(wh.w); lo[7] = hv[7] - bfhi(wh.w);
;                     u32x4 wl; wl.x = pk2(lo[0], lo[1]); wl.y = pk2(lo[2], lo[3]); wl.z = pk2(lo[4], lo[5]); wl.w = pk2(lo[6], lo[7]);
;                     *(u32x4*)(HO + off) = wh; *(u32x4*)(LO + off) = wl;
.LBB0_1348:
	s_or_b64 exec, exec, s[12:13]
	v_add_u32_e32 v56, 0x90, v144
	v_ashrrev_i32_e32 v57, 31, v56
	v_lshlrev_b64 v[54:55], 6, v[56:57]
	s_waitcnt lgkmcnt(0)
	v_lshl_add_u64 v[50:51], v[136:137], 0, v[54:55]
	global_load_dwordx4 v[50:53], v[50:51], off
	v_readlane_b32 s10, v253, 35
	v_readlane_b32 s11, v253, 36
	v_readlane_b32 s6, v250, 49
	v_readlane_b32 s7, v250, 50
	s_waitcnt vmcnt(0)
	v_mov_b32_e32 v58, v51
	v_mov_b32_e32 v59, v52
	v_mov_b32_e32 v51, v53
	v_pk_add_f32 v[50:51], v[58:59], v[50:51]
	s_nop 0
	v_add_f32_e32 v50, v50, v51
	v_mov_b32_e32 v51, v50
	s_nop 1
	v_permlane16_swap_b32_e32 v50, v51
	s_waitcnt lgkmcnt(0)
	v_add_f32_e32 v50, v50, v51
	v_mov_b32_e32 v51, v50
	s_nop 1
	v_permlane32_swap_b32_e32 v50, v51
	s_waitcnt lgkmcnt(0)
	v_add_f32_e32 v50, v50, v51
	v_fmamk_f32 v50, v50, 0x3a800000, v239
	s_nop 0
	v_rsq_f32_e32 v72, v50
	s_nop 0
	s_nop 0
	v_lshlrev_b64 v[50:51], 10, v[56:57]
	v_lshl_add_u64 v[50:51], v[50:51], 0, v[142:143]
	v_lshlrev_b64 v[56:57], 1, v[50:51]
	v_lshl_add_u64 v[50:51], s[10:11], 0, v[56:57]
	v_lshl_add_u64 v[52:53], s[14:15], 0, v[56:57]
	global_load_dwordx4 v[62:65], v[50:51], off
	global_load_dwordx4 v[74:77], v[52:53], off
	v_lshl_add_u64 v[50:51], s[6:7], 0, v[56:57]
	global_load_dwordx4 v[66:69], v[50:51], off
	v_mul_f32_e32 v42, v42, v72
	v_mul_f32_e32 v42, 0xbfb8aa3b, v42
	v_exp_f32_e32 v42, v42
	v_mul_f32_e32 v46, v46, v72
	v_mul_f32_e32 v47, v47, v72
	v_mul_f32_e32 v46, 0xbfb8aa3b, v46
	v_add_f32_e32 v42, 1.0, v42
	v_rcp_f32_e32 v52, v42
	v_mul_f32_e32 v42, v43, v72
	v_mul_f32_e32 v42, 0xbfb8aa3b, v42
	v_exp_f32_e32 v42, v42
	v_mul_f32_e32 v47, 0xbfb8aa3b, v47
	v_exp_f32_e32 v46, v46
	v_exp_f32_e32 v47, v47
	v_add_f32_e32 v42, 1.0, v42
	v_rcp_f32_e32 v53, v42
	v_mul_f32_e32 v42, v44, v72
	v_mul_f32_e32 v42, 0xbfb8aa3b, v42
	v_exp_f32_e32 v42, v42
	v_mul_f32_e32 v48, v48, v72
	v_mul_f32_e32 v49, v49, v72
	v_add_f32_e32 v46, 1.0, v46
	v_add_f32_e32 v42, 1.0, v42
	v_rcp_f32_e32 v70, v42
	v_mul_f32_e32 v42, v45, v72
	v_mul_f32_e32 v42, 0xbfb8aa3b, v42
	v_exp_f32_e32 v42, v42
	v_add_f32_e32 v47, 1.0, v47
	v_mul_f32_e32 v48, 0xbfb8aa3b, v48
	v_mul_f32_e32 v49, 0xbfb8aa3b, v49
	v_rcp_f32_e32 v46, v46
	v_rcp_f32_e32 v47, v47
	v_exp_f32_e32 v48, v48
	v_exp_f32_e32 v49, v49
	v_add_f32_e32 v42, 1.0, v42
	v_rcp_f32_e32 v71, v42
	v_add_f32_e32 v48, 1.0, v48
	v_add_f32_e32 v49, 1.0, v49
	v_rcp_f32_e32 v48, v48
	v_rcp_f32_e32 v49, v49
	v_mul_f32_e32 v38, v38, v72
	v_mul_f32_e32 v38, 0xbfb8aa3b, v38
	v_exp_f32_e32 v38, v38
	v_mul_f32_e32 v34, v34, v72
	v_mul_f32_e32 v34, 0xbfb8aa3b, v34
	v_exp_f32_e32 v34, v34
	v_add_f32_e32 v38, 1.0, v38
	v_add_f32_e32 v34, 1.0, v34
	s_waitcnt vmcnt(2)
	v_lshlrev_b32_e32 v42, 16, v62
	v_and_b32_e32 v43, 0xffff0000, v62
	s_waitcnt vmcnt(0)
	v_lshlrev_b32_e32 v44, 16, v66
	v_and_b32_e32 v45, 0xffff0000, v66
	v_pk_add_f32 v[42:43], v[42:43], v[44:45]
	v_lshlrev_b32_e32 v44, 16, v74
	v_and_b32_e32 v45, 0xffff0000, v74
	v_pk_fma_f32 v[44:45], v[46:47], v[44:45], v[42:43]
	v_lshlrev_b32_e32 v60, 16, v67
	v_cvt_pk_bf16_f32 v42, v44, v45
	v_lshlrev_b32_e32 v46, 16, v42
	v_and_b32_e32 v47, 0xffff0000, v42
	v_pk_mul_f32 v[58:59], v[44:45], v[44:45]
	v_pk_add_f32 v[46:47], v[44:45], v[46:47] neg_lo:[0,1] neg_hi:[0,1]
	v_lshlrev_b32_e32 v44, 16, v63
	v_and_b32_e32 v45, 0xffff0000, v63
	v_and_b32_e32 v61, 0xffff0000, v67
	v_pk_add_f32 v[44:45], v[44:45], v[60:61]
	v_lshlrev_b32_e32 v60, 16, v75
	v_and_b32_e32 v61, 0xffff0000, v75
	v_pk_fma_f32 v[44:45], v[48:49], v[60:61], v[44:45]
	v_lshlrev_b32_e32 v62, 16, v68
	v_cvt_pk_bf16_f32 v43, v44, v45
	v_lshlrev_b32_e32 v48, 16, v43
	v_and_b32_e32 v49, 0xffff0000, v43
	v_pk_mul_f32 v[60:61], v[44:45], v[44:45]
	v_pk_add_f32 v[48:49], v[44:45], v[48:49] neg_lo:[0,1] neg_hi:[0,1]
	v_lshlrev_b32_e32 v44, 16, v64
	v_and_b32_e32 v45, 0xffff0000, v64
	v_and_b32_e32 v63, 0xffff0000, v68
	v_pk_add_f32 v[44:45], v[44:45], v[62:63]
	v_lshlrev_b32_e32 v62, 16, v76
	v_and_b32_e32 v63, 0xffff0000, v76
	v_pk_fma_f32 v[52:53], v[52:53], v[62:63], v[44:45]
	v_lshlrev_b32_e32 v64, 16, v65
	v_cvt_pk_bf16_f32 v44, v52, v53
	v_lshlrev_b32_e32 v66, 16, v44
	v_and_b32_e32 v67, 0xffff0000, v44
	v_pk_mul_f32 v[62:63], v[52:53], v[52:53]
	v_pk_add_f32 v[52:53], v[52:53], v[66:67] neg_lo:[0,1] neg_hi:[0,1]
	v_and_b32_e32 v65, 0xffff0000, v65
	v_lshlrev_b32_e32 v66, 16, v69
	v_and_b32_e32 v67, 0xffff0000, v69
	v_pk_add_f32 v[64:65], v[64:65], v[66:67]
	v_lshlrev_b32_e32 v66, 16, v77
	v_and_b32_e32 v67, 0xffff0000, v77
	v_pk_fma_f32 v[66:67], v[70:71], v[66:67], v[64:65]
	v_cvt_pk_bf16_f32 v46, v46, v47
	v_cvt_pk_bf16_f32 v45, v66, v67
	v_lshlrev_b32_e32 v68, 16, v45
	v_and_b32_e32 v69, 0xffff0000, v45
	v_pk_mul_f32 v[64:65], v[66:67], v[66:67]
	v_pk_add_f32 v[66:67], v[66:67], v[68:69] neg_lo:[0,1] neg_hi:[0,1]
	v_cvt_pk_bf16_f32 v47, v48, v49
	v_cvt_pk_bf16_f32 v48, v52, v53
	v_lshl_add_u64 v[52:53], s[58:59], 0, v[56:57]
	v_or_b32_e32 v56, 0x100, v56
	v_cvt_pk_bf16_f32 v49, v66, v67
	global_store_dwordx4 v[52:53], v[42:45], off
	global_store_dwordx4 v[50:51], v[46:49], off
	v_lshl_add_u64 v[66:67], s[6:7], 0, v[56:57]
	v_lshl_add_u64 v[42:43], s[10:11], 0, v[56:57]
	global_load_dwordx4 v[42:45], v[42:43], off
	v_lshl_add_u64 v[50:51], s[14:15], 0, v[56:57]
	global_load_dwordx4 v[46:49], v[66:67], off
	v_rcp_f32_e32 v70, v38
	global_load_dwordx4 v[50:53], v[50:51], off
	v_mul_f32_e32 v38, v39, v72
	v_mul_f32_e32 v38, 0xbfb8aa3b, v38
	v_exp_f32_e32 v38, v38
	s_nop 0
	v_add_f32_e32 v38, 1.0, v38
	v_rcp_f32_e32 v71, v38
	v_mul_f32_e32 v38, v40, v72
	v_rcp_f32_e32 v40, v34
	v_mul_f32_e32 v34, v35, v72
	v_mul_f32_e32 v38, 0xbfb8aa3b, v38
	v_mul_f32_e32 v34, 0xbfb8aa3b, v34
	v_exp_f32_e32 v38, v38
	v_exp_f32_e32 v34, v34
	v_add_f32_e32 v38, 1.0, v38
	v_add_f32_e32 v34, 1.0, v34
	v_rcp_f32_e32 v68, v38
	v_mul_f32_e32 v38, v41, v72
	v_rcp_f32_e32 v41, v34
	v_mul_f32_e32 v34, v36, v72
	v_mul_f32_e32 v38, 0xbfb8aa3b, v38
	v_mul_f32_e32 v34, 0xbfb8aa3b, v34
	v_exp_f32_e32 v38, v38
	v_exp_f32_e32 v34, v34
	v_add_f32_e32 v38, 1.0, v38
	v_add_f32_e32 v34, 1.0, v34
	v_rcp_f32_e32 v69, v38
	v_rcp_f32_e32 v38, v34
	v_mul_f32_e32 v34, v37, v72
	v_mul_f32_e32 v34, 0xbfb8aa3b, v34
	v_exp_f32_e32 v34, v34
	s_waitcnt vmcnt(2)
;     __device__ __forceinline__ void operator()(const f32x4 (&acc)[2][2][4][2], const Unit& u, int wr, int wc, int fr, int fq) const {
;     ...
;                 const int row = row0 + ai * HALF + m * 16;
;                 float rs = 0.f; if (GATED) rs = rsqrtf(row_ssq(ssq_in, 16, 4, row, fq) * (1.f / 1024.f) + EPS);
;                 float sq = 0.f;
; #pragma unroll
;                 for (int bj = 0; bj < 2; ++bj) {
;                     const size_t off = (size_t)row * DM + col0 + bj * HALF;
;                     const u32x4 hh = *(const u32x4*)(HI + off), ll = *(const u32x4*)(LO + off);
;                     float hv[8] = {bflo(hh.x) + bflo(ll.x), bfhi(hh.x) + bfhi(ll.x), bflo(hh.y) + bflo(ll.y), bfhi(hh.y) + bfhi(ll.y),
;                                    bflo(hh.z) + bflo(ll.z), bfhi(hh.z) + bfhi(ll.z), bflo(hh.w) + bflo(ll.w), bfhi(hh.w) + bfhi(ll.w)};
;                     float av[8] = {acc[ai][bj][m][0][0], acc[ai][bj][m][0][1], acc[ai][bj][m][0][2], acc[ai][bj][m][0][3], acc[ai][bj][m][1][0], acc[ai][bj][m][1][1], acc[ai][bj][m][1][2], acc[ai][bj][m][1][3]};
;                     if (GATED) { const u32x4 pp = *(const u32x4*)(PP + off);
;                         const float pv[8] = {bflo(pp.x), bfhi(pp.x), bflo(pp.y), bfhi(pp.y), bflo(pp.z), bfhi(pp.z), bflo(pp.w), bfhi(pp.w)};
; #pragma unroll
;                         for (int e = 0; e < 8; ++e) av[e] = fast_sigmoid(av[e] * rs) * pv[e]; }
;                     else {
; #pragma unroll
;                         for (int e = 0; e < 8; ++e) av[e] *= alpha; }
;                     float lo[8];
; #pragma unroll
;                     for (int e = 0; e < 8; ++e) { hv[e] += av[e]; sq += hv[e] * hv[e]; }
;                     u32x4 wh; wh.x = pk2(hv[0], hv[1]); wh.y = pk2(hv[2], hv[3]); wh.z = pk2(hv[4], hv[5]); wh.w = pk2(hv[6], hv[7]);
;                     lo[0] = hv[0] - bflo(wh.x); lo[1] = hv[1] - bfhi(wh.x); lo[2] = hv[2] - bflo(wh.y); lo[3] = hv[3] - bfhi(wh.y);
;                     lo[4] = hv[4] - bflo(wh.z); lo[5] = hv[5] - bfhi(wh.z); lo[6] = hv[6] - bflo(wh.w); lo[7] = hv[7] - bfhi(wh.w);
;                     u32x4 wl; wl.x = pk2(lo[0], lo[1]); wl.y = pk2(lo[2], lo[3]); wl.z = pk2(lo[4], lo[5]); wl.w = pk2(lo[6], lo[7]);
;                     *(u32x4*)(HO + off) = wh; *(u32x4*)(LO + off) = wl;
;                 }
;                 sq += __shfl_xor(sq, 16); sq += __shfl_xor(sq, 32);
	v_and_b32_e32 v35, 0xffff0000, v42
	v_add_f32_e32 v34, 1.0, v34
	v_rcp_f32_e32 v39, v34
	v_lshlrev_b32_e32 v34, 16, v42
	s_waitcnt vmcnt(1)
	v_lshlrev_b32_e32 v36, 16, v46
	v_and_b32_e32 v37, 0xffff0000, v46
	v_pk_add_f32 v[34:35], v[34:35], v[36:37]
	s_waitcnt vmcnt(0)
	v_lshlrev_b32_e32 v36, 16, v50
	v_and_b32_e32 v37, 0xffff0000, v50
	v_pk_fma_f32 v[36:37], v[70:71], v[36:37], v[34:35]
	v_lshlrev_b32_e32 v42, 16, v47
	v_cvt_pk_bf16_f32 v34, v36, v37
	v_lshlrev_b32_e32 v70, 16, v34
	v_and_b32_e32 v71, 0xffff0000, v34
	v_pk_mul_f32 v[72:73], v[36:37], v[36:37]
	v_pk_add_f32 v[70:71], v[36:37], v[70:71] neg_lo:[0,1] neg_hi:[0,1]
	v_lshlrev_b32_e32 v36, 16, v43
	v_and_b32_e32 v37, 0xffff0000, v43
	v_and_b32_e32 v43, 0xffff0000, v47
	v_pk_add_f32 v[36:37], v[36:37], v[42:43]
	v_lshlrev_b32_e32 v42, 16, v51
	v_and_b32_e32 v43, 0xffff0000, v51
	v_pk_fma_f32 v[36:37], v[68:69], v[42:43], v[36:37]
	v_lshlrev_b32_e32 v50, 16, v48
	v_cvt_pk_bf16_f32 v35, v36, v37
	v_lshlrev_b32_e32 v46, 16, v35
	v_and_b32_e32 v47, 0xffff0000, v35
	v_pk_mul_f32 v[42:43], v[36:37], v[36:37]
	v_pk_add_f32 v[46:47], v[36:37], v[46:47] neg_lo:[0,1] neg_hi:[0,1]
	v_lshlrev_b32_e32 v36, 16, v44
	v_and_b32_e32 v37, 0xffff0000, v44
	v_and_b32_e32 v51, 0xffff0000, v48
	v_pk_add_f32 v[36:37], v[36:37], v[50:51]
	v_lshlrev_b32_e32 v50, 16, v52
	v_and_b32_e32 v51, 0xffff0000, v52
	v_pk_fma_f32 v[40:41], v[40:41], v[50:51], v[36:37]
	v_add_f32_e32 v37, v58, v59
	v_add_f32_e32 v37, v60, v37
	v_add_f32_e32 v37, v61, v37
	v_add_f32_e32 v37, v62, v37
	v_add_f32_e32 v37, v63, v37
	v_add_f32_e32 v37, v64, v37
	v_add_f32_e32 v37, v65, v37
	v_add_f32_e32 v37, v72, v37
	v_add_f32_e32 v37, v73, v37
	v_lshlrev_b32_e32 v44, 16, v45
	v_and_b32_e32 v45, 0xffff0000, v45
	v_lshlrev_b32_e32 v48, 16, v49
	v_and_b32_e32 v49, 0xffff0000, v49
	v_add_f32_e32 v37, v42, v37
	v_pk_mul_f32 v[50:51], v[40:41], v[40:41]
	v_pk_add_f32 v[44:45], v[44:45], v[48:49]
	v_lshlrev_b32_e32 v48, 16, v53
	v_and_b32_e32 v49, 0xffff0000, v53
	v_add_f32_e32 v37, v43, v37
	v_pk_fma_f32 v[38:39], v[38:39], v[48:49], v[44:45]
	v_add_f32_e32 v37, v50, v37
	v_pk_mul_f32 v[44:45], v[38:39], v[38:39]
	v_add_f32_e32 v37, v51, v37
	v_add_f32_e32 v37, v44, v37
	v_cvt_pk_bf16_f32 v36, v40, v41
	v_add_f32_e32 v44, v45, v37
	v_cvt_pk_bf16_f32 v37, v38, v39
	v_lshlrev_b32_e32 v68, 16, v36
	v_and_b32_e32 v69, 0xffff0000, v36
	v_lshlrev_b32_e32 v42, 16, v37
	v_and_b32_e32 v43, 0xffff0000, v37
	v_pk_add_f32 v[40:41], v[40:41], v[68:69] neg_lo:[0,1] neg_hi:[0,1]
	v_pk_add_f32 v[42:43], v[38:39], v[42:43] neg_lo:[0,1] neg_hi:[0,1]
	v_cvt_pk_bf16_f32 v40, v40, v41
	v_cvt_pk_bf16_f32 v41, v42, v43
	v_lshl_add_u64 v[42:43], s[58:59], 0, v[56:57]
	v_cvt_pk_bf16_f32 v38, v70, v71
	v_cvt_pk_bf16_f32 v39, v46, v47
	global_store_dwordx4 v[42:43], v[34:37], off
	global_store_dwordx4 v[66:67], v[38:41], off
	v_mov_b32_e32 v34, v44
	s_nop 1
	v_permlane16_swap_b32_e32 v44, v34
	s_waitcnt lgkmcnt(0)
	v_add_f32_e32 v34, v44, v34
	ds_bpermute_b32 v35, v145, v34
	s_and_saveexec_b64 s[12:13], s[0:1]
	s_cbranch_execz .LBB0_1350
	v_readlane_b32 s44, v250, 8
	v_readlane_b32 s46, v250, 10
	v_readlane_b32 s47, v250, 11
	s_waitcnt lgkmcnt(0)
	v_add_f32_e32 v36, v34, v35
	s_lshl_b32 s40, s25, 2
	v_lshl_add_u64 v[34:35], s[46:47], 0, v[54:55]
	v_lshl_add_u64 v[34:35], s[54:55], 2, v[34:35]
	v_lshl_add_u64 v[34:35], v[34:35], 0, s[40:41]
	v_readlane_b32 s45, v250, 9
	global_store_dword v[34:35], v36, off
.LBB0_1350:
	s_or_b64 exec, exec, s[12:13]
	v_add_u32_e32 v40, 0xa0, v144
	v_ashrrev_i32_e32 v41, 31, v40
	v_lshlrev_b64 v[38:39], 6, v[40:41]
	s_waitcnt lgkmcnt(0)
	v_lshl_add_u64 v[34:35], v[136:137], 0, v[38:39]
	global_load_dwordx4 v[34:37], v[34:35], off
	v_readlane_b32 s10, v253, 35
	v_readlane_b32 s11, v253, 36
	v_readlane_b32 s6, v250, 49
	v_readlane_b32 s7, v250, 50
	s_waitcnt vmcnt(0)
	v_mov_b32_e32 v42, v35
	v_mov_b32_e32 v43, v36
	v_mov_b32_e32 v35, v37
	v_pk_add_f32 v[34:35], v[42:43], v[34:35]
	s_nop 0
	v_add_f32_e32 v34, v34, v35
	v_mov_b32_e32 v35, v34
	s_nop 1
	v_permlane16_swap_b32_e32 v34, v35
	s_waitcnt lgkmcnt(0)
	v_add_f32_e32 v34, v34, v35
	v_mov_b32_e32 v35, v34
	s_nop 1
	v_permlane32_swap_b32_e32 v34, v35
	s_waitcnt lgkmcnt(0)
	v_add_f32_e32 v34, v34, v35
	v_fmamk_f32 v34, v34, 0x3a800000, v239
	s_nop 0
	v_rsq_f32_e32 v56, v34
	s_nop 0
	s_nop 0
	v_lshlrev_b64 v[34:35], 10, v[40:41]
	v_lshl_add_u64 v[34:35], v[34:35], 0, v[142:143]
	v_lshlrev_b64 v[40:41], 1, v[34:35]
	v_lshl_add_u64 v[34:35], s[10:11], 0, v[40:41]
	v_lshl_add_u64 v[36:37], s[14:15], 0, v[40:41]
	global_load_dwordx4 v[46:49], v[34:35], off
	global_load_dwordx4 v[58:61], v[36:37], off
	v_lshl_add_u64 v[34:35], s[6:7], 0, v[40:41]
	global_load_dwordx4 v[50:53], v[34:35], off
	v_mul_f32_e32 v26, v26, v56
	v_mul_f32_e32 v26, 0xbfb8aa3b, v26
	v_exp_f32_e32 v26, v26
	v_mul_f32_e32 v30, v30, v56
	v_mul_f32_e32 v31, v31, v56
	v_mul_f32_e32 v30, 0xbfb8aa3b, v30
	v_add_f32_e32 v26, 1.0, v26
	v_rcp_f32_e32 v36, v26
	v_mul_f32_e32 v26, v27, v56
	v_mul_f32_e32 v26, 0xbfb8aa3b, v26
	v_exp_f32_e32 v26, v26
	v_mul_f32_e32 v31, 0xbfb8aa3b, v31
	v_exp_f32_e32 v30, v30
	v_exp_f32_e32 v31, v31
	v_add_f32_e32 v26, 1.0, v26
	v_rcp_f32_e32 v37, v26
	v_mul_f32_e32 v26, v28, v56
	v_mul_f32_e32 v26, 0xbfb8aa3b, v26
	v_exp_f32_e32 v26, v26
	v_mul_f32_e32 v32, v32, v56
	v_mul_f32_e32 v33, v33, v56
	v_add_f32_e32 v30, 1.0, v30
	v_add_f32_e32 v26, 1.0, v26
	v_rcp_f32_e32 v54, v26
	v_mul_f32_e32 v26, v29, v56
	v_mul_f32_e32 v26, 0xbfb8aa3b, v26
	v_exp_f32_e32 v26, v26
	v_add_f32_e32 v31, 1.0, v31
	v_mul_f32_e32 v32, 0xbfb8aa3b, v32
	v_mul_f32_e32 v33, 0xbfb8aa3b, v33
	v_rcp_f32_e32 v30, v30
	v_rcp_f32_e32 v31, v31
	v_exp_f32_e32 v32, v32
	v_exp_f32_e32 v33, v33
	v_add_f32_e32 v26, 1.0, v26
	v_rcp_f32_e32 v55, v26
	v_add_f32_e32 v32, 1.0, v32
	v_add_f32_e32 v33, 1.0, v33
	v_rcp_f32_e32 v32, v32
	v_rcp_f32_e32 v33, v33
	v_mul_f32_e32 v22, v22, v56
	v_mul_f32_e32 v22, 0xbfb8aa3b, v22
	v_exp_f32_e32 v22, v22
	v_mul_f32_e32 v18, v18, v56
	v_mul_f32_e32 v18, 0xbfb8aa3b, v18
	v_exp_f32_e32 v18, v18
	v_add_f32_e32 v22, 1.0, v22
	v_add_f32_e32 v18, 1.0, v18
	s_waitcnt vmcnt(2)
; __device__ __forceinline__ float bflo(unsigned u) { return __uint_as_float(u << 16); }
;     __device__ __forceinline__ void operator()(const f32x4 (&acc)[2][2][4][2], const Unit& u, int wr, int wc, int fr, int fq) const {
;     ...
;                 for (int bj = 0; bj < 2; ++bj) {
;                     const size_t off = (size_t)row * DM + col0 + bj * HALF;
;                     const u32x4 hh = *(const u32x4*)(HI + off), ll = *(const u32x4*)(LO + off);
;                     float hv[8] = {bflo(hh.x) + bflo(ll.x), bfhi(hh.x) + bfhi(ll.x), bflo(hh.y) + bflo(ll.y), bfhi(hh.y) + bfhi(ll.y),
;                                    bflo(hh.z) + bflo(ll.z), bfhi(hh.z) + bfhi(ll.z), bflo(hh.w) + bflo(ll.w), bfhi(hh.w) + bfhi(ll.w)};
;                     float av[8] = {acc[ai][bj][m][0][0], acc[ai][bj][m][0][1], acc[ai][bj][m][0][2], acc[ai][bj][m][0][3], acc[ai][bj][m][1][0], acc[ai][bj][m][1][1], acc[ai][bj][m][1][2], acc[ai][bj][m][1][3]};
;                     if (GATED) { const u32x4 pp = *(const u32x4*)(PP + off);
;                         const float pv[8] = {bflo(pp.x), bfhi(pp.x), bflo(pp.y), bfhi(pp.y), bflo(pp.z), bfhi(pp.z), bflo(pp.w), bfhi(pp.w)};
; #pragma unroll
;                         for (int e = 0; e < 8; ++e) av[e] = fast_sigmoid(av[e] * rs) * pv[e]; }
;                     else {
; #pragma unroll
;                         for (int e = 0; e < 8; ++e) av[e] *= alpha; }
;                     float lo[8];
; #pragma unroll
;                     for (int e = 0; e < 8; ++e) { hv[e] += av[e]; sq += hv[e] * hv[e]; }
;                     u32x4 wh; wh.x = pk2(hv[0], hv[1]); wh.y = pk2(hv[2], hv[3]); wh.z = pk2(hv[4], hv[5]); wh.w = pk2(hv[6], hv[7]);
;                     lo[0] = hv[0] - bflo(wh.x); lo[1] = hv[1] - bfhi(wh.x); lo[2] = hv[2] - bflo(wh.y); lo[3] = hv[3] - bfhi(wh.y);
;                     lo[4] = hv[4] - bflo(wh.z); lo[5] = hv[5] - bfhi(wh.z); lo[6] = hv[6] - bflo(wh.w); lo[7] = hv[7] - bfhi(wh.w);
;                     u32x4 wl; wl.x = pk2(lo[0], lo[1]); wl.y = pk2(lo[2], lo[3]); wl.z = pk2(lo[4], lo[5]); wl.w = pk2(lo[6], lo[7]);
;                     *(u32x4*)(HO + off) = wh; *(u32x4*)(LO + off) = wl;
;                 }
;                 sq += __shfl_xor(sq, 16); sq += __shfl_xor(sq, 32);
;                 if (fq == 0) ssq_out[(size_t)row * 16 + 4 * u.pn + wc] = sq;
	v_lshlrev_b32_e32 v26, 16, v46
	v_and_b32_e32 v27, 0xffff0000, v46
	s_waitcnt vmcnt(0)
	v_lshlrev_b32_e32 v28, 16, v50
	v_and_b32_e32 v29, 0xffff0000, v50
	v_pk_add_f32 v[26:27], v[26:27], v[28:29]
	v_lshlrev_b32_e32 v28, 16, v58
	v_and_b32_e32 v29, 0xffff0000, v58
	v_pk_fma_f32 v[28:29], v[30:31], v[28:29], v[26:27]
	v_lshlrev_b32_e32 v44, 16, v51
	v_cvt_pk_bf16_f32 v26, v28, v29
	v_lshlrev_b32_e32 v30, 16, v26
	v_and_b32_e32 v31, 0xffff0000, v26
	v_pk_mul_f32 v[42:43], v[28:29], v[28:29]
	v_pk_add_f32 v[30:31], v[28:29], v[30:31] neg_lo:[0,1] neg_hi:[0,1]
	v_lshlrev_b32_e32 v28, 16, v47
	v_and_b32_e32 v29, 0xffff0000, v47
	v_and_b32_e32 v45, 0xffff0000, v51
	v_pk_add_f32 v[28:29], v[28:29], v[44:45]
	v_lshlrev_b32_e32 v44, 16, v59
	v_and_b32_e32 v45, 0xffff0000, v59
	v_pk_fma_f32 v[28:29], v[32:33], v[44:45], v[28:29]
	v_lshlrev_b32_e32 v46, 16, v52
	v_cvt_pk_bf16_f32 v27, v28, v29
	v_lshlrev_b32_e32 v32, 16, v27
	v_and_b32_e32 v33, 0xffff0000, v27
	v_pk_mul_f32 v[44:45], v[28:29], v[28:29]
	v_pk_add_f32 v[32:33], v[28:29], v[32:33] neg_lo:[0,1] neg_hi:[0,1]
	v_lshlrev_b32_e32 v28, 16, v48
	v_and_b32_e32 v29, 0xffff0000, v48
	v_and_b32_e32 v47, 0xffff0000, v52
	v_pk_add_f32 v[28:29], v[28:29], v[46:47]
	v_lshlrev_b32_e32 v46, 16, v60
	v_and_b32_e32 v47, 0xffff0000, v60
	v_pk_fma_f32 v[36:37], v[36:37], v[46:47], v[28:29]
	v_lshlrev_b32_e32 v48, 16, v49
	v_cvt_pk_bf16_f32 v28, v36, v37
	v_lshlrev_b32_e32 v50, 16, v28
	v_and_b32_e32 v51, 0xffff0000, v28
	v_pk_mul_f32 v[46:47], v[36:37], v[36:37]
	v_pk_add_f32 v[36:37], v[36:37], v[50:51] neg_lo:[0,1] neg_hi:[0,1]
	v_and_b32_e32 v49, 0xffff0000, v49
	v_lshlrev_b32_e32 v50, 16, v53
	v_and_b32_e32 v51, 0xffff0000, v53
	v_pk_add_f32 v[48:49], v[48:49], v[50:51]
	v_lshlrev_b32_e32 v50, 16, v61
	v_and_b32_e32 v51, 0xffff0000, v61
	v_pk_fma_f32 v[50:51], v[54:55], v[50:51], v[48:49]
	v_cvt_pk_bf16_f32 v30, v30, v31
	v_cvt_pk_bf16_f32 v29, v50, v51
	v_lshlrev_b32_e32 v52, 16, v29
	v_and_b32_e32 v53, 0xffff0000, v29
	v_pk_mul_f32 v[48:49], v[50:51], v[50:51]
	v_pk_add_f32 v[50:51], v[50:51], v[52:53] neg_lo:[0,1] neg_hi:[0,1]
	v_cvt_pk_bf16_f32 v31, v32, v33
	v_cvt_pk_bf16_f32 v32, v36, v37
	v_lshl_add_u64 v[36:37], s[58:59], 0, v[40:41]
	v_or_b32_e32 v40, 0x100, v40
	v_cvt_pk_bf16_f32 v33, v50, v51
	global_store_dwordx4 v[36:37], v[26:29], off
	global_store_dwordx4 v[34:35], v[30:33], off
	v_lshl_add_u64 v[50:51], s[6:7], 0, v[40:41]
	v_lshl_add_u64 v[26:27], s[10:11], 0, v[40:41]
	global_load_dwordx4 v[26:29], v[26:27], off
	v_lshl_add_u64 v[34:35], s[14:15], 0, v[40:41]
	global_load_dwordx4 v[30:33], v[50:51], off
	v_rcp_f32_e32 v54, v22
	global_load_dwordx4 v[34:37], v[34:35], off
	v_mul_f32_e32 v22, v23, v56
	v_mul_f32_e32 v22, 0xbfb8aa3b, v22
	v_exp_f32_e32 v22, v22
	s_nop 0
	v_add_f32_e32 v22, 1.0, v22
	v_rcp_f32_e32 v55, v22
	v_mul_f32_e32 v22, v24, v56
	v_rcp_f32_e32 v24, v18
	v_mul_f32_e32 v18, v19, v56
	v_mul_f32_e32 v22, 0xbfb8aa3b, v22
	v_mul_f32_e32 v18, 0xbfb8aa3b, v18
	v_exp_f32_e32 v22, v22
	v_exp_f32_e32 v18, v18
	v_add_f32_e32 v22, 1.0, v22
	v_add_f32_e32 v18, 1.0, v18
	v_rcp_f32_e32 v52, v22
	v_mul_f32_e32 v22, v25, v56
	v_rcp_f32_e32 v25, v18
	v_mul_f32_e32 v18, v20, v56
	v_mul_f32_e32 v22, 0xbfb8aa3b, v22
	v_mul_f32_e32 v18, 0xbfb8aa3b, v18
	v_exp_f32_e32 v22, v22
	v_exp_f32_e32 v18, v18
	v_add_f32_e32 v22, 1.0, v22
	v_add_f32_e32 v18, 1.0, v18
	v_rcp_f32_e32 v53, v22
	v_rcp_f32_e32 v22, v18
	v_mul_f32_e32 v18, v21, v56
	v_mul_f32_e32 v18, 0xbfb8aa3b, v18
	v_exp_f32_e32 v18, v18
	s_waitcnt vmcnt(2)
	v_and_b32_e32 v19, 0xffff0000, v26
	v_add_f32_e32 v18, 1.0, v18
	v_rcp_f32_e32 v23, v18
	v_lshlrev_b32_e32 v18, 16, v26
	s_waitcnt vmcnt(1)
	v_lshlrev_b32_e32 v20, 16, v30
	v_and_b32_e32 v21, 0xffff0000, v30
	v_pk_add_f32 v[18:19], v[18:19], v[20:21]
	s_waitcnt vmcnt(0)
	v_lshlrev_b32_e32 v20, 16, v34
	v_and_b32_e32 v21, 0xffff0000, v34
	v_pk_fma_f32 v[20:21], v[54:55], v[20:21], v[18:19]
	v_lshlrev_b32_e32 v26, 16, v31
	v_cvt_pk_bf16_f32 v18, v20, v21
	v_lshlrev_b32_e32 v54, 16, v18
	v_and_b32_e32 v55, 0xffff0000, v18
	v_pk_mul_f32 v[56:57], v[20:21], v[20:21]
	v_pk_add_f32 v[54:55], v[20:21], v[54:55] neg_lo:[0,1] neg_hi:[0,1]
	v_lshlrev_b32_e32 v20, 16, v27
	v_and_b32_e32 v21, 0xffff0000, v27
	v_and_b32_e32 v27, 0xffff0000, v31
	v_pk_add_f32 v[20:21], v[20:21], v[26:27]
	v_lshlrev_b32_e32 v26, 16, v35
	v_and_b32_e32 v27, 0xffff0000, v35
	v_pk_fma_f32 v[20:21], v[52:53], v[26:27], v[20:21]
	v_lshlrev_b32_e32 v34, 16, v32
	v_cvt_pk_bf16_f32 v19, v20, v21
	v_lshlrev_b32_e32 v30, 16, v19
	v_and_b32_e32 v31, 0xffff0000, v19
	v_pk_mul_f32 v[26:27], v[20:21], v[20:21]
	v_pk_add_f32 v[30:31], v[20:21], v[30:31] neg_lo:[0,1] neg_hi:[0,1]
	v_lshlrev_b32_e32 v20, 16, v28
	v_and_b32_e32 v21, 0xffff0000, v28
	v_and_b32_e32 v35, 0xffff0000, v32
	v_pk_add_f32 v[20:21], v[20:21], v[34:35]
	v_lshlrev_b32_e32 v34, 16, v36
	v_and_b32_e32 v35, 0xffff0000, v36
	v_pk_fma_f32 v[24:25], v[24:25], v[34:35], v[20:21]
	v_add_f32_e32 v21, v42, v43
	v_add_f32_e32 v21, v44, v21
	v_add_f32_e32 v21, v45, v21
	v_add_f32_e32 v21, v46, v21
	v_add_f32_e32 v21, v47, v21
	v_add_f32_e32 v21, v48, v21
	v_add_f32_e32 v21, v49, v21
	v_add_f32_e32 v21, v56, v21
	v_add_f32_e32 v21, v57, v21
	v_lshlrev_b32_e32 v28, 16, v29
	v_and_b32_e32 v29, 0xffff0000, v29
	v_lshlrev_b32_e32 v32, 16, v33
	v_and_b32_e32 v33, 0xffff0000, v33
	v_add_f32_e32 v21, v26, v21
	v_pk_mul_f32 v[34:35], v[24:25], v[24:25]
	v_pk_add_f32 v[28:29], v[28:29], v[32:33]
	v_lshlrev_b32_e32 v32, 16, v37
	v_and_b32_e32 v33, 0xffff0000, v37
	v_add_f32_e32 v21, v27, v21
	v_pk_fma_f32 v[22:23], v[22:23], v[32:33], v[28:29]
	v_add_f32_e32 v21, v34, v21
	v_pk_mul_f32 v[28:29], v[22:23], v[22:23]
	v_add_f32_e32 v21, v35, v21
	v_add_f32_e32 v21, v28, v21
	v_cvt_pk_bf16_f32 v20, v24, v25
	v_add_f32_e32 v28, v29, v21
	v_cvt_pk_bf16_f32 v21, v22, v23
	v_lshlrev_b32_e32 v52, 16, v20
	v_and_b32_e32 v53, 0xffff0000, v20
	v_lshlrev_b32_e32 v26, 16, v21
	v_and_b32_e32 v27, 0xffff0000, v21
	v_pk_add_f32 v[24:25], v[24:25], v[52:53] neg_lo:[0,1] neg_hi:[0,1]
	v_pk_add_f32 v[26:27], v[22:23], v[26:27] neg_lo:[0,1] neg_hi:[0,1]
	v_cvt_pk_bf16_f32 v24, v24, v25
	v_cvt_pk_bf16_f32 v25, v26, v27
	v_lshl_add_u64 v[26:27], s[58:59], 0, v[40:41]
	v_cvt_pk_bf16_f32 v22, v54, v55
	v_cvt_pk_bf16_f32 v23, v30, v31
	global_store_dwordx4 v[26:27], v[18:21], off
	global_store_dwordx4 v[50:51], v[22:25], off
	v_mov_b32_e32 v18, v28
	s_nop 1
	v_permlane16_swap_b32_e32 v28, v18
	s_waitcnt lgkmcnt(0)
	v_add_f32_e32 v18, v28, v18
	ds_bpermute_b32 v19, v145, v18
	s_and_saveexec_b64 s[12:13], s[0:1]
	s_cbranch_execz .LBB0_1352
	v_readlane_b32 s44, v250, 8
	v_readlane_b32 s46, v250, 10
	v_readlane_b32 s47, v250, 11
	s_waitcnt lgkmcnt(0)
	v_add_f32_e32 v20, v18, v19
	s_lshl_b32 s40, s25, 2
	v_lshl_add_u64 v[18:19], s[46:47], 0, v[38:39]
	v_lshl_add_u64 v[18:19], s[54:55], 2, v[18:19]
	v_lshl_add_u64 v[18:19], v[18:19], 0, s[40:41]
	v_readlane_b32 s45, v250, 9
	global_store_dword v[18:19], v20, off
; __device__ __forceinline__ float bflo(unsigned u) { return __uint_as_float(u << 16); }
;     __device__ __forceinline__ void operator()(const f32x4 (&acc)[2][2][4][2], const Unit& u, int wr, int wc, int fr, int fq) const {
;     ...
;                 const int row = row0 + ai * HALF + m * 16;
;                 float rs = 0.f; if (GATED) rs = rsqrtf(row_ssq(ssq_in, 16, 4, row, fq) * (1.f / 1024.f) + EPS);
;                 float sq = 0.f;
; #pragma unroll
;                 for (int bj = 0; bj < 2; ++bj) {
;                     const size_t off = (size_t)row * DM + col0 + bj * HALF;
;                     const u32x4 hh = *(const u32x4*)(HI + off), ll = *(const u32x4*)(LO + off);
;                     float hv[8] = {bflo(hh.x) + bflo(ll.x), bfhi(hh.x) + bfhi(ll.x), bflo(hh.y) + bflo(ll.y), bfhi(hh.y) + bfhi(ll.y),
;                                    bflo(hh.z) + bflo(ll.z), bfhi(hh.z) + bfhi(ll.z), bflo(hh.w) + bflo(ll.w), bfhi(hh.w) + bfhi(ll.w)};
;                     float av[8] = {acc[ai][bj][m][0][0], acc[ai][bj][m][0][1], acc[ai][bj][m][0][2], acc[ai][bj][m][0][3], acc[ai][bj][m][1][0], acc[ai][bj][m][1][1], acc[ai][bj][m][1][2], acc[ai][bj][m][1][3]};
;                     if (GATED) { const u32x4 pp = *(const u32x4*)(PP + off);
;                         const float pv[8] = {bflo(pp.x), bfhi(pp.x), bflo(pp.y), bfhi(pp.y), bflo(pp.z), bfhi(pp.z), bflo(pp.w), bfhi(pp.w)};
; #pragma unroll
;                         for (int e = 0; e < 8; ++e) av[e] = fast_sigmoid(av[e] * rs) * pv[e]; }
;                     else {
; #pragma unroll
;                         for (int e = 0; e < 8; ++e) av[e] *= alpha; }
;                     float lo[8];
; #pragma unroll
;                     for (int e = 0; e < 8; ++e) { hv[e] += av[e]; sq += hv[e] * hv[e]; }
;                     u32x4 wh; wh.x = pk2(hv[0], hv[1]); wh.y = pk2(hv[2], hv[3]); wh.z = pk2(hv[4], hv[5]); wh.w = pk2(hv[6], hv[7]);
;                     lo[0] = hv[0] - bflo(wh.x); lo[1] = hv[1] - bfhi(wh.x); lo[2] = hv[2] - bflo(wh.y); lo[3] = hv[3] - bfhi(wh.y);
;                     lo[4] = hv[4] - bflo(wh.z); lo[5] = hv[5] - bfhi(wh.z); lo[6] = hv[6] - bflo(wh.w); lo[7] = hv[7] - bfhi(wh.w);
;                     u32x4 wl; wl.x = pk2(lo[0], lo[1]); wl.y = pk2(lo[2], lo[3]); wl.z = pk2(lo[4], lo[5]); wl.w = pk2(lo[6], lo[7]);
;                     *(u32x4*)(HO + off) = wh; *(u32x4*)(LO + off) = wl;
.LBB0_1352:
	s_or_b64 exec, exec, s[12:13]
	v_add_u32_e32 v24, 0xb0, v144
	v_ashrrev_i32_e32 v25, 31, v24
	v_lshlrev_b64 v[22:23], 6, v[24:25]
	s_waitcnt lgkmcnt(0)
	v_lshl_add_u64 v[18:19], v[136:137], 0, v[22:23]
	global_load_dwordx4 v[18:21], v[18:19], off
	v_readlane_b32 s10, v253, 35
	v_readlane_b32 s11, v253, 36
	v_readlane_b32 s6, v250, 49
	v_readlane_b32 s7, v250, 50
	s_waitcnt vmcnt(0)
	v_mov_b32_e32 v26, v19
	v_mov_b32_e32 v27, v20
	v_mov_b32_e32 v19, v21
	v_pk_add_f32 v[18:19], v[26:27], v[18:19]
	s_nop 0
	v_add_f32_e32 v18, v18, v19
	v_mov_b32_e32 v19, v18
	s_nop 1
	v_permlane16_swap_b32_e32 v18, v19
	s_waitcnt lgkmcnt(0)
	v_add_f32_e32 v18, v18, v19
	v_mov_b32_e32 v19, v18
	s_nop 1
	v_permlane32_swap_b32_e32 v18, v19
	s_waitcnt lgkmcnt(0)
	v_add_f32_e32 v18, v18, v19
	v_fmamk_f32 v18, v18, 0x3a800000, v239
	s_nop 0
	v_rsq_f32_e32 v40, v18
	s_nop 0
	s_nop 0
	v_lshlrev_b64 v[18:19], 10, v[24:25]
	v_lshl_add_u64 v[18:19], v[18:19], 0, v[142:143]
	v_lshlrev_b64 v[24:25], 1, v[18:19]
	v_lshl_add_u64 v[18:19], s[10:11], 0, v[24:25]
	v_lshl_add_u64 v[20:21], s[14:15], 0, v[24:25]
	global_load_dwordx4 v[30:33], v[18:19], off
	global_load_dwordx4 v[42:45], v[20:21], off
	v_lshl_add_u64 v[18:19], s[6:7], 0, v[24:25]
	global_load_dwordx4 v[34:37], v[18:19], off
	v_mul_f32_e32 v10, v10, v40
	v_mul_f32_e32 v10, 0xbfb8aa3b, v10
	v_exp_f32_e32 v10, v10
	v_mul_f32_e32 v14, v14, v40
	v_mul_f32_e32 v15, v15, v40
	v_mul_f32_e32 v14, 0xbfb8aa3b, v14
	v_add_f32_e32 v10, 1.0, v10
	v_rcp_f32_e32 v20, v10
	v_mul_f32_e32 v10, v11, v40
	v_mul_f32_e32 v10, 0xbfb8aa3b, v10
	v_exp_f32_e32 v10, v10
	v_mul_f32_e32 v15, 0xbfb8aa3b, v15
	v_exp_f32_e32 v14, v14
	v_exp_f32_e32 v15, v15
	v_add_f32_e32 v10, 1.0, v10
	v_rcp_f32_e32 v21, v10
	v_mul_f32_e32 v10, v12, v40
	v_mul_f32_e32 v10, 0xbfb8aa3b, v10
	v_exp_f32_e32 v10, v10
	v_mul_f32_e32 v16, v16, v40
	v_mul_f32_e32 v17, v17, v40
	v_add_f32_e32 v14, 1.0, v14
	v_add_f32_e32 v10, 1.0, v10
	v_rcp_f32_e32 v38, v10
	v_mul_f32_e32 v10, v13, v40
	v_mul_f32_e32 v10, 0xbfb8aa3b, v10
	v_exp_f32_e32 v10, v10
	v_add_f32_e32 v15, 1.0, v15
	v_mul_f32_e32 v16, 0xbfb8aa3b, v16
	v_mul_f32_e32 v17, 0xbfb8aa3b, v17
	v_rcp_f32_e32 v14, v14
	v_rcp_f32_e32 v15, v15
	v_exp_f32_e32 v16, v16
	v_exp_f32_e32 v17, v17
	v_add_f32_e32 v10, 1.0, v10
	v_rcp_f32_e32 v39, v10
	v_add_f32_e32 v16, 1.0, v16
	v_add_f32_e32 v17, 1.0, v17
	v_rcp_f32_e32 v16, v16
	v_rcp_f32_e32 v17, v17
	v_mul_f32_e32 v6, v6, v40
	v_mul_f32_e32 v6, 0xbfb8aa3b, v6
	v_exp_f32_e32 v6, v6
	v_mul_f32_e32 v2, v2, v40
	v_mul_f32_e32 v2, 0xbfb8aa3b, v2
	v_exp_f32_e32 v2, v2
	v_add_f32_e32 v6, 1.0, v6
	v_add_f32_e32 v2, 1.0, v2
	s_waitcnt vmcnt(2)
	v_lshlrev_b32_e32 v10, 16, v30
	v_and_b32_e32 v11, 0xffff0000, v30
	s_waitcnt vmcnt(0)
	v_lshlrev_b32_e32 v12, 16, v34
	v_and_b32_e32 v13, 0xffff0000, v34
	v_pk_add_f32 v[10:11], v[10:11], v[12:13]
	v_lshlrev_b32_e32 v12, 16, v42
	v_and_b32_e32 v13, 0xffff0000, v42
	v_pk_fma_f32 v[12:13], v[14:15], v[12:13], v[10:11]
	v_lshlrev_b32_e32 v28, 16, v35
	v_cvt_pk_bf16_f32 v10, v12, v13
	v_lshlrev_b32_e32 v14, 16, v10
	v_and_b32_e32 v15, 0xffff0000, v10
	v_pk_mul_f32 v[26:27], v[12:13], v[12:13]
	v_pk_add_f32 v[14:15], v[12:13], v[14:15] neg_lo:[0,1] neg_hi:[0,1]
	v_lshlrev_b32_e32 v12, 16, v31
	v_and_b32_e32 v13, 0xffff0000, v31
	v_and_b32_e32 v29, 0xffff0000, v35
	v_pk_add_f32 v[12:13], v[12:13], v[28:29]
	v_lshlrev_b32_e32 v28, 16, v43
	v_and_b32_e32 v29, 0xffff0000, v43
	v_pk_fma_f32 v[12:13], v[16:17], v[28:29], v[12:13]
	v_lshlrev_b32_e32 v30, 16, v36
	v_cvt_pk_bf16_f32 v11, v12, v13
	v_lshlrev_b32_e32 v16, 16, v11
	v_and_b32_e32 v17, 0xffff0000, v11
	v_pk_mul_f32 v[28:29], v[12:13], v[12:13]
	v_pk_add_f32 v[16:17], v[12:13], v[16:17] neg_lo:[0,1] neg_hi:[0,1]
	v_lshlrev_b32_e32 v12, 16, v32
	v_and_b32_e32 v13, 0xffff0000, v32
	v_and_b32_e32 v31, 0xffff0000, v36
	v_pk_add_f32 v[12:13], v[12:13], v[30:31]
	v_lshlrev_b32_e32 v30, 16, v44
	v_and_b32_e32 v31, 0xffff0000, v44
	v_pk_fma_f32 v[20:21], v[20:21], v[30:31], v[12:13]
	v_lshlrev_b32_e32 v32, 16, v33
	v_cvt_pk_bf16_f32 v12, v20, v21
	v_lshlrev_b32_e32 v34, 16, v12
	v_and_b32_e32 v35, 0xffff0000, v12
	v_pk_mul_f32 v[30:31], v[20:21], v[20:21]
	v_pk_add_f32 v[20:21], v[20:21], v[34:35] neg_lo:[0,1] neg_hi:[0,1]
	v_and_b32_e32 v33, 0xffff0000, v33
	v_lshlrev_b32_e32 v34, 16, v37
	v_and_b32_e32 v35, 0xffff0000, v37
	v_pk_add_f32 v[32:33], v[32:33], v[34:35]
	v_lshlrev_b32_e32 v34, 16, v45
	v_and_b32_e32 v35, 0xffff0000, v45
	v_pk_fma_f32 v[34:35], v[38:39], v[34:35], v[32:33]
	v_cvt_pk_bf16_f32 v14, v14, v15
	v_cvt_pk_bf16_f32 v13, v34, v35
	v_lshlrev_b32_e32 v36, 16, v13
	v_and_b32_e32 v37, 0xffff0000, v13
	v_pk_mul_f32 v[32:33], v[34:35], v[34:35]
	v_pk_add_f32 v[34:35], v[34:35], v[36:37] neg_lo:[0,1] neg_hi:[0,1]
	v_cvt_pk_bf16_f32 v15, v16, v17
	v_cvt_pk_bf16_f32 v16, v20, v21
	v_lshl_add_u64 v[20:21], s[58:59], 0, v[24:25]
	v_or_b32_e32 v24, 0x100, v24
	v_cvt_pk_bf16_f32 v17, v34, v35
	global_store_dwordx4 v[20:21], v[10:13], off
	global_store_dwordx4 v[18:19], v[14:17], off
	v_lshl_add_u64 v[34:35], s[6:7], 0, v[24:25]
	v_lshl_add_u64 v[10:11], s[10:11], 0, v[24:25]
	global_load_dwordx4 v[10:13], v[10:11], off
	v_lshl_add_u64 v[18:19], s[14:15], 0, v[24:25]
	global_load_dwordx4 v[14:17], v[34:35], off
	v_rcp_f32_e32 v38, v6
	global_load_dwordx4 v[18:21], v[18:19], off
	v_mul_f32_e32 v6, v7, v40
	v_mul_f32_e32 v6, 0xbfb8aa3b, v6
	v_exp_f32_e32 v6, v6
	s_nop 0
	v_add_f32_e32 v6, 1.0, v6
	v_rcp_f32_e32 v39, v6
	v_mul_f32_e32 v6, v8, v40
	v_rcp_f32_e32 v8, v2
	v_mul_f32_e32 v2, v3, v40
	v_mul_f32_e32 v6, 0xbfb8aa3b, v6
	v_mul_f32_e32 v2, 0xbfb8aa3b, v2
	v_exp_f32_e32 v6, v6
	v_exp_f32_e32 v2, v2
	v_add_f32_e32 v6, 1.0, v6
	v_add_f32_e32 v2, 1.0, v2
	v_rcp_f32_e32 v36, v6
	v_mul_f32_e32 v6, v9, v40
	v_rcp_f32_e32 v9, v2
	v_mul_f32_e32 v2, v4, v40
	v_mul_f32_e32 v6, 0xbfb8aa3b, v6
	v_mul_f32_e32 v2, 0xbfb8aa3b, v2
	v_exp_f32_e32 v6, v6
	v_exp_f32_e32 v2, v2
	v_add_f32_e32 v6, 1.0, v6
	v_add_f32_e32 v2, 1.0, v2
	v_rcp_f32_e32 v37, v6
	v_rcp_f32_e32 v6, v2
	v_mul_f32_e32 v2, v5, v40
	v_mul_f32_e32 v2, 0xbfb8aa3b, v2
	v_exp_f32_e32 v2, v2
	s_waitcnt vmcnt(2)
; __device__ __forceinline__ float bflo(unsigned u) { return __uint_as_float(u << 16); }
;     __device__ __forceinline__ void operator()(const f32x4 (&acc)[2][2][4][2], const Unit& u, int wr, int wc, int fr, int fq) const {
;     ...
;                 for (int bj = 0; bj < 2; ++bj) {
;                     const size_t off = (size_t)row * DM + col0 + bj * HALF;
;                     const u32x4 hh = *(const u32x4*)(HI + off), ll = *(const u32x4*)(LO + off);
;                     float hv[8] = {bflo(hh.x) + bflo(ll.x), bfhi(hh.x) + bfhi(ll.x), bflo(hh.y) + bflo(ll.y), bfhi(hh.y) + bfhi(ll.y),
;                                    bflo(hh.z) + bflo(ll.z), bfhi(hh.z) + bfhi(ll.z), bflo(hh.w) + bflo(ll.w), bfhi(hh.w) + bfhi(ll.w)};
;                     float av[8] = {acc[ai][bj][m][0][0], acc[ai][bj][m][0][1], acc[ai][bj][m][0][2], acc[ai][bj][m][0][3], acc[ai][bj][m][1][0], acc[ai][bj][m][1][1], acc[ai][bj][m][1][2], acc[ai][bj][m][1][3]};
;                     if (GATED) { const u32x4 pp = *(const u32x4*)(PP + off);
;                         const float pv[8] = {bflo(pp.x), bfhi(pp.x), bflo(pp.y), bfhi(pp.y), bflo(pp.z), bfhi(pp.z), bflo(pp.w), bfhi(pp.w)};
; #pragma unroll
;                         for (int e = 0; e < 8; ++e) av[e] = fast_sigmoid(av[e] * rs) * pv[e]; }
;                     else {
; #pragma unroll
;                         for (int e = 0; e < 8; ++e) av[e] *= alpha; }
;                     float lo[8];
; #pragma unroll
;                     for (int e = 0; e < 8; ++e) { hv[e] += av[e]; sq += hv[e] * hv[e]; }
;                     u32x4 wh; wh.x = pk2(hv[0], hv[1]); wh.y = pk2(hv[2], hv[3]); wh.z = pk2(hv[4], hv[5]); wh.w = pk2(hv[6], hv[7]);
;                     lo[0] = hv[0] - bflo(wh.x); lo[1] = hv[1] - bfhi(wh.x); lo[2] = hv[2] - bflo(wh.y); lo[3] = hv[3] - bfhi(wh.y);
;                     lo[4] = hv[4] - bflo(wh.z); lo[5] = hv[5] - bfhi(wh.z); lo[6] = hv[6] - bflo(wh.w); lo[7] = hv[7] - bfhi(wh.w);
;                     u32x4 wl; wl.x = pk2(lo[0], lo[1]); wl.y = pk2(lo[2], lo[3]); wl.z = pk2(lo[4], lo[5]); wl.w = pk2(lo[6], lo[7]);
;                     *(u32x4*)(HO + off) = wh; *(u32x4*)(LO + off) = wl;
;                 }
;                 sq += __shfl_xor(sq, 16); sq += __shfl_xor(sq, 32);
;                 if (fq == 0) ssq_out[(size_t)row * 16 + 4 * u.pn + wc] = sq;
	v_and_b32_e32 v3, 0xffff0000, v10
	v_add_f32_e32 v2, 1.0, v2
	v_rcp_f32_e32 v7, v2
	v_lshlrev_b32_e32 v2, 16, v10
	s_waitcnt vmcnt(1)
	v_lshlrev_b32_e32 v4, 16, v14
	v_and_b32_e32 v5, 0xffff0000, v14
	v_pk_add_f32 v[2:3], v[2:3], v[4:5]
	s_waitcnt vmcnt(0)
	v_lshlrev_b32_e32 v4, 16, v18
	v_and_b32_e32 v5, 0xffff0000, v18
	v_pk_fma_f32 v[4:5], v[38:39], v[4:5], v[2:3]
	v_lshlrev_b32_e32 v10, 16, v15
	v_cvt_pk_bf16_f32 v2, v4, v5
	v_lshlrev_b32_e32 v38, 16, v2
	v_and_b32_e32 v39, 0xffff0000, v2
	v_pk_mul_f32 v[40:41], v[4:5], v[4:5]
	v_pk_add_f32 v[38:39], v[4:5], v[38:39] neg_lo:[0,1] neg_hi:[0,1]
	v_lshlrev_b32_e32 v4, 16, v11
	v_and_b32_e32 v5, 0xffff0000, v11
	v_and_b32_e32 v11, 0xffff0000, v15
	v_pk_add_f32 v[4:5], v[4:5], v[10:11]
	v_lshlrev_b32_e32 v10, 16, v19
	v_and_b32_e32 v11, 0xffff0000, v19
	v_pk_fma_f32 v[4:5], v[36:37], v[10:11], v[4:5]
	v_lshlrev_b32_e32 v18, 16, v16
	v_cvt_pk_bf16_f32 v3, v4, v5
	v_lshlrev_b32_e32 v14, 16, v3
	v_and_b32_e32 v15, 0xffff0000, v3
	v_pk_mul_f32 v[10:11], v[4:5], v[4:5]
	v_pk_add_f32 v[14:15], v[4:5], v[14:15] neg_lo:[0,1] neg_hi:[0,1]
	v_lshlrev_b32_e32 v4, 16, v12
	v_and_b32_e32 v5, 0xffff0000, v12
	v_and_b32_e32 v19, 0xffff0000, v16
	v_pk_add_f32 v[4:5], v[4:5], v[18:19]
	v_lshlrev_b32_e32 v18, 16, v20
	v_and_b32_e32 v19, 0xffff0000, v20
	v_pk_fma_f32 v[8:9], v[8:9], v[18:19], v[4:5]
	v_add_f32_e32 v5, v26, v27
	v_add_f32_e32 v5, v28, v5
	v_add_f32_e32 v5, v29, v5
	v_add_f32_e32 v5, v30, v5
	v_add_f32_e32 v5, v31, v5
	v_add_f32_e32 v5, v32, v5
	v_add_f32_e32 v5, v33, v5
	v_add_f32_e32 v5, v40, v5
	v_add_f32_e32 v5, v41, v5
	v_lshlrev_b32_e32 v12, 16, v13
	v_and_b32_e32 v13, 0xffff0000, v13
	v_lshlrev_b32_e32 v16, 16, v17
	v_and_b32_e32 v17, 0xffff0000, v17
	v_add_f32_e32 v5, v10, v5
	v_pk_mul_f32 v[18:19], v[8:9], v[8:9]
	v_pk_add_f32 v[12:13], v[12:13], v[16:17]
	v_lshlrev_b32_e32 v16, 16, v21
	v_and_b32_e32 v17, 0xffff0000, v21
	v_add_f32_e32 v5, v11, v5
	v_pk_fma_f32 v[6:7], v[6:7], v[16:17], v[12:13]
	v_add_f32_e32 v5, v18, v5
	v_pk_mul_f32 v[12:13], v[6:7], v[6:7]
	v_add_f32_e32 v5, v19, v5
	v_add_f32_e32 v5, v12, v5
	v_cvt_pk_bf16_f32 v4, v8, v9
	v_add_f32_e32 v12, v13, v5
	v_cvt_pk_bf16_f32 v5, v6, v7
	v_lshlrev_b32_e32 v36, 16, v4
	v_and_b32_e32 v37, 0xffff0000, v4
	v_lshlrev_b32_e32 v10, 16, v5
	v_and_b32_e32 v11, 0xffff0000, v5
	v_pk_add_f32 v[8:9], v[8:9], v[36:37] neg_lo:[0,1] neg_hi:[0,1]
	v_pk_add_f32 v[10:11], v[6:7], v[10:11] neg_lo:[0,1] neg_hi:[0,1]
	v_cvt_pk_bf16_f32 v8, v8, v9
	v_cvt_pk_bf16_f32 v9, v10, v11
	v_lshl_add_u64 v[10:11], s[58:59], 0, v[24:25]
	v_cvt_pk_bf16_f32 v6, v38, v39
	v_cvt_pk_bf16_f32 v7, v14, v15
	global_store_dwordx4 v[10:11], v[2:5], off
	global_store_dwordx4 v[34:35], v[6:9], off
	v_mov_b32_e32 v2, v12
	s_nop 1
	v_permlane16_swap_b32_e32 v12, v2
	s_waitcnt lgkmcnt(0)
	v_add_f32_e32 v2, v12, v2
	ds_bpermute_b32 v3, v145, v2
	s_and_saveexec_b64 s[12:13], s[0:1]
	s_cbranch_execz .LBB0_1354
	v_readlane_b32 s44, v250, 8
	v_readlane_b32 s46, v250, 10
	v_readlane_b32 s47, v250, 11
	s_waitcnt lgkmcnt(0)
	v_add_f32_e32 v4, v2, v3
	s_lshl_b32 s40, s25, 2
	v_lshl_add_u64 v[2:3], s[46:47], 0, v[22:23]
	v_lshl_add_u64 v[2:3], s[54:55], 2, v[2:3]
	v_lshl_add_u64 v[2:3], v[2:3], 0, s[40:41]
	v_readlane_b32 s45, v250, 9
	global_store_dword v[2:3], v4, off
